# serialized wave-sum butterflies (ds_bpermute + full wait per step) in m3 rows / row passes replaced by DPP and permlane-swap adds
# baseline (speedup 1.0000x reference)
; #define LAS __attribute__((address_space(3)))
; __device__ __forceinline__ float bf2f(unsigned h) { return __uint_as_float(h << 16); }
; __device__ __forceinline__ unsigned pk2(float lo, float hi) { return pg8::cvt_pk_bf16(lo, hi); }
; __device__ __forceinline__ float wave_sum(float v) {
; #pragma unroll
;     for (int o = 1; o < 64; o <<= 1) v += __shfl_xor(v, o);
;     return v;
; template <int MODE> __device__ __forceinline__ void rows_pass(const Ctx& C, const float* src, const float* g, bf16* dst_bf, float* dst_f, const LAS float* wg, const float* b_ig = nullptr, const float* b_fg = nullptr, const bf16* add_bf = nullptr, const bf16* add2_bf = nullptr) {
;     const int gw = C.bid * 8 + C.wave, NGW = C.G * 8, lane = C.lane;
;     for (int m = gw; m < M; m += NGW) {
;         const f32x4* xr = (const f32x4*)(src + (size_t)m * DM) + lane;
;         f32x4 v[8]; float ss = 0.f;
; #pragma unroll
;         for (int j = 0; j < 8; ++j) v[j] = xr[64 * j];
;         if (MODE != 0) { const u32x2* ar = (const u32x2*)(add_bf + (size_t)m * DM) + lane;
; #pragma unroll
;             for (int j = 0; j < 8; ++j) { const u32x2 a = ar[64 * j]; v[j].x += bf2f(a.x & 0xffffu); v[j].y += bf2f(a.x >> 16); v[j].z += bf2f(a.y & 0xffffu); v[j].w += bf2f(a.y >> 16); }
;             if (MODE == 2) { const u32x2* ar2 = (const u32x2*)(add2_bf + (size_t)m * DM) + lane;
; #pragma unroll
;                 for (int j = 0; j < 8; ++j) { const u32x2 a = ar2[64 * j]; v[j].x += bf2f(a.x & 0xffffu); v[j].y += bf2f(a.x >> 16); v[j].z += bf2f(a.y & 0xffffu); v[j].w += bf2f(a.y >> 16); } } }
; #pragma unroll
;         for (int j = 0; j < 8; ++j) ss += (v[j].x * v[j].x + v[j].y * v[j].y) + (v[j].z * v[j].z + v[j].w * v[j].w);
;         const float rs = 1.0f / sqrtf(wave_sum(ss) * (1.0f / DM) + EPS);
; #pragma unroll
;         for (int j = 0; j < 8; ++j) { const f32x4 gg = ((const f32x4*)g)[64 * j + lane]; v[j] = v[j] * rs * gg; }
;         if (MODE == 2) {
;             f32x4* o = (f32x4*)(dst_f + (size_t)m * DM) + lane;
; #pragma unroll
;             for (int j = 0; j < 8; ++j) o[64 * j] = v[j];
;         } else {
;             u32x2* o = (u32x2*)(dst_bf + (size_t)m * DM) + lane;
; #pragma unroll
;             for (int j = 0; j < 8; ++j) { u32x2 w; w.x = pk2(v[j].x, v[j].y); w.y = pk2(v[j].z, v[j].w); o[64 * j] = w; }
.LBB0_34:
	global_load_dwordx4 v[30:33], v[48:49], off offset:-4096
	global_load_dwordx4 v[18:21], v[48:49], off offset:-3072
	global_load_dwordx4 v[10:13], v[48:49], off offset:-2048
	s_waitcnt lgkmcnt(0)
	global_load_dwordx4 v[6:9], v[48:49], off
	global_load_dwordx4 v[22:25], v[48:49], off offset:-1024
	global_load_dwordx4 v[14:17], v[48:49], off offset:1024
	global_load_dwordx4 v[2:5], v[48:49], off offset:3072
	global_load_dwordx4 v[26:29], v[48:49], off offset:2048
	s_waitcnt vmcnt(7)
	v_mov_b32_e32 v68, v31
	s_waitcnt vmcnt(6)
	v_mov_b32_e32 v69, v19
	v_mov_b32_e32 v72, v33
	v_mov_b32_e32 v73, v21
	v_mov_b32_e32 v54, v30
	v_mov_b32_e32 v55, v18
	v_mov_b32_e32 v70, v32
	v_mov_b32_e32 v71, v20
	s_waitcnt vmcnt(5)
	v_pk_mul_f32 v[74:75], v[12:13], v[12:13]
	v_pk_mul_f32 v[76:77], v[10:11], v[10:11]
	v_pk_mul_f32 v[68:69], v[68:69], v[68:69]
	v_pk_mul_f32 v[72:73], v[72:73], v[72:73]
	v_pk_mov_b32 v[90:91], v[76:77], v[74:75] op_sel:[1,0]
	v_mov_b32_e32 v77, v75
	v_pk_fma_f32 v[54:55], v[54:55], v[54:55], v[68:69]
	v_pk_fma_f32 v[68:69], v[70:71], v[70:71], v[72:73]
	s_waitcnt vmcnt(3)
	v_mul_f32_e32 v78, v23, v23
	v_mul_f32_e32 v80, v25, v25
	v_pk_add_f32 v[70:71], v[90:91], v[76:77]
	v_pk_add_f32 v[54:55], v[54:55], v[68:69]
	v_mul_f32_e32 v53, v6, v6
	v_mul_f32_e32 v89, v7, v7
	v_mul_f32_e32 v92, v8, v8
	v_mul_f32_e32 v93, v9, v9
	v_pk_fma_f32 v[74:75], v[22:23], v[22:23], v[78:79] op_sel_hi:[1,1,0]
	v_pk_fma_f32 v[78:79], v[24:25], v[24:25], v[80:81] op_sel_hi:[1,1,0]
	v_pk_add_f32 v[68:69], v[70:71], v[70:71] op_sel:[0,1] op_sel_hi:[1,0]
	v_pk_add_f32 v[54:55], v[54:55], v[54:55] op_sel:[0,1] op_sel_hi:[1,0]
	s_waitcnt vmcnt(2)
	v_pk_mul_f32 v[82:83], v[16:17], v[16:17]
	v_pk_mul_f32 v[84:85], v[14:15], v[14:15]
	v_mov_b32_e32 v75, v92
	v_mov_b32_e32 v79, v93
	v_mov_b32_e32 v69, v89
	v_mov_b32_e32 v55, v53
	v_pk_mov_b32 v[80:81], v[84:85], v[82:83] op_sel:[1,0]
	v_mov_b32_e32 v85, v83
	v_pk_add_f32 v[70:71], v[74:75], v[78:79]
	v_pk_add_f32 v[54:55], v[54:55], v[68:69]
	s_waitcnt vmcnt(0)
	v_mul_f32_e32 v86, v27, v27
	v_mul_f32_e32 v88, v29, v29
	v_pk_add_f32 v[72:73], v[80:81], v[84:85]
	v_pk_add_f32 v[54:55], v[54:55], v[70:71]
	v_mul_f32_e32 v94, v2, v2
	v_mul_f32_e32 v95, v3, v3
	v_mul_f32_e32 v96, v4, v4
	v_mul_f32_e32 v97, v5, v5
	v_pk_fma_f32 v[82:83], v[26:27], v[26:27], v[86:87] op_sel_hi:[1,1,0]
	v_pk_fma_f32 v[86:87], v[28:29], v[28:29], v[88:89] op_sel_hi:[1,1,0]
	v_pk_add_f32 v[72:73], v[72:73], v[72:73] op_sel:[0,1] op_sel_hi:[1,0]
	v_pk_add_f32 v[54:55], v[54:55], v[54:55] op_sel:[0,1] op_sel_hi:[1,0]
	v_mov_b32_e32 v83, v96
	v_mov_b32_e32 v87, v97
	v_mov_b32_e32 v73, v95
	v_mov_b32_e32 v55, v94
	v_pk_add_f32 v[74:75], v[82:83], v[86:87]
	v_pk_add_f32 v[54:55], v[54:55], v[72:73]
	s_nop 0
	v_pk_add_f32 v[54:55], v[54:55], v[74:75]
	global_load_dwordx4 v[68:71], v[38:39], off
	global_load_dwordx4 v[72:75], v[38:39], off offset:1024
	global_load_dwordx4 v[76:79], v[38:39], off offset:2048
	global_load_dwordx4 v[80:83], v[38:39], off offset:3072
	global_load_dwordx4 v[84:87], v[40:41], off
	global_load_dwordx4 v[88:91], v[42:43], off
	global_load_dwordx4 v[92:95], v[44:45], off
	global_load_dwordx4 v[96:99], v[46:47], off
	v_add_f32_e32 v53, v54, v55
	s_waitcnt lgkmcnt(0)
	s_nop 1
	v_add_f32_dpp v53, v53, v53 quad_perm:[1,0,3,2] row_mask:0xf bank_mask:0xf
	s_waitcnt lgkmcnt(0)
	s_nop 1
	v_add_f32_dpp v53, v53, v53 quad_perm:[2,3,0,1] row_mask:0xf bank_mask:0xf
	s_waitcnt lgkmcnt(0)
	s_nop 1
	v_add_f32_dpp v53, v53, v53 row_half_mirror row_mask:0xf bank_mask:0xf
	s_waitcnt lgkmcnt(0)
	s_nop 1
	v_add_f32_dpp v53, v53, v53 row_mirror row_mask:0xf bank_mask:0xf
	s_waitcnt lgkmcnt(0)
	v_mov_b32_e32 v54, v53
	s_nop 1
	v_permlane16_swap_b32_e32 v53, v54
	v_add_f32_e32 v53, v53, v54
	s_waitcnt lgkmcnt(0)
	v_mov_b32_e32 v54, v53
	s_nop 1
	v_permlane32_swap_b32_e32 v53, v54
	v_add_f32_e32 v53, v53, v54
	v_fmamk_f32 v53, v53, 0x3a000000, v63
	v_mul_f32_e32 v54, 0x4f800000, v53
	v_cmp_gt_f32_e32 vcc, s29, v53
	s_nop 1
	v_cndmask_b32_e32 v53, v53, v54, vcc
	v_sqrt_f32_e32 v54, v53
	s_nop 0
	v_add_u32_e32 v55, -1, v54
	v_add_u32_e32 v100, 1, v54
	v_fma_f32 v101, -v55, v54, v53
	v_fma_f32 v102, -v100, v54, v53
	v_cmp_ge_f32_e64 s[24:25], 0, v101
	s_nop 1
	v_cndmask_b32_e64 v54, v54, v55, s[24:25]
	v_cmp_lt_f32_e64 s[24:25], 0, v102
	s_nop 1
	v_cndmask_b32_e64 v54, v54, v100, s[24:25]
	v_mul_f32_e32 v55, 0x37800000, v54
	v_cndmask_b32_e32 v54, v54, v55, vcc
	v_cmp_class_f32_e32 vcc, v53, v64
	s_nop 1
	v_cndmask_b32_e32 v53, v54, v53, vcc
	v_div_scale_f32 v54, s[24:25], v53, v53, 1.0
	v_rcp_f32_e32 v55, v54
	v_div_scale_f32 v100, vcc, 1.0, v53, 1.0
	v_fma_f32 v101, -v54, v55, 1.0
	v_fmac_f32_e32 v55, v101, v55
	v_mul_f32_e32 v101, v100, v55
	v_fma_f32 v102, -v54, v101, v100
	v_fmac_f32_e32 v101, v102, v55
	v_fma_f32 v54, -v54, v101, v100
	v_div_fmas_f32 v54, v54, v55, v101
	v_div_fixup_f32 v54, v54, v53, 1.0
	v_pk_mul_f32 v[30:31], v[30:31], v[54:55] op_sel_hi:[1,0]
	v_pk_mul_f32 v[32:33], v[32:33], v[54:55] op_sel_hi:[1,0]
	v_pk_mul_f32 v[22:23], v[22:23], v[54:55] op_sel_hi:[1,0]
	v_pk_mul_f32 v[6:7], v[6:7], v[54:55] op_sel_hi:[1,0]
	v_pk_mul_f32 v[18:19], v[18:19], v[54:55] op_sel_hi:[1,0]
	v_pk_mul_f32 v[20:21], v[20:21], v[54:55] op_sel_hi:[1,0]
	v_pk_mul_f32 v[10:11], v[10:11], v[54:55] op_sel_hi:[1,0]
	v_pk_mul_f32 v[12:13], v[12:13], v[54:55] op_sel_hi:[1,0]
	v_pk_mul_f32 v[100:101], v[24:25], v[54:55] op_sel_hi:[1,0]
	v_pk_mul_f32 v[8:9], v[8:9], v[54:55] op_sel_hi:[1,0]
	v_pk_mul_f32 v[14:15], v[14:15], v[54:55] op_sel_hi:[1,0]
	v_pk_mul_f32 v[16:17], v[16:17], v[54:55] op_sel_hi:[1,0]
	v_pk_mul_f32 v[102:103], v[26:27], v[54:55] op_sel_hi:[1,0]
	v_pk_mul_f32 v[104:105], v[28:29], v[54:55] op_sel_hi:[1,0]
	v_pk_mul_f32 v[106:107], v[2:3], v[54:55] op_sel_hi:[1,0]
	v_pk_mul_f32 v[108:109], v[4:5], v[54:55] op_sel_hi:[1,0]
	s_waitcnt vmcnt(7)
; #define LAS __attribute__((address_space(3)))
; __device__ __forceinline__ unsigned pk2(float lo, float hi) { return pg8::cvt_pk_bf16(lo, hi); }
; template <int MODE> __device__ __forceinline__ void rows_pass(const Ctx& C, const float* src, const float* g, bf16* dst_bf, float* dst_f, const LAS float* wg, const float* b_ig = nullptr, const float* b_fg = nullptr, const bf16* add_bf = nullptr, const bf16* add2_bf = nullptr) {
;     ...
;         for (int j = 0; j < 8; ++j) { const f32x4 gg = ((const f32x4*)g)[64 * j + lane]; v[j] = v[j] * rs * gg; }
;         if (MODE == 2) {
;             f32x4* o = (f32x4*)(dst_f + (size_t)m * DM) + lane;
; #pragma unroll
;             for (int j = 0; j < 8; ++j) o[64 * j] = v[j];
;         } else {
;             u32x2* o = (u32x2*)(dst_bf + (size_t)m * DM) + lane;
; #pragma unroll
;             for (int j = 0; j < 8; ++j) { u32x2 w; w.x = pk2(v[j].x, v[j].y); w.y = pk2(v[j].z, v[j].w); o[64 * j] = w; }
;         }
;         if (MODE == 0) {
;             float ga[8];
; #pragma unroll
;             for (int q = 0; q < 8; ++q) { float a = 0.f;
; #pragma unroll
;                 for (int j = 0; j < 8; ++j) { const f32x4 w = ((const LAS f32x4*)(wg + q * DM))[64 * j + lane]; a += (v[j].x * w.x + v[j].y * w.y) + (v[j].z * w.z + v[j].w * w.w); }
;                 ga[q] = wave_sum(a); }
	v_pk_mul_f32 v[32:33], v[70:71], v[32:33]
	v_pk_mul_f32 v[54:55], v[68:69], v[30:31]
	s_waitcnt vmcnt(4)
	v_pk_mul_f32 v[4:5], v[80:81], v[22:23]
	s_waitcnt vmcnt(3)
	v_pk_mul_f32 v[22:23], v[84:85], v[6:7]
	v_cvt_pk_bf16_f32 v6, v54, v55
	v_cvt_pk_bf16_f32 v7, v32, v33
	v_pk_mul_f32 v[28:29], v[74:75], v[20:21]
	v_pk_mul_f32 v[30:31], v[72:73], v[18:19]
	global_store_dwordx2 v[50:51], v[6:7], off
	v_cvt_pk_bf16_f32 v6, v30, v31
	v_cvt_pk_bf16_f32 v7, v28, v29
	v_pk_mul_f32 v[24:25], v[78:79], v[12:13]
	v_pk_mul_f32 v[26:27], v[76:77], v[10:11]
	global_store_dwordx2 v[50:51], v[6:7], off offset:512
	v_cvt_pk_bf16_f32 v6, v26, v27
	v_cvt_pk_bf16_f32 v7, v24, v25
	v_pk_mul_f32 v[2:3], v[82:83], v[100:101]
	global_store_dwordx2 v[50:51], v[6:7], off offset:1024
	v_cvt_pk_bf16_f32 v6, v4, v5
	v_cvt_pk_bf16_f32 v7, v2, v3
	v_pk_mul_f32 v[20:21], v[86:87], v[8:9]
	global_store_dwordx2 v[50:51], v[6:7], off offset:1536
	v_cvt_pk_bf16_f32 v6, v22, v23
	v_cvt_pk_bf16_f32 v7, v20, v21
	s_waitcnt vmcnt(6)
	v_pk_mul_f32 v[16:17], v[90:91], v[16:17]
	v_pk_mul_f32 v[18:19], v[88:89], v[14:15]
	global_store_dwordx2 v[50:51], v[6:7], off offset:2048
	v_cvt_pk_bf16_f32 v6, v18, v19
	v_cvt_pk_bf16_f32 v7, v16, v17
	s_waitcnt vmcnt(6)
	v_pk_mul_f32 v[8:9], v[94:95], v[104:105]
	v_pk_mul_f32 v[10:11], v[92:93], v[102:103]
	global_store_dwordx2 v[50:51], v[6:7], off offset:2560
	v_cvt_pk_bf16_f32 v6, v10, v11
	v_cvt_pk_bf16_f32 v7, v8, v9
	s_waitcnt vmcnt(6)
	v_pk_mul_f32 v[12:13], v[98:99], v[108:109]
	v_pk_mul_f32 v[14:15], v[96:97], v[106:107]
	global_store_dwordx2 v[50:51], v[6:7], off offset:3072
	v_cvt_pk_bf16_f32 v6, v14, v15
	v_cvt_pk_bf16_f32 v7, v12, v13
	ds_read_b128 v[68:71], v61
	ds_read_b128 v[72:75], v61 offset:1024
	global_store_dwordx2 v[50:51], v[6:7], off offset:3584
	s_waitcnt lgkmcnt(1)
	v_mul_f32_e32 v53, v55, v69
	v_fmac_f32_e32 v53, v54, v68
	v_mul_f32_e32 v68, v33, v71
	v_fmac_f32_e32 v68, v32, v70
	v_add_f32_e32 v53, v53, v68
	s_waitcnt lgkmcnt(0)
	v_mul_f32_e32 v73, v31, v73
	ds_read_b128 v[68:71], v61 offset:2048
	v_fmac_f32_e32 v73, v30, v72
	v_mul_f32_e32 v72, v29, v75
	v_fmac_f32_e32 v72, v28, v74
	v_add_f32_e32 v53, 0, v53
	v_add_f32_e32 v72, v73, v72
	v_add_f32_e32 v53, v53, v72
	ds_read_b128 v[72:75], v61 offset:3072
	s_waitcnt lgkmcnt(1)
	v_mul_f32_e32 v69, v27, v69
	v_fmac_f32_e32 v69, v26, v68
	v_mul_f32_e32 v68, v25, v71
	v_fmac_f32_e32 v68, v24, v70
	v_add_f32_e32 v68, v69, v68
	v_add_f32_e32 v53, v53, v68
	s_waitcnt lgkmcnt(0)
	v_mul_f32_e32 v73, v5, v73
	ds_read_b128 v[68:71], v61 offset:4096
	v_fmac_f32_e32 v73, v4, v72
	v_mul_f32_e32 v72, v3, v75
	v_fmac_f32_e32 v72, v2, v74
	v_add_f32_e32 v72, v73, v72
	v_add_f32_e32 v53, v53, v72
	ds_read_b128 v[72:75], v61 offset:5120
	s_waitcnt lgkmcnt(1)
	v_mul_f32_e32 v69, v23, v69
	v_fmac_f32_e32 v69, v22, v68
	v_mul_f32_e32 v68, v21, v71
	v_fmac_f32_e32 v68, v20, v70
	v_add_f32_e32 v68, v69, v68
	v_add_f32_e32 v53, v53, v68
	s_waitcnt lgkmcnt(0)
	v_mul_f32_e32 v73, v19, v73
	ds_read_b128 v[68:71], v61 offset:6144
	v_fmac_f32_e32 v73, v18, v72
	v_mul_f32_e32 v72, v17, v75
	v_fmac_f32_e32 v72, v16, v74
	v_add_f32_e32 v72, v73, v72
	v_add_f32_e32 v53, v53, v72
	ds_read_b128 v[72:75], v61 offset:7168
	s_waitcnt lgkmcnt(1)
	v_mul_f32_e32 v69, v11, v69
	v_fmac_f32_e32 v69, v10, v68
	v_mul_f32_e32 v68, v9, v71
	v_fmac_f32_e32 v68, v8, v70
	v_add_f32_e32 v68, v69, v68
	v_add_f32_e32 v53, v53, v68
	s_waitcnt lgkmcnt(0)
	v_mul_f32_e32 v68, v15, v73
	v_mul_f32_e32 v69, v13, v75
	v_fmac_f32_e32 v68, v14, v72
	v_fmac_f32_e32 v69, v12, v74
	v_add_f32_e32 v68, v68, v69
	v_add_f32_e32 v53, v53, v68
	ds_bpermute_b32 v72, v35, v53
	ds_read_b128 v[68:71], v61 offset:8192
	s_waitcnt lgkmcnt(1)
	v_add_f32_e32 v53, v53, v72
	ds_read_b128 v[72:75], v61 offset:9216
	s_waitcnt lgkmcnt(1)
	v_mul_f32_e32 v69, v55, v69
	v_fmac_f32_e32 v69, v54, v68
	v_mul_f32_e32 v68, v33, v71
	v_fmac_f32_e32 v68, v32, v70
	v_add_f32_e32 v68, v69, v68
	s_waitcnt lgkmcnt(0)
	v_mul_f32_e32 v73, v31, v73
	v_add_f32_e32 v77, 0, v68
	v_fmac_f32_e32 v73, v30, v72
	v_mul_f32_e32 v72, v29, v75
	ds_read_b128 v[68:71], v61 offset:10240
	v_fmac_f32_e32 v72, v28, v74
	v_add_f32_e32 v72, v73, v72
	v_add_f32_e32 v77, v77, v72
	ds_read_b128 v[72:75], v61 offset:11264
	s_waitcnt lgkmcnt(1)
	v_mul_f32_e32 v69, v27, v69
	v_fmac_f32_e32 v69, v26, v68
	v_mul_f32_e32 v68, v25, v71
	v_fmac_f32_e32 v68, v24, v70
	v_add_f32_e32 v68, v69, v68
	s_waitcnt lgkmcnt(0)
	v_mul_f32_e32 v73, v5, v73
	v_add_f32_e32 v77, v77, v68
	v_fmac_f32_e32 v73, v4, v72
	v_mul_f32_e32 v72, v3, v75
	ds_read_b128 v[68:71], v61 offset:12288
	v_fmac_f32_e32 v72, v2, v74
	v_add_f32_e32 v72, v73, v72
	v_add_f32_e32 v77, v77, v72
	ds_read_b128 v[72:75], v61 offset:13312
	s_waitcnt lgkmcnt(1)
	v_mul_f32_e32 v69, v23, v69
	v_fmac_f32_e32 v69, v22, v68
	v_mul_f32_e32 v68, v21, v71
	v_fmac_f32_e32 v68, v20, v70
	v_add_f32_e32 v68, v69, v68
	s_waitcnt lgkmcnt(0)
	v_mul_f32_e32 v73, v19, v73
	v_add_f32_e32 v77, v77, v68
	v_fmac_f32_e32 v73, v18, v72
	v_mul_f32_e32 v72, v17, v75
	ds_read_b128 v[68:71], v61 offset:14336
	v_fmac_f32_e32 v72, v16, v74
	v_add_f32_e32 v72, v73, v72
	v_add_f32_e32 v77, v77, v72
	ds_read_b128 v[72:75], v61 offset:15360
	s_waitcnt lgkmcnt(1)
	v_mul_f32_e32 v69, v11, v69
	v_fmac_f32_e32 v69, v10, v68
	v_mul_f32_e32 v68, v9, v71
	v_fmac_f32_e32 v68, v8, v70
	v_add_f32_e32 v68, v69, v68
	s_waitcnt lgkmcnt(0)
	v_mul_f32_e32 v69, v15, v73
	v_mul_f32_e32 v70, v13, v75
	ds_bpermute_b32 v76, v56, v53
	v_fmac_f32_e32 v69, v14, v72
	v_fmac_f32_e32 v70, v12, v74
	v_add_f32_e32 v68, v77, v68
	v_add_f32_e32 v69, v69, v70
	v_add_f32_e32 v68, v68, v69
	ds_bpermute_b32 v69, v35, v68
	s_waitcnt lgkmcnt(1)
; #define LAS __attribute__((address_space(3)))
; template <int MODE> __device__ __forceinline__ void rows_pass(const Ctx& C, const float* src, const float* g, bf16* dst_bf, float* dst_f, const LAS float* wg, const float* b_ig = nullptr, const float* b_fg = nullptr, const bf16* add_bf = nullptr, const bf16* add2_bf = nullptr) {
;     ...
;             for (int q = 0; q < 8; ++q) { float a = 0.f;
; #pragma unroll
;                 for (int j = 0; j < 8; ++j) { const f32x4 w = ((const LAS f32x4*)(wg + q * DM))[64 * j + lane]; a += (v[j].x * w.x + v[j].y * w.y) + (v[j].z * w.z + v[j].w * w.w); }
;                 ga[q] = wave_sum(a); }
	v_add_f32_e32 v53, v53, v76
	ds_bpermute_b32 v70, v57, v53
	s_waitcnt lgkmcnt(1)
	v_add_f32_e32 v72, v68, v69
	ds_bpermute_b32 v73, v56, v72
	s_waitcnt lgkmcnt(1)
	v_add_f32_e32 v53, v53, v70
	ds_read_b128 v[68:71], v61 offset:16384
	ds_bpermute_b32 v76, v58, v53
	s_waitcnt lgkmcnt(2)
	v_add_f32_e32 v77, v72, v73
	ds_read_b128 v[72:75], v61 offset:17408
	s_waitcnt lgkmcnt(2)
	v_mul_f32_e32 v69, v55, v69
	v_fmac_f32_e32 v69, v54, v68
	v_mul_f32_e32 v68, v33, v71
	v_fmac_f32_e32 v68, v32, v70
	v_add_f32_e32 v68, v69, v68
	s_waitcnt lgkmcnt(0)
	v_mul_f32_e32 v73, v31, v73
	v_add_f32_e32 v79, 0, v68
	v_fmac_f32_e32 v73, v30, v72
	v_mul_f32_e32 v72, v29, v75
	ds_read_b128 v[68:71], v61 offset:18432
	v_fmac_f32_e32 v72, v28, v74
	v_add_f32_e32 v72, v73, v72
	v_add_f32_e32 v79, v79, v72
	ds_read_b128 v[72:75], v61 offset:19456
	s_waitcnt lgkmcnt(1)
	v_mul_f32_e32 v69, v27, v69
	v_fmac_f32_e32 v69, v26, v68
	v_mul_f32_e32 v68, v25, v71
	v_fmac_f32_e32 v68, v24, v70
	v_add_f32_e32 v68, v69, v68
	s_waitcnt lgkmcnt(0)
	v_mul_f32_e32 v73, v5, v73
	v_add_f32_e32 v79, v79, v68
	v_fmac_f32_e32 v73, v4, v72
	v_mul_f32_e32 v72, v3, v75
	ds_read_b128 v[68:71], v61 offset:20480
	v_fmac_f32_e32 v72, v2, v74
	v_add_f32_e32 v72, v73, v72
	v_add_f32_e32 v79, v79, v72
	ds_read_b128 v[72:75], v61 offset:21504
	s_waitcnt lgkmcnt(1)
	v_mul_f32_e32 v69, v23, v69
	v_fmac_f32_e32 v69, v22, v68
	v_mul_f32_e32 v68, v21, v71
	v_fmac_f32_e32 v68, v20, v70
	v_add_f32_e32 v68, v69, v68
	s_waitcnt lgkmcnt(0)
	v_mul_f32_e32 v73, v19, v73
	v_add_f32_e32 v79, v79, v68
	v_fmac_f32_e32 v73, v18, v72
	v_mul_f32_e32 v72, v17, v75
	ds_read_b128 v[68:71], v61 offset:22528
	v_fmac_f32_e32 v72, v16, v74
	v_add_f32_e32 v72, v73, v72
	v_add_f32_e32 v79, v79, v72
	ds_read_b128 v[72:75], v61 offset:23552
	s_waitcnt lgkmcnt(1)
	v_mul_f32_e32 v69, v11, v69
	v_fmac_f32_e32 v69, v10, v68
	v_mul_f32_e32 v68, v9, v71
	v_fmac_f32_e32 v68, v8, v70
	v_add_f32_e32 v68, v69, v68
	s_waitcnt lgkmcnt(0)
	v_mul_f32_e32 v69, v15, v73
	v_mul_f32_e32 v70, v13, v75
	v_fmac_f32_e32 v69, v14, v72
	v_fmac_f32_e32 v70, v12, v74
	v_add_f32_e32 v68, v79, v68
	v_add_f32_e32 v69, v69, v70
	v_add_f32_e32 v68, v68, v69
	ds_bpermute_b32 v78, v57, v77
	ds_bpermute_b32 v69, v35, v68
	v_add_f32_e32 v53, v53, v76
	ds_bpermute_b32 v70, v59, v53
	s_waitcnt lgkmcnt(2)
	v_add_f32_e32 v74, v77, v78
	s_waitcnt lgkmcnt(1)
	v_add_f32_e32 v69, v68, v69
	ds_bpermute_b32 v75, v58, v74
	ds_bpermute_b32 v76, v56, v69
	s_waitcnt lgkmcnt(2)
	v_add_f32_e32 v53, v53, v70
	ds_read_b128 v[70:73], v61 offset:24576
	ds_bpermute_b32 v68, v60, v53
	s_waitcnt lgkmcnt(3)
	v_add_f32_e32 v78, v74, v75
	s_waitcnt lgkmcnt(2)
	v_add_f32_e32 v69, v69, v76
	ds_read_b128 v[74:77], v61 offset:25600
	s_waitcnt lgkmcnt(2)
	v_mul_f32_e32 v71, v55, v71
	v_fmac_f32_e32 v71, v54, v70
	v_mul_f32_e32 v70, v33, v73
	v_fmac_f32_e32 v70, v32, v72
	v_add_f32_e32 v70, v71, v70
	s_waitcnt lgkmcnt(0)
	v_mul_f32_e32 v75, v31, v75
	v_add_f32_e32 v80, 0, v70
	v_fmac_f32_e32 v75, v30, v74
	v_mul_f32_e32 v74, v29, v77
	ds_read_b128 v[70:73], v61 offset:26624
	v_fmac_f32_e32 v74, v28, v76
	v_add_f32_e32 v74, v75, v74
	v_add_f32_e32 v80, v80, v74
	ds_read_b128 v[74:77], v61 offset:27648
	s_waitcnt lgkmcnt(1)
	v_mul_f32_e32 v71, v27, v71
	v_fmac_f32_e32 v71, v26, v70
	v_mul_f32_e32 v70, v25, v73
	v_fmac_f32_e32 v70, v24, v72
	v_add_f32_e32 v70, v71, v70
	s_waitcnt lgkmcnt(0)
	v_mul_f32_e32 v75, v5, v75
	v_add_f32_e32 v80, v80, v70
	v_fmac_f32_e32 v75, v4, v74
	v_mul_f32_e32 v74, v3, v77
	ds_read_b128 v[70:73], v61 offset:28672
	v_fmac_f32_e32 v74, v2, v76
	v_add_f32_e32 v74, v75, v74
	v_add_f32_e32 v80, v80, v74
	ds_read_b128 v[74:77], v61 offset:29696
	s_waitcnt lgkmcnt(1)
	v_mul_f32_e32 v71, v23, v71
	v_fmac_f32_e32 v71, v22, v70
	v_mul_f32_e32 v70, v21, v73
	v_fmac_f32_e32 v70, v20, v72
	v_add_f32_e32 v70, v71, v70
	s_waitcnt lgkmcnt(0)
	v_mul_f32_e32 v75, v19, v75
	v_add_f32_e32 v80, v80, v70
	v_fmac_f32_e32 v75, v18, v74
	v_mul_f32_e32 v74, v17, v77
	ds_read_b128 v[70:73], v61 offset:30720
	v_fmac_f32_e32 v74, v16, v76
	v_add_f32_e32 v74, v75, v74
	v_add_f32_e32 v80, v80, v74
	ds_read_b128 v[74:77], v61 offset:31744
	s_waitcnt lgkmcnt(1)
	v_mul_f32_e32 v71, v11, v71
	v_fmac_f32_e32 v71, v10, v70
	v_mul_f32_e32 v70, v9, v73
	v_fmac_f32_e32 v70, v8, v72
	v_add_f32_e32 v70, v71, v70
	s_waitcnt lgkmcnt(0)
	v_mul_f32_e32 v75, v15, v75
	v_add_f32_e32 v80, v80, v70
	v_fmac_f32_e32 v75, v14, v74
	v_mul_f32_e32 v74, v13, v77
	ds_read_b128 v[70:73], v61 offset:32768
	v_fmac_f32_e32 v74, v12, v76
	v_add_f32_e32 v74, v75, v74
	v_add_f32_e32 v80, v80, v74
	ds_read_b128 v[74:77], v61 offset:33792
	s_waitcnt lgkmcnt(1)
	v_mul_f32_e32 v71, v55, v71
	v_fmac_f32_e32 v71, v54, v70
	v_mul_f32_e32 v70, v33, v73
	v_fmac_f32_e32 v70, v32, v72
	v_add_f32_e32 v70, v71, v70
	s_waitcnt lgkmcnt(0)
	v_mul_f32_e32 v75, v31, v75
	v_add_f32_e32 v82, 0, v70
	v_fmac_f32_e32 v75, v30, v74
	v_mul_f32_e32 v74, v29, v77
	ds_read_b128 v[70:73], v61 offset:34816
	v_fmac_f32_e32 v74, v28, v76
	v_add_f32_e32 v74, v75, v74
	v_add_f32_e32 v82, v82, v74
	ds_read_b128 v[74:77], v61 offset:35840
	s_waitcnt lgkmcnt(1)
	v_mul_f32_e32 v71, v27, v71
	v_fmac_f32_e32 v71, v26, v70
	v_mul_f32_e32 v70, v25, v73
	v_fmac_f32_e32 v70, v24, v72
	v_add_f32_e32 v70, v71, v70
	s_waitcnt lgkmcnt(0)
	v_mul_f32_e32 v75, v5, v75
	v_add_f32_e32 v82, v82, v70
	v_fmac_f32_e32 v75, v4, v74
	v_mul_f32_e32 v74, v3, v77
	ds_read_b128 v[70:73], v61 offset:36864
	v_fmac_f32_e32 v74, v2, v76
	v_add_f32_e32 v74, v75, v74
	v_add_f32_e32 v82, v82, v74
	ds_read_b128 v[74:77], v61 offset:37888
	s_waitcnt lgkmcnt(1)
; #define LAS __attribute__((address_space(3)))
; template <int MODE> __device__ __forceinline__ void rows_pass(const Ctx& C, const float* src, const float* g, bf16* dst_bf, float* dst_f, const LAS float* wg, const float* b_ig = nullptr, const float* b_fg = nullptr, const bf16* add_bf = nullptr, const bf16* add2_bf = nullptr) {
;     ...
;             for (int q = 0; q < 8; ++q) { float a = 0.f;
; #pragma unroll
;                 for (int j = 0; j < 8; ++j) { const f32x4 w = ((const LAS f32x4*)(wg + q * DM))[64 * j + lane]; a += (v[j].x * w.x + v[j].y * w.y) + (v[j].z * w.z + v[j].w * w.w); }
;                 ga[q] = wave_sum(a); }
	v_mul_f32_e32 v71, v23, v71
	v_fmac_f32_e32 v71, v22, v70
	v_mul_f32_e32 v70, v21, v73
	v_fmac_f32_e32 v70, v20, v72
	v_add_f32_e32 v70, v71, v70
	s_waitcnt lgkmcnt(0)
	v_mul_f32_e32 v75, v19, v75
	v_add_f32_e32 v82, v82, v70
	v_fmac_f32_e32 v75, v18, v74
	v_mul_f32_e32 v74, v17, v77
	ds_read_b128 v[70:73], v61 offset:38912
	v_fmac_f32_e32 v74, v16, v76
	v_add_f32_e32 v74, v75, v74
	v_add_f32_e32 v82, v82, v74
	ds_read_b128 v[74:77], v61 offset:39936
	s_waitcnt lgkmcnt(1)
	v_mul_f32_e32 v71, v11, v71
	v_fmac_f32_e32 v71, v10, v70
	v_mul_f32_e32 v70, v9, v73
	v_fmac_f32_e32 v70, v8, v72
	v_add_f32_e32 v70, v71, v70
	s_waitcnt lgkmcnt(0)
	v_mul_f32_e32 v71, v15, v75
	v_mul_f32_e32 v72, v13, v77
	v_fmac_f32_e32 v71, v14, v74
	v_fmac_f32_e32 v72, v12, v76
	v_add_f32_e32 v70, v82, v70
	v_add_f32_e32 v71, v71, v72
	v_add_f32_e32 v70, v70, v71
	ds_bpermute_b32 v71, v35, v70
	ds_bpermute_b32 v79, v57, v69
	ds_bpermute_b32 v72, v59, v78
	ds_bpermute_b32 v81, v35, v80
	ds_read_b128 v[82:85], v61 offset:41984
	s_waitcnt lgkmcnt(4)
	v_add_f32_e32 v70, v70, v71
	ds_bpermute_b32 v71, v56, v70
	s_waitcnt lgkmcnt(4)
	v_add_f32_e32 v75, v69, v79
	ds_bpermute_b32 v76, v58, v75
	s_waitcnt lgkmcnt(4)
	v_add_f32_e32 v69, v78, v72
	s_waitcnt lgkmcnt(3)
	v_add_f32_e32 v73, v80, v81
	s_waitcnt lgkmcnt(1)
	v_add_f32_e32 v70, v70, v71
	ds_bpermute_b32 v71, v57, v70
	s_waitcnt lgkmcnt(1)
	v_add_f32_e32 v72, v75, v76
	ds_bpermute_b32 v75, v59, v72
	ds_read_b128 v[78:81], v61 offset:40960
	v_mul_f32_e32 v83, v31, v83
	s_waitcnt lgkmcnt(2)
	v_add_f32_e32 v76, v70, v71
	ds_bpermute_b32 v77, v58, v76
	s_waitcnt lgkmcnt(2)
	v_add_f32_e32 v71, v72, v75
	v_fmac_f32_e32 v83, v30, v82
	v_mul_f32_e32 v82, v29, v85
	v_fmac_f32_e32 v82, v28, v84
	s_waitcnt lgkmcnt(0)
	v_add_f32_e32 v75, v76, v77
	v_mul_f32_e32 v77, v55, v79
	v_fmac_f32_e32 v77, v54, v78
	v_mul_f32_e32 v78, v33, v81
	v_fmac_f32_e32 v78, v32, v80
	v_add_f32_e32 v77, v77, v78
	ds_read_b128 v[78:81], v61 offset:43008
	v_add_f32_e32 v77, 0, v77
	v_add_f32_e32 v82, v83, v82
	v_add_f32_e32 v77, v77, v82
	ds_read_b128 v[82:85], v61 offset:44032
	s_waitcnt lgkmcnt(1)
	v_mul_f32_e32 v79, v27, v79
	v_fmac_f32_e32 v79, v26, v78
	v_mul_f32_e32 v78, v25, v81
	v_fmac_f32_e32 v78, v24, v80
	v_add_f32_e32 v78, v79, v78
	v_add_f32_e32 v77, v77, v78
	s_waitcnt lgkmcnt(0)
	v_mul_f32_e32 v83, v5, v83
	ds_read_b128 v[78:81], v61 offset:45056
	v_fmac_f32_e32 v83, v4, v82
	v_mul_f32_e32 v82, v3, v85
	v_fmac_f32_e32 v82, v2, v84
	v_add_f32_e32 v82, v83, v82
	v_add_f32_e32 v77, v77, v82
	ds_read_b128 v[82:85], v61 offset:46080
	s_waitcnt lgkmcnt(1)
	v_mul_f32_e32 v79, v23, v79
	v_fmac_f32_e32 v79, v22, v78
	v_mul_f32_e32 v78, v21, v81
	v_fmac_f32_e32 v78, v20, v80
	v_add_f32_e32 v78, v79, v78
	v_add_f32_e32 v77, v77, v78
	s_waitcnt lgkmcnt(0)
	v_mul_f32_e32 v83, v19, v83
	ds_read_b128 v[78:81], v61 offset:47104
	v_fmac_f32_e32 v83, v18, v82
	v_mul_f32_e32 v82, v17, v85
	v_fmac_f32_e32 v82, v16, v84
	v_add_f32_e32 v82, v83, v82
	v_add_f32_e32 v77, v77, v82
	ds_read_b128 v[82:85], v61 offset:48128
	s_waitcnt lgkmcnt(1)
	v_mul_f32_e32 v79, v11, v79
	v_fmac_f32_e32 v79, v10, v78
	v_mul_f32_e32 v78, v9, v81
	v_fmac_f32_e32 v78, v8, v80
	v_add_f32_e32 v78, v79, v78
	v_add_f32_e32 v77, v77, v78
	s_waitcnt lgkmcnt(0)
	v_mul_f32_e32 v78, v15, v83
	v_fmac_f32_e32 v78, v14, v82
	ds_read_b128 v[80:83], v61 offset:49152
	v_mul_f32_e32 v79, v13, v85
	v_fmac_f32_e32 v79, v12, v84
	ds_read_b128 v[84:87], v61 offset:50176
	v_add_f32_e32 v78, v78, v79
	s_waitcnt lgkmcnt(1)
	v_mul_f32_e32 v79, v55, v81
	v_fmac_f32_e32 v79, v54, v80
	v_mul_f32_e32 v80, v33, v83
	v_fmac_f32_e32 v80, v32, v82
	v_add_f32_e32 v79, v79, v80
	s_waitcnt lgkmcnt(0)
	v_mul_f32_e32 v85, v31, v85
	ds_read_b128 v[80:83], v61 offset:51200
	v_fmac_f32_e32 v85, v30, v84
	v_mul_f32_e32 v84, v29, v87
	v_fmac_f32_e32 v84, v28, v86
	v_add_f32_e32 v79, 0, v79
	v_add_f32_e32 v84, v85, v84
	v_add_f32_e32 v79, v79, v84
	ds_read_b128 v[84:87], v61 offset:52224
	s_waitcnt lgkmcnt(1)
	v_mul_f32_e32 v81, v27, v81
	v_fmac_f32_e32 v81, v26, v80
	v_mul_f32_e32 v80, v25, v83
	v_fmac_f32_e32 v80, v24, v82
	v_add_f32_e32 v80, v81, v80
	v_add_f32_e32 v79, v79, v80
	s_waitcnt lgkmcnt(0)
	v_mul_f32_e32 v85, v5, v85
	ds_read_b128 v[80:83], v61 offset:53248
	v_fmac_f32_e32 v85, v4, v84
	v_mul_f32_e32 v84, v3, v87
	v_fmac_f32_e32 v84, v2, v86
	v_add_f32_e32 v84, v85, v84
	v_add_f32_e32 v79, v79, v84
	ds_read_b128 v[84:87], v61 offset:54272
	s_waitcnt lgkmcnt(1)
	v_mul_f32_e32 v81, v23, v81
	v_fmac_f32_e32 v81, v22, v80
	v_mul_f32_e32 v80, v21, v83
	v_fmac_f32_e32 v80, v20, v82
	v_add_f32_e32 v80, v81, v80
	v_add_f32_e32 v79, v79, v80
	s_waitcnt lgkmcnt(0)
	v_mul_f32_e32 v85, v19, v85
	ds_read_b128 v[80:83], v61 offset:55296
	v_fmac_f32_e32 v85, v18, v84
	v_mul_f32_e32 v84, v17, v87
	v_fmac_f32_e32 v84, v16, v86
	v_add_f32_e32 v84, v85, v84
	v_add_f32_e32 v79, v79, v84
	ds_read_b128 v[84:87], v61 offset:56320
	s_waitcnt lgkmcnt(1)
	v_mul_f32_e32 v81, v11, v81
	v_fmac_f32_e32 v81, v10, v80
	v_mul_f32_e32 v80, v9, v83
	v_fmac_f32_e32 v80, v8, v82
	v_add_f32_e32 v80, v81, v80
	v_add_f32_e32 v79, v79, v80
	s_waitcnt lgkmcnt(0)
; #define LAS __attribute__((address_space(3)))
; template <int MODE> __device__ __forceinline__ void rows_pass(const Ctx& C, const float* src, const float* g, bf16* dst_bf, float* dst_f, const LAS float* wg, const float* b_ig = nullptr, const float* b_fg = nullptr, const bf16* add_bf = nullptr, const bf16* add2_bf = nullptr) {
;     ...
;             for (int q = 0; q < 8; ++q) { float a = 0.f;
; #pragma unroll
;                 for (int j = 0; j < 8; ++j) { const f32x4 w = ((const LAS f32x4*)(wg + q * DM))[64 * j + lane]; a += (v[j].x * w.x + v[j].y * w.y) + (v[j].z * w.z + v[j].w * w.w); }
;                 ga[q] = wave_sum(a); }
;             float mine = ga[0];
; #pragma unroll
;             for (int q = 1; q < 8; ++q) mine = (lane == q) ? ga[q] : mine;
;             if (lane < 8) { const int hh = lane & 3; const float pre = mine + (lane < 4 ? b_ig[hh] : b_fg[hh]); const float cp = 15.0f * tanhf(pre * (1.0f / 15.0f));
;                 if (lane < 4) ((float*)(C.ws + WS_IG))[hh * M + m] = cp; else ((float*)(C.ws + WS_LOGF))[hh * M + m] = fminf(cp, 0.f) - log1pf(expf(-fabsf(cp))); }
	v_mul_f32_e32 v80, v15, v85
	v_fmac_f32_e32 v80, v14, v84
	ds_read_b128 v[82:85], v61 offset:57344
	v_mul_f32_e32 v81, v13, v87
	v_fmac_f32_e32 v81, v12, v86
	ds_read_b128 v[86:89], v61 offset:58368
	v_add_f32_e32 v80, v80, v81
	s_waitcnt lgkmcnt(1)
	v_mul_f32_e32 v55, v55, v83
	v_mul_f32_e32 v33, v33, v85
	v_fmac_f32_e32 v55, v54, v82
	v_fmac_f32_e32 v33, v32, v84
	v_add_f32_e32 v32, v55, v33
	s_waitcnt lgkmcnt(0)
	v_mul_f32_e32 v55, v31, v87
	v_add_f32_e32 v54, 0, v32
	v_fmac_f32_e32 v55, v30, v86
	ds_read_b128 v[30:33], v61 offset:59392
	ds_read_b128 v[82:85], v61 offset:60416
	v_mul_f32_e32 v29, v29, v89
	v_fmac_f32_e32 v29, v28, v88
	v_add_f32_e32 v28, v55, v29
	s_waitcnt lgkmcnt(1)
	v_mul_f32_e32 v27, v27, v31
	v_mul_f32_e32 v25, v25, v33
	v_fmac_f32_e32 v27, v26, v30
	v_fmac_f32_e32 v25, v24, v32
	s_waitcnt lgkmcnt(0)
	v_mul_f32_e32 v5, v5, v83
	v_mul_f32_e32 v3, v3, v85
	v_add_f32_e32 v28, v54, v28
	v_add_f32_e32 v24, v27, v25
	v_fmac_f32_e32 v5, v4, v82
	v_fmac_f32_e32 v3, v2, v84
	v_add_f32_e32 v28, v28, v24
	v_add_f32_e32 v2, v5, v3
	ds_read_b128 v[24:27], v61 offset:61440
	v_add_f32_e32 v28, v28, v2
	ds_read_b128 v[2:5], v61 offset:62464
	v_add_f32_e32 v77, v77, v78
	v_add_f32_e32 v79, v79, v80
	s_waitcnt lgkmcnt(1)
	v_mul_f32_e32 v23, v23, v25
	v_mul_f32_e32 v21, v21, v27
	s_waitcnt lgkmcnt(0)
	v_mul_f32_e32 v3, v19, v3
	v_fmac_f32_e32 v23, v22, v24
	v_fmac_f32_e32 v21, v20, v26
	v_fmac_f32_e32 v3, v18, v2
	v_mul_f32_e32 v2, v17, v5
	v_add_f32_e32 v20, v23, v21
	v_fmac_f32_e32 v2, v16, v4
	v_add_f32_e32 v22, v28, v20
	v_add_f32_e32 v2, v3, v2
	ds_read_b128 v[18:21], v61 offset:63488
	v_add_f32_e32 v16, v22, v2
	ds_read_b128 v[2:5], v61 offset:64512
	ds_bpermute_b32 v78, v35, v77
	ds_bpermute_b32 v80, v35, v79
	s_waitcnt lgkmcnt(3)
	v_mul_f32_e32 v11, v11, v19
	v_mul_f32_e32 v9, v9, v21
	s_waitcnt lgkmcnt(2)
	v_mul_f32_e32 v3, v15, v3
	v_fmac_f32_e32 v11, v10, v18
	v_fmac_f32_e32 v9, v8, v20
	v_fmac_f32_e32 v3, v14, v2
	v_mul_f32_e32 v2, v13, v5
	v_add_f32_e32 v8, v11, v9
	v_fmac_f32_e32 v2, v12, v4
	v_add_f32_e32 v8, v16, v8
	v_add_f32_e32 v2, v3, v2
	v_add_f32_e32 v2, v8, v2
	ds_bpermute_b32 v3, v35, v2
	s_waitcnt lgkmcnt(2)
	v_add_f32_e32 v4, v77, v78
	s_waitcnt lgkmcnt(1)
	v_add_f32_e32 v8, v79, v80
	ds_bpermute_b32 v74, v56, v73
	ds_bpermute_b32 v5, v56, v4
	s_waitcnt lgkmcnt(2)
	v_add_f32_e32 v2, v2, v3
	ds_bpermute_b32 v9, v56, v8
	ds_bpermute_b32 v3, v56, v2
	s_waitcnt lgkmcnt(3)
	v_add_f32_e32 v73, v73, v74
	s_waitcnt lgkmcnt(2)
	v_add_f32_e32 v4, v4, v5
	ds_bpermute_b32 v74, v57, v73
	s_waitcnt lgkmcnt(2)
	v_add_f32_e32 v8, v8, v9
	s_waitcnt lgkmcnt(1)
	v_add_f32_e32 v2, v2, v3
	ds_bpermute_b32 v5, v57, v4
	ds_bpermute_b32 v9, v57, v8
	ds_bpermute_b32 v3, v57, v2
	s_waitcnt lgkmcnt(3)
	v_add_f32_e32 v73, v73, v74
	ds_bpermute_b32 v74, v58, v73
	s_waitcnt lgkmcnt(3)
	v_add_f32_e32 v4, v4, v5
	s_waitcnt lgkmcnt(2)
	v_add_f32_e32 v8, v8, v9
	s_waitcnt lgkmcnt(1)
	v_add_f32_e32 v2, v2, v3
	ds_bpermute_b32 v5, v58, v4
	ds_bpermute_b32 v9, v58, v8
	ds_bpermute_b32 v3, v58, v2
	s_waitcnt lgkmcnt(3)
	v_add_f32_e32 v73, v73, v74
	ds_bpermute_b32 v74, v59, v73
	s_waitcnt lgkmcnt(3)
	v_add_f32_e32 v4, v4, v5
	s_waitcnt lgkmcnt(2)
	v_add_f32_e32 v8, v8, v9
	s_waitcnt lgkmcnt(1)
	v_add_f32_e32 v10, v2, v3
	ds_bpermute_b32 v76, v59, v75
	ds_bpermute_b32 v5, v59, v4
	ds_bpermute_b32 v9, v59, v8
	ds_bpermute_b32 v11, v59, v10
	s_waitcnt lgkmcnt(4)
	v_add_f32_e32 v73, v73, v74
	s_waitcnt lgkmcnt(3)
	v_add_f32_e32 v75, v75, v76
	s_waitcnt lgkmcnt(2)
	v_add_f32_e32 v2, v4, v5
	s_waitcnt lgkmcnt(1)
	v_add_f32_e32 v4, v8, v9
	s_waitcnt lgkmcnt(0)
	v_add_f32_e32 v8, v10, v11
	ds_bpermute_b32 v70, v60, v69
	ds_bpermute_b32 v72, v60, v71
	ds_bpermute_b32 v74, v60, v73
	ds_bpermute_b32 v76, v60, v75
	ds_bpermute_b32 v3, v60, v2
	ds_bpermute_b32 v5, v60, v4
	ds_bpermute_b32 v9, v60, v8
	s_and_saveexec_b64 s[24:25], s[6:7]
	s_cbranch_execz .LBB0_33
	global_load_dword v6, v[36:37], off
	s_waitcnt lgkmcnt(0)
	v_add_f32_e32 v7, v8, v9
	v_add_f32_e32 v9, v69, v70
	v_add_f32_e32 v10, v53, v68
	v_add_f32_e32 v8, v71, v72
	v_cndmask_b32_e64 v9, v10, v9, s[10:11]
	v_add_f32_e32 v4, v4, v5
	v_add_f32_e32 v5, v73, v74
	v_cndmask_b32_e64 v8, v9, v8, s[12:13]
	v_add_f32_e32 v2, v2, v3
	v_add_f32_e32 v3, v75, v76
	v_cndmask_b32_e64 v5, v8, v5, s[14:15]
	v_cndmask_b32_e64 v3, v5, v3, s[16:17]
	v_cndmask_b32_e64 v2, v3, v2, s[18:19]
	v_cndmask_b32_e64 v2, v2, v4, s[20:21]
	v_cndmask_b32_e64 v2, v2, v7, s[22:23]
	s_waitcnt vmcnt(0)
	v_add_f32_e32 v2, v2, v6
	v_mul_f32_e32 v2, 0x3d888889, v2
	v_cmp_nlt_f32_e64 s[38:39], |v2|, s31
	s_and_saveexec_b64 s[62:63], s[38:39]
	s_xor_b64 s[38:39], exec, s[62:63]
	s_cbranch_execz .LBB0_37
	v_add_f32_e64 v3, |v2|, |v2|
	v_mul_f32_e32 v4, 0x3fb8aa3b, v3
	v_rndne_f32_e32 v5, v4
	v_sub_f32_e32 v6, v4, v5
	v_fma_f32 v4, v3, s40, -v4
	v_fmac_f32_e32 v4, 0x32a5705f, v3
	v_add_f32_e32 v4, v6, v4
	v_cvt_i32_f32_e32 v5, v5
	v_exp_f32_e32 v4, v4
	v_cmp_ngt_f32_e32 vcc, s41, v3
	v_ldexp_f32 v4, v4, v5
	s_nop 0
	v_cndmask_b32_e32 v4, 0, v4, vcc
	v_cmp_nlt_f32_e32 vcc, s48, v3
	s_nop 1
	v_cndmask_b32_e32 v3, v67, v4, vcc
	v_add_f32_e32 v3, 1.0, v3
	v_rcp_f32_e32 v3, v3
	s_nop 0
	v_fma_f32 v3, v3, -2.0, 1.0

; #define LAS __attribute__((address_space(3)))
; __device__ __forceinline__ void m3_phase(const Ctx& C, const float* mnorm_g, const float* conv_w, const float* conv_b) {
;     ...
;         { f32x4 accI[4][2], accP[4][2];
; #pragma unroll
;           for (int rt = 0; rt < 4; ++rt)
; #pragma unroll
;             for (int ci = 0; ci < 2; ++ci) { accI[rt][ci] = (f32x4){0.f, 0.f, 0.f, 0.f}; accP[rt][ci] = (f32x4){0.f, 0.f, 0.f, 0.f}; }
; #pragma unroll
;           for (int ks = 0; ks < 4; ++ks) {
; #pragma unroll
;             for (int rt = 0; rt < 4; ++rt) { const bf16x8 a = *(const LAS bf16x8*)(Qs + (rt * 16 + fr) * QKS + 32 * ks + 8 * fq);
; #pragma unroll
;                 for (int ci = 0; ci < 2; ++ci) accI[rt][ci] = __builtin_amdgcn_mfma_f32_16x16x32_bf16(a, ctf[ks][ci], accI[rt][ci], 0, 0, 0); } }
; #pragma unroll
;           for (int ks = 0; ks < 2; ++ks) { bf16x8 b[2];
; #pragma unroll
;             for (int ci = 0; ci < 2; ++ci) b[ci] = *(const LAS bf16x8*)(VT + ((2 * wave + ci) * 16 + fr) * VTS + 32 * ks + 8 * fq);
; #pragma unroll
;             for (int rt = 0; rt < 4; ++rt) { const bf16x8 a = *(const LAS bf16x8*)(P + (rt * 16 + fr) * VTS + 32 * ks + 8 * fq);
; #pragma unroll
;                 for (int ci = 0; ci < 2; ++ci) accP[rt][ci] = __builtin_amdgcn_mfma_f32_16x16x32_bf16(a, b[ci], accP[rt][ci], 0, 0, 0); } }
.LBB0_627:
	s_or_b64 exec, exec, s[78:79]
	s_waitcnt lgkmcnt(0)
	s_barrier
	ds_read_b128 v[38:41], v207
	ds_read_b128 v[46:49], v207 offset:4352
	ds_read_b128 v[54:57], v207 offset:8704
	ds_read_b128 v[62:65], v207 offset:13056
	s_add_i32 s80, s80, s46
	s_add_i32 s3, s3, s93
	s_waitcnt lgkmcnt(3)
	v_mfma_f32_16x16x32_bf16 v[42:45], v[38:41], v[30:33], 0
	v_lshl_add_u64 v[116:117], v[116:117], 0, s[74:75]
	v_add_u32_e32 v118, s94, v118
	v_mfma_f32_16x16x32_bf16 v[38:41], v[38:41], v[34:37], 0
	s_waitcnt lgkmcnt(2)
	v_mfma_f32_16x16x32_bf16 v[50:53], v[46:49], v[30:33], 0
	v_mfma_f32_16x16x32_bf16 v[46:49], v[46:49], v[34:37], 0
	s_waitcnt lgkmcnt(1)
	v_mfma_f32_16x16x32_bf16 v[58:61], v[54:57], v[30:33], 0
	v_mfma_f32_16x16x32_bf16 v[54:57], v[54:57], v[34:37], 0
	s_waitcnt lgkmcnt(0)
	v_mfma_f32_16x16x32_bf16 v[30:33], v[62:65], v[30:33], 0
	v_mfma_f32_16x16x32_bf16 v[34:37], v[62:65], v[34:37], 0
	ds_read_b128 v[62:65], v207 offset:64
	s_waitcnt lgkmcnt(0)
	v_mfma_f32_16x16x32_bf16 v[42:45], v[62:65], v[22:25], v[42:45]
	v_mfma_f32_16x16x32_bf16 v[38:41], v[62:65], v[26:29], v[38:41]
	ds_read_b128 v[62:65], v207 offset:4416
	s_waitcnt lgkmcnt(0)
	v_mfma_f32_16x16x32_bf16 v[50:53], v[62:65], v[22:25], v[50:53]
	v_mfma_f32_16x16x32_bf16 v[46:49], v[62:65], v[26:29], v[46:49]
	ds_read_b128 v[62:65], v207 offset:8768
	s_waitcnt lgkmcnt(0)
	v_mfma_f32_16x16x32_bf16 v[58:61], v[62:65], v[22:25], v[58:61]
	v_mfma_f32_16x16x32_bf16 v[54:57], v[62:65], v[26:29], v[54:57]
	ds_read_b128 v[62:65], v207 offset:13120
	s_waitcnt lgkmcnt(0)
	v_mfma_f32_16x16x32_bf16 v[22:25], v[62:65], v[22:25], v[30:33]
	s_nop 2
	ds_read_b128 v[30:33], v207 offset:128
	v_mfma_f32_16x16x32_bf16 v[26:29], v[62:65], v[26:29], v[34:37]
	s_waitcnt lgkmcnt(0)
	v_mfma_f32_16x16x32_bf16 v[34:37], v[30:33], v[14:17], v[42:45]
	v_mfma_f32_16x16x32_bf16 v[30:33], v[30:33], v[18:21], v[38:41]
	s_nop 2
	ds_read_b128 v[38:41], v207 offset:4480
	s_waitcnt lgkmcnt(0)
	v_mfma_f32_16x16x32_bf16 v[42:45], v[38:41], v[14:17], v[50:53]
	v_mfma_f32_16x16x32_bf16 v[38:41], v[38:41], v[18:21], v[46:49]
	s_nop 2
	ds_read_b128 v[46:49], v207 offset:8832
	s_waitcnt lgkmcnt(0)
	v_mfma_f32_16x16x32_bf16 v[50:53], v[46:49], v[14:17], v[58:61]
	v_mfma_f32_16x16x32_bf16 v[46:49], v[46:49], v[18:21], v[54:57]
	s_nop 2
	ds_read_b128 v[54:57], v207 offset:13184
	s_waitcnt lgkmcnt(0)
	v_mfma_f32_16x16x32_bf16 v[14:17], v[54:57], v[14:17], v[22:25]
	s_nop 2
	ds_read_b128 v[22:25], v207 offset:192
	v_mfma_f32_16x16x32_bf16 v[18:21], v[54:57], v[18:21], v[26:29]
	s_waitcnt lgkmcnt(0)
	v_mfma_f32_16x16x32_bf16 v[58:61], v[22:25], v[6:9], v[34:37]
	v_mfma_f32_16x16x32_bf16 v[54:57], v[22:25], v[10:13], v[30:33]
	ds_read_b128 v[22:25], v207 offset:4544
	s_nop 1
	ds_read_b128 v[30:33], v207 offset:13248
	s_waitcnt lgkmcnt(1)
	v_mfma_f32_16x16x32_bf16 v[42:45], v[22:25], v[6:9], v[42:45]
	v_mfma_f32_16x16x32_bf16 v[38:41], v[22:25], v[10:13], v[38:41]
	ds_read_b128 v[22:25], v207 offset:8896
	s_waitcnt lgkmcnt(0)
	v_mfma_f32_16x16x32_bf16 v[26:29], v[22:25], v[6:9], v[50:53]
	v_mfma_f32_16x16x32_bf16 v[22:25], v[22:25], v[10:13], v[46:49]
	v_mfma_f32_16x16x32_bf16 v[14:17], v[30:33], v[6:9], v[14:17]
	v_mfma_f32_16x16x32_bf16 v[6:9], v[30:33], v[10:13], v[18:21]
	ds_read_b128 v[10:13], v208 offset:34816
	s_nop 1
	ds_read_b128 v[18:21], v208 offset:37120
	ds_read_b128 v[30:33], v209
	ds_read_b128 v[46:49], v209 offset:2304
	ds_read_b128 v[62:65], v209 offset:4608
	s_waitcnt lgkmcnt(0)
	v_mfma_f32_16x16x32_bf16 v[70:73], v[62:65], v[10:13], 0
	v_mfma_f32_16x16x32_bf16 v[80:83], v[62:65], v[18:21], 0
	ds_read_b128 v[62:65], v209 offset:6912
	v_mfma_f32_16x16x32_bf16 v[34:37], v[30:33], v[10:13], 0
	v_mfma_f32_16x16x32_bf16 v[30:33], v[30:33], v[18:21], 0
	v_mfma_f32_16x16x32_bf16 v[50:53], v[46:49], v[10:13], 0
	v_mfma_f32_16x16x32_bf16 v[46:49], v[46:49], v[18:21], 0
	s_waitcnt lgkmcnt(0)
	v_mfma_f32_16x16x32_bf16 v[10:13], v[62:65], v[10:13], 0
	v_mfma_f32_16x16x32_bf16 v[84:87], v[62:65], v[18:21], 0
	ds_read_b128 v[18:21], v208 offset:34880
	ds_read_b128 v[88:91], v208 offset:37184
	ds_read_b128 v[62:65], v209 offset:64
	s_waitcnt lgkmcnt(0)
	v_mfma_f32_16x16x32_bf16 v[66:69], v[62:65], v[18:21], v[34:37]
	v_mfma_f32_16x16x32_bf16 v[62:65], v[62:65], v[88:91], v[30:33]
	s_nop 2
	ds_read_b128 v[30:33], v209 offset:2368
	s_waitcnt lgkmcnt(0)
	v_mfma_f32_16x16x32_bf16 v[50:53], v[30:33], v[18:21], v[50:53]
	v_mfma_f32_16x16x32_bf16 v[46:49], v[30:33], v[88:91], v[46:49]
	ds_read_b128 v[30:33], v209 offset:4672
	s_waitcnt lgkmcnt(0)
	v_mfma_f32_16x16x32_bf16 v[34:37], v[30:33], v[18:21], v[70:73]
	s_nop 2
	ds_read_b128 v[70:73], v209 offset:6976
	v_mfma_f32_16x16x32_bf16 v[30:33], v[30:33], v[88:91], v[80:83]
	s_waitcnt lgkmcnt(0)
	v_mfma_f32_16x16x32_bf16 v[18:21], v[70:73], v[18:21], v[10:13]
	v_mfma_f32_16x16x32_bf16 v[10:13], v[70:73], v[88:91], v[84:87]
	ds_read_b128 v[70:73], v196
	ds_read_b128 v[80:83], v197
	s_waitcnt lgkmcnt(1)
	v_fma_f32 v54, v54, v70, v62
	s_waitcnt lgkmcnt(0)
; __device__ __forceinline__ void m3_phase(const Ctx& C, const float* mnorm_g, const float* conv_w, const float* conv_b) {
;     ...
;           for (int rt = 0; rt < 4; ++rt)
; #pragma unroll
;             for (int j = 0; j < 4; ++j) { const int t = rt * 16 + 4 * fq + j; const float e = eb[t], dn = 1.0f / fmaxf(fabsf(den[t]), 1.0f);
; #pragma unroll
;                 for (int ci = 0; ci < 2; ++ci) hv[rt][ci][j] = (e * accI[rt][ci][j] + accP[rt][ci][j]) * dn; } }
	v_max_f32_e64 v79, |v80|, |v80|
	v_max_f32_e32 v79, 1.0, v79
	v_div_scale_f32 v80, s[4:5], v79, v79, 1.0
	v_rcp_f32_e32 v84, v80
	v_max_f32_e64 v62, |v81|, |v81|
	v_max_f32_e32 v62, 1.0, v62
	v_fma_f32 v58, v58, v70, v66
	v_fma_f32 v85, -v80, v84, 1.0
	v_fmac_f32_e32 v84, v85, v84
	v_div_scale_f32 v85, vcc, 1.0, v79, 1.0
	v_mul_f32_e32 v86, v85, v84
	v_fma_f32 v87, -v80, v86, v85
	v_div_scale_f32 v66, s[4:5], v62, v62, 1.0
	v_fmac_f32_e32 v86, v87, v84
	v_rcp_f32_e32 v70, v66
	v_fma_f32 v80, -v80, v86, v85
	v_div_fmas_f32 v80, v80, v84, v86
	v_div_fixup_f32 v79, v80, v79, 1.0
	v_mul_f32_e32 v58, v58, v79
	v_mul_f32_e32 v54, v54, v79
	v_fma_f32 v79, -v66, v70, 1.0
	v_fmac_f32_e32 v70, v79, v70
	v_div_scale_f32 v79, vcc, 1.0, v62, 1.0
	v_mul_f32_e32 v80, v79, v70
	v_fma_f32 v81, -v66, v80, v79
	v_fmac_f32_e32 v80, v81, v70
	v_fma_f32 v66, -v66, v80, v79
	v_div_fmas_f32 v66, v66, v70, v80
	v_div_fixup_f32 v62, v66, v62, 1.0
	v_fma_f32 v59, v59, v71, v67
	v_fma_f32 v55, v55, v71, v63
	v_mul_f32_e32 v59, v59, v62
	v_mul_f32_e32 v55, v55, v62
	v_max_f32_e64 v62, |v82|, |v82|
	v_max_f32_e32 v62, 1.0, v62
	v_div_scale_f32 v63, s[4:5], v62, v62, 1.0
	v_rcp_f32_e32 v66, v63
	v_fma_f32 v60, v60, v72, v68
	v_fma_f32 v56, v56, v72, v64
	v_fmac_f32_e32 v69, v61, v73
	v_fma_f32 v67, -v63, v66, 1.0
	v_fmac_f32_e32 v66, v67, v66
	v_div_scale_f32 v67, vcc, 1.0, v62, 1.0
	v_mul_f32_e32 v70, v67, v66
	v_fma_f32 v71, -v63, v70, v67
	v_fmac_f32_e32 v70, v71, v66
	v_fma_f32 v63, -v63, v70, v67
	v_div_fmas_f32 v63, v63, v66, v70
	v_div_fixup_f32 v62, v63, v62, 1.0
	v_mul_f32_e32 v60, v60, v62
	v_mul_f32_e32 v56, v56, v62
	v_max_f32_e64 v62, |v83|, |v83|
	v_max_f32_e32 v62, 1.0, v62
	v_div_scale_f32 v63, s[4:5], v62, v62, 1.0
	v_rcp_f32_e32 v64, v63
	v_fmac_f32_e32 v65, v57, v73
	v_fma_f32 v66, -v63, v64, 1.0
	v_fmac_f32_e32 v64, v66, v64
	v_div_scale_f32 v66, vcc, 1.0, v62, 1.0
	v_mul_f32_e32 v67, v66, v64
	v_fma_f32 v68, -v63, v67, v66
	v_fmac_f32_e32 v67, v68, v64
	v_fma_f32 v63, -v63, v67, v66
	v_div_fmas_f32 v63, v63, v64, v67
	v_div_fixup_f32 v62, v63, v62, 1.0
	v_mul_f32_e32 v61, v69, v62
	v_mul_f32_e32 v57, v65, v62
	ds_read_b128 v[62:65], v198
	ds_read_b128 v[66:69], v199
	s_waitcnt lgkmcnt(1)
	v_fma_f32 v38, v38, v62, v46
	s_waitcnt lgkmcnt(0)
	v_max_f32_e64 v66, |v66|, |v66|
	v_max_f32_e32 v66, 1.0, v66
	v_div_scale_f32 v70, s[4:5], v66, v66, 1.0
	v_rcp_f32_e32 v71, v70
	v_max_f32_e64 v46, |v67|, |v67|
	v_max_f32_e32 v46, 1.0, v46
	v_fma_f32 v42, v42, v62, v50
	v_fma_f32 v72, -v70, v71, 1.0
	v_fmac_f32_e32 v71, v72, v71
	v_div_scale_f32 v72, vcc, 1.0, v66, 1.0
	v_mul_f32_e32 v73, v72, v71
	v_fma_f32 v79, -v70, v73, v72
	v_div_scale_f32 v50, s[4:5], v46, v46, 1.0
	v_fmac_f32_e32 v73, v79, v71
	v_rcp_f32_e32 v62, v50
	v_fma_f32 v70, -v70, v73, v72
	v_div_fmas_f32 v70, v70, v71, v73
	v_div_fixup_f32 v66, v70, v66, 1.0
	v_mul_f32_e32 v42, v42, v66
	v_mul_f32_e32 v38, v38, v66
	v_fma_f32 v66, -v50, v62, 1.0
	v_fmac_f32_e32 v62, v66, v62
	v_div_scale_f32 v66, vcc, 1.0, v46, 1.0
	v_mul_f32_e32 v67, v66, v62
	v_fma_f32 v70, -v50, v67, v66
	v_fmac_f32_e32 v67, v70, v62
	v_fma_f32 v50, -v50, v67, v66
	v_div_fmas_f32 v50, v50, v62, v67
	v_div_fixup_f32 v46, v50, v46, 1.0
	v_fma_f32 v43, v43, v63, v51
	v_fma_f32 v39, v39, v63, v47
	v_mul_f32_e32 v43, v43, v46
	v_mul_f32_e32 v39, v39, v46
	v_max_f32_e64 v46, |v68|, |v68|
	v_max_f32_e32 v46, 1.0, v46
	v_div_scale_f32 v47, s[4:5], v46, v46, 1.0
	v_rcp_f32_e32 v50, v47
	v_fma_f32 v44, v44, v64, v52
	v_fma_f32 v40, v40, v64, v48
	v_fmac_f32_e32 v53, v45, v65
	v_fma_f32 v51, -v47, v50, 1.0
	v_fmac_f32_e32 v50, v51, v50
	v_div_scale_f32 v51, vcc, 1.0, v46, 1.0
	v_mul_f32_e32 v62, v51, v50
	v_fma_f32 v63, -v47, v62, v51
	v_fmac_f32_e32 v62, v63, v50
	v_fma_f32 v47, -v47, v62, v51
	v_div_fmas_f32 v47, v47, v50, v62
	v_div_fixup_f32 v46, v47, v46, 1.0
	v_mul_f32_e32 v52, v44, v46
	v_max_f32_e64 v44, |v69|, |v69|
	v_max_f32_e32 v44, 1.0, v44
	v_mul_f32_e32 v40, v40, v46
	v_div_scale_f32 v46, s[4:5], v44, v44, 1.0
	v_rcp_f32_e32 v47, v46
	v_fmac_f32_e32 v49, v41, v65
	v_fma_f32 v48, -v46, v47, 1.0
	v_fmac_f32_e32 v47, v48, v47
	v_div_scale_f32 v48, vcc, 1.0, v44, 1.0
	v_mul_f32_e32 v50, v48, v47
	v_fma_f32 v51, -v46, v50, v48
	v_fmac_f32_e32 v50, v51, v47
	v_fma_f32 v46, -v46, v50, v48
	v_div_fmas_f32 v46, v46, v47, v50
	v_div_fixup_f32 v44, v46, v44, 1.0
	v_mul_f32_e32 v53, v53, v44
	v_mul_f32_e32 v41, v49, v44
	ds_read_b128 v[44:47], v200
	ds_read_b128 v[48:51], v201
	s_waitcnt lgkmcnt(1)
	v_fma_f32 v22, v22, v44, v30
	s_waitcnt lgkmcnt(0)
	v_max_f32_e64 v48, |v48|, |v48|
	v_max_f32_e32 v48, 1.0, v48
	v_div_scale_f32 v62, s[4:5], v48, v48, 1.0
	v_rcp_f32_e32 v63, v62
	v_fma_f32 v26, v26, v44, v34
	v_fma_f32 v23, v23, v45, v31
	v_fmac_f32_e32 v37, v29, v47
	v_fma_f32 v64, -v62, v63, 1.0
	v_fmac_f32_e32 v63, v64, v63
	v_div_scale_f32 v64, vcc, 1.0, v48, 1.0
	v_mul_f32_e32 v65, v64, v63
	v_fma_f32 v66, -v62, v65, v64
	v_fmac_f32_e32 v65, v66, v63
	v_fma_f32 v62, -v62, v65, v64
	v_div_fmas_f32 v62, v62, v63, v65
	v_div_fixup_f32 v48, v62, v48, 1.0
	v_mul_f32_e32 v30, v22, v48
	v_max_f32_e64 v22, |v49|, |v49|
	v_max_f32_e32 v22, 1.0, v22
	v_mul_f32_e32 v34, v26, v48
	v_div_scale_f32 v26, s[4:5], v22, v22, 1.0
	v_rcp_f32_e32 v44, v26
	v_fmac_f32_e32 v33, v25, v47
	v_fma_f32 v48, -v26, v44, 1.0
	v_fmac_f32_e32 v44, v48, v44
	v_div_scale_f32 v48, vcc, 1.0, v22, 1.0
	v_mul_f32_e32 v49, v48, v44
	v_fma_f32 v62, -v26, v49, v48
	v_fmac_f32_e32 v49, v62, v44
	v_fma_f32 v26, -v26, v49, v48
	v_div_fmas_f32 v26, v26, v44, v49
	v_div_fixup_f32 v22, v26, v22, 1.0
	v_fma_f32 v26, v27, v45, v35
	v_mul_f32_e32 v35, v26, v22
	v_mul_f32_e32 v31, v23, v22
	v_max_f32_e64 v22, |v50|, |v50|
	v_max_f32_e32 v22, 1.0, v22
	v_div_scale_f32 v23, s[4:5], v22, v22, 1.0
	v_rcp_f32_e32 v26, v23
	s_nop 0
	v_fma_f32 v27, -v23, v26, 1.0
	v_fmac_f32_e32 v26, v27, v26
	v_div_scale_f32 v27, vcc, 1.0, v22, 1.0
	v_mul_f32_e32 v44, v27, v26
	v_fma_f32 v45, -v23, v44, v27
	v_fmac_f32_e32 v44, v45, v26
	v_fma_f32 v23, -v23, v44, v27
	v_div_fmas_f32 v23, v23, v26, v44
	v_div_fixup_f32 v22, v23, v22, 1.0
	v_fma_f32 v23, v28, v46, v36
	v_mul_f32_e32 v36, v23, v22
	v_fma_f32 v23, v24, v46, v32
	v_mul_f32_e32 v32, v23, v22
	v_max_f32_e64 v22, |v51|, |v51|
	v_max_f32_e32 v22, 1.0, v22
	v_div_scale_f32 v23, s[4:5], v22, v22, 1.0
	v_rcp_f32_e32 v24, v23
	s_nop 0
	v_fma_f32 v26, -v23, v24, 1.0
	v_fmac_f32_e32 v24, v26, v24
	v_div_scale_f32 v26, vcc, 1.0, v22, 1.0
	v_mul_f32_e32 v27, v26, v24
	v_fma_f32 v28, -v23, v27, v26
	v_fmac_f32_e32 v27, v28, v24
	v_fma_f32 v23, -v23, v27, v26
	v_div_fmas_f32 v23, v23, v24, v27
	v_div_fixup_f32 v22, v23, v22, 1.0
	v_mul_f32_e32 v37, v37, v22
	v_mul_f32_e32 v33, v33, v22
	ds_read_b128 v[22:25], v202
	ds_read_b128 v[26:29], v203
	s_waitcnt lgkmcnt(0)
	s_barrier
; #define LAS __attribute__((address_space(3)))
; __device__ __forceinline__ void m3_phase(const Ctx& C, const float* mnorm_g, const float* conv_w, const float* conv_b) {
;     ...
;           for (int rt = 0; rt < 4; ++rt)
; #pragma unroll
;             for (int j = 0; j < 4; ++j) { const int t = rt * 16 + 4 * fq + j; const float e = eb[t], dn = 1.0f / fmaxf(fabsf(den[t]), 1.0f);
; #pragma unroll
;                 for (int ci = 0; ci < 2; ++ci) hv[rt][ci][j] = (e * accI[rt][ci][j] + accP[rt][ci][j]) * dn; } }
;         __syncthreads();
; #pragma unroll
;         for (int rt = 0; rt < 4; ++rt)
; #pragma unroll
;             for (int ci = 0; ci < 2; ++ci)
; #pragma unroll
;                 for (int j = 0; j < 4; ++j) Hb[(rt * 16 + 4 * fq + j) * 260 + (2 * wave + ci) * 16 + fr] = hv[rt][ci][j];
;         __syncthreads();
; #pragma unroll
;         for (int i = 0; i < 8; ++i) { const int t = 8 * wave + i;
;             const f32x4 v = *(const LAS f32x4*)(Hb + t * 260 + 4 * lane);
;             const float ss = wave_sum((v.x * v.x + v.y * v.y) + (v.z * v.z + v.w * v.w));
;             const float rs = 1.0f / sqrtf(ss * (1.0f / DV) + EPS);
	v_fma_f32 v6, v6, v22, v10
	v_max_f32_e64 v26, |v26|, |v26|
	v_max_f32_e32 v26, 1.0, v26
	v_div_scale_f32 v44, s[4:5], v26, v26, 1.0
	v_rcp_f32_e32 v45, v44
	v_max_f32_e64 v10, |v27|, |v27|
	v_max_f32_e32 v10, 1.0, v10
	v_fma_f32 v14, v14, v22, v18
	v_fma_f32 v46, -v44, v45, 1.0
	v_fmac_f32_e32 v45, v46, v45
	v_div_scale_f32 v46, vcc, 1.0, v26, 1.0
	v_mul_f32_e32 v47, v46, v45
	v_fma_f32 v48, -v44, v47, v46
	v_div_scale_f32 v18, s[4:5], v10, v10, 1.0
	v_fmac_f32_e32 v47, v48, v45
	v_rcp_f32_e32 v22, v18
	v_fma_f32 v44, -v44, v47, v46
	v_div_fmas_f32 v44, v44, v45, v47
	v_div_fixup_f32 v26, v44, v26, 1.0
	v_mul_f32_e32 v14, v14, v26
	v_mul_f32_e32 v6, v6, v26
	v_fma_f32 v26, -v18, v22, 1.0
	v_fmac_f32_e32 v22, v26, v22
	v_div_scale_f32 v26, vcc, 1.0, v10, 1.0
	v_mul_f32_e32 v27, v26, v22
	v_fma_f32 v44, -v18, v27, v26
	v_fmac_f32_e32 v27, v44, v22
	v_fma_f32 v18, -v18, v27, v26
	v_div_fmas_f32 v18, v18, v22, v27
	v_div_fixup_f32 v10, v18, v10, 1.0
	v_fma_f32 v15, v15, v23, v19
	v_fma_f32 v7, v7, v23, v11
	v_mul_f32_e32 v15, v15, v10
	v_mul_f32_e32 v7, v7, v10
	v_max_f32_e64 v10, |v28|, |v28|
	v_max_f32_e32 v10, 1.0, v10
	v_div_scale_f32 v11, s[4:5], v10, v10, 1.0
	v_rcp_f32_e32 v18, v11
	v_fma_f32 v8, v8, v24, v12
	v_fmac_f32_e32 v21, v17, v25
	v_fmac_f32_e32 v13, v9, v25
	v_fma_f32 v19, -v11, v18, 1.0
	v_fmac_f32_e32 v18, v19, v18
	v_div_scale_f32 v19, vcc, 1.0, v10, 1.0
	v_mul_f32_e32 v22, v19, v18
	v_fma_f32 v23, -v11, v22, v19
	v_fmac_f32_e32 v22, v23, v18
	v_fma_f32 v11, -v11, v22, v19
	v_div_fmas_f32 v11, v11, v18, v22
	v_div_fixup_f32 v10, v11, v10, 1.0
	v_fma_f32 v11, v16, v24, v20
	v_mul_f32_e32 v11, v11, v10
	v_mul_f32_e32 v8, v8, v10
	v_max_f32_e64 v10, |v29|, |v29|
	v_max_f32_e32 v10, 1.0, v10
	v_div_scale_f32 v12, s[4:5], v10, v10, 1.0
	v_rcp_f32_e32 v16, v12
	ds_write_b32 v210, v58
	ds_write_b32 v211, v59
	ds_write_b32 v211, v60 offset:1040
	ds_write_b32 v211, v61 offset:2080
	ds_write_b32 v210, v54 offset:64
	ds_write_b32 v211, v55 offset:64
	ds_write_b32 v211, v56 offset:1104
	ds_write_b32 v211, v57 offset:2144
	s_mul_i32 s4, s83, 0x2080
	v_fma_f32 v18, -v12, v16, 1.0
	v_fmac_f32_e32 v16, v18, v16
	v_div_scale_f32 v18, vcc, 1.0, v10, 1.0
	v_mul_f32_e32 v19, v18, v16
	v_fma_f32 v20, -v12, v19, v18
	v_fmac_f32_e32 v19, v20, v16
	v_fma_f32 v12, -v12, v19, v18
	v_div_fmas_f32 v12, v12, v16, v19
	v_div_fixup_f32 v10, v12, v10, 1.0
	v_mul_f32_e32 v12, v21, v10
	v_mul_f32_e32 v9, v13, v10
	v_add_u32_e32 v10, 0x3c00, v211
	ds_write2_b32 v10, v42, v38 offset0:60 offset1:76
	v_add_u32_e32 v10, 0x4000, v211
	ds_write2_b32 v10, v43, v39 offset0:64 offset1:80
	v_add_u32_e32 v10, 0x4400, v211
	ds_write2_b32 v10, v52, v40 offset0:68 offset1:84
	v_add_u32_e32 v10, 0x4800, v211
	ds_write2_b32 v10, v53, v41 offset0:72 offset1:88
	v_add_u32_e32 v10, 0x7c00, v211
	ds_write2_b32 v10, v34, v30 offset0:124 offset1:140
	v_add_u32_e32 v10, 0x8000, v211
	ds_write2_b32 v10, v35, v31 offset0:128 offset1:144
	v_add_u32_e32 v10, 0x8400, v211
	ds_write2_b32 v10, v36, v32 offset0:132 offset1:148
	v_add_u32_e32 v10, 0x8800, v211
	ds_write2_b32 v10, v37, v33 offset0:136 offset1:152
	v_add_u32_e32 v10, 0xbc00, v211
	ds_write2_b32 v10, v14, v6 offset0:188 offset1:204
	v_add_u32_e32 v6, 0xc000, v211
	ds_write2_b32 v6, v15, v7 offset0:192 offset1:208
	v_add_u32_e32 v6, 0xc400, v211
	ds_write2_b32 v6, v11, v8 offset0:196 offset1:212
	v_add_u32_e32 v6, 0xc800, v211
	ds_write2_b32 v6, v12, v9 offset0:200 offset1:216
	v_xor_b32_e32 v6, 8, v78
	v_cmp_lt_i32_e32 vcc, v6, v77
	s_waitcnt lgkmcnt(0)
	s_barrier
	v_cndmask_b32_e32 v6, v78, v6, vcc
	v_lshlrev_b32_e32 v12, 2, v6
	v_xor_b32_e32 v6, 16, v78
	v_cmp_lt_i32_e32 vcc, v6, v77
	v_lshl_add_u64 v[10:11], s[40:41], 1, v[112:113]
	s_nop 0
	v_cndmask_b32_e32 v6, v78, v6, vcc
	v_lshlrev_b32_e32 v13, 2, v6
	v_xor_b32_e32 v6, 32, v78
	v_cmp_lt_i32_e32 vcc, v6, v77
	s_nop 1
	v_cndmask_b32_e32 v6, v78, v6, vcc
	v_lshlrev_b32_e32 v14, 2, v6
	v_add_u32_e32 v6, s4, v174
	ds_read_b128 v[6:9], v6
	s_waitcnt lgkmcnt(0)
	v_mul_f32_e32 v15, v7, v7
	v_mul_f32_e32 v16, v9, v9
	v_fmac_f32_e32 v15, v6, v6
	v_fmac_f32_e32 v16, v8, v8
	v_add_f32_e32 v15, v15, v16
	s_waitcnt lgkmcnt(0)
	s_nop 1
	v_add_f32_dpp v15, v15, v15 quad_perm:[1,0,3,2] row_mask:0xf bank_mask:0xf
	s_waitcnt lgkmcnt(0)
	s_nop 1
	v_add_f32_dpp v15, v15, v15 quad_perm:[2,3,0,1] row_mask:0xf bank_mask:0xf
	s_waitcnt lgkmcnt(0)
	s_nop 1
	v_add_f32_dpp v15, v15, v15 row_half_mirror row_mask:0xf bank_mask:0xf
	s_waitcnt lgkmcnt(0)
	s_nop 1
	v_add_f32_dpp v15, v15, v15 row_mirror row_mask:0xf bank_mask:0xf
	s_waitcnt lgkmcnt(0)
	v_mov_b32_e32 v16, v15
	s_nop 1
	v_permlane16_swap_b32_e32 v15, v16
	v_add_f32_e32 v15, v15, v16
	s_waitcnt lgkmcnt(0)
; #define LAS __attribute__((address_space(3)))
; __device__ __forceinline__ float bf2f(unsigned h) { return __uint_as_float(h << 16); }
; __device__ __forceinline__ unsigned pk2(float lo, float hi) { return pg8::cvt_pk_bf16(lo, hi); }
; __device__ __forceinline__ float sigmoidf_(float v) { return 1.0f / (1.0f + __expf(-v)); }
; __device__ __forceinline__ void m3_phase(const Ctx& C, const float* mnorm_g, const float* conv_w, const float* conv_b) {
;     ...
;         for (int i = 0; i < 8; ++i) { const int t = 8 * wave + i;
;             const f32x4 v = *(const LAS f32x4*)(Hb + t * 260 + 4 * lane);
;             const float ss = wave_sum((v.x * v.x + v.y * v.y) + (v.z * v.z + v.w * v.w));
;             const float rs = 1.0f / sqrtf(ss * (1.0f / DV) + EPS);
;             const f32x4 g = gmn; const u32x2 mo = mov[i];
;             const float o0 = v.x * rs * g.x * sigmoidf_(bf2f(mo.x & 0xffffu)), o1 = v.y * rs * g.y * sigmoidf_(bf2f(mo.x >> 16));
;             const float o2 = v.z * rs * g.z * sigmoidf_(bf2f(mo.y & 0xffffu)), o3 = v.w * rs * g.w * sigmoidf_(bf2f(mo.y >> 16));
;             u32x2 w; w.x = pk2(o0, o1); w.y = pk2(o2, o3);
;             *(u32x2*)(CAT + (size_t)(row0 + t) * DM + h * DV + 4 * lane) = w; }
	v_mov_b32_e32 v16, v15
	s_nop 1
	v_permlane32_swap_b32_e32 v15, v16
	v_add_f32_e32 v15, v15, v16
	v_fmamk_f32 v15, v15, 0x3b800000, v212
	v_cmp_gt_f32_e32 vcc, s97, v15
	v_mul_f32_e32 v16, 0x4f800000, v15
	s_nop 0
	v_cndmask_b32_e32 v15, v15, v16, vcc
	v_sqrt_f32_e32 v16, v15
	s_nop 0
	v_add_u32_e32 v17, -1, v16
	v_fma_f32 v18, -v17, v16, v15
	v_cmp_ge_f32_e64 s[40:41], 0, v18
	v_add_u32_e32 v18, 1, v16
	s_nop 0
	v_cndmask_b32_e64 v17, v16, v17, s[40:41]
	v_fma_f32 v16, -v18, v16, v15
	v_cmp_lt_f32_e64 s[40:41], 0, v16
	s_nop 1
	v_cndmask_b32_e64 v16, v17, v18, s[40:41]
	v_mul_f32_e32 v17, 0x37800000, v16
	v_cndmask_b32_e32 v16, v16, v17, vcc
	v_cmp_class_f32_e32 vcc, v15, v213
	s_nop 1
	v_cndmask_b32_e32 v15, v16, v15, vcc
	v_div_scale_f32 v16, s[4:5], v15, v15, 1.0
	v_rcp_f32_e32 v17, v16
	s_nop 0
	v_fma_f32 v18, -v16, v17, 1.0
	v_fmac_f32_e32 v17, v18, v17
	v_div_scale_f32 v18, vcc, 1.0, v15, 1.0
	v_mul_f32_e32 v19, v18, v17
	v_fma_f32 v20, -v16, v19, v18
	v_fmac_f32_e32 v19, v20, v17
	v_fma_f32 v16, -v16, v19, v18
	v_div_fmas_f32 v16, v16, v17, v19
	v_div_fixup_f32 v15, v16, v15, 1.0
	v_lshlrev_b32_e32 v16, 16, v136
	v_mul_f32_e32 v16, 0xbfb8aa3b, v16
	v_exp_f32_e32 v16, v16
	v_mul_f32_e32 v6, v6, v15
	v_mul_f32_e32 v6, v2, v6
	v_mul_f32_e32 v7, v7, v15
	v_add_f32_e32 v16, 1.0, v16
	v_div_scale_f32 v17, s[4:5], v16, v16, 1.0
	v_rcp_f32_e32 v18, v17
	v_mul_f32_e32 v7, v3, v7
	v_mul_f32_e32 v8, v8, v15
	v_mul_f32_e32 v9, v9, v15
	v_fma_f32 v19, -v17, v18, 1.0
	v_fmac_f32_e32 v18, v19, v18
	v_div_scale_f32 v19, vcc, 1.0, v16, 1.0
	v_mul_f32_e32 v20, v19, v18
	v_fma_f32 v21, -v17, v20, v19
	v_fmac_f32_e32 v20, v21, v18
	v_fma_f32 v17, -v17, v20, v19
	v_div_fmas_f32 v17, v17, v18, v20
	v_div_fixup_f32 v16, v17, v16, 1.0
	v_mul_f32_e32 v6, v16, v6
	v_and_b32_e32 v16, 0xffff0000, v136
	v_mul_f32_e32 v16, 0xbfb8aa3b, v16
	v_exp_f32_e32 v16, v16
	v_and_b32_e32 v15, 0xffff0000, v137
	v_mul_f32_e32 v15, 0xbfb8aa3b, v15
	v_exp_f32_e32 v15, v15
	v_add_f32_e32 v16, 1.0, v16
	v_div_scale_f32 v17, s[4:5], v16, v16, 1.0
	v_rcp_f32_e32 v18, v17
	v_mul_f32_e32 v8, v4, v8
	v_add_f32_e32 v15, 1.0, v15
	v_mul_f32_e32 v9, v5, v9
	v_fma_f32 v19, -v17, v18, 1.0
	v_fmac_f32_e32 v18, v19, v18
	v_div_scale_f32 v19, vcc, 1.0, v16, 1.0
	v_mul_f32_e32 v20, v19, v18
	v_fma_f32 v21, -v17, v20, v19
	v_fmac_f32_e32 v20, v21, v18
	v_fma_f32 v17, -v17, v20, v19
	v_div_fmas_f32 v17, v17, v18, v20
	v_div_fixup_f32 v16, v17, v16, 1.0
	v_mul_f32_e32 v7, v16, v7
	v_lshlrev_b32_e32 v16, 16, v137
	v_mul_f32_e32 v16, 0xbfb8aa3b, v16
	v_exp_f32_e32 v16, v16
	v_cvt_pk_bf16_f32 v6, v6, v7
	s_nop 0
	v_add_f32_e32 v16, 1.0, v16
	v_div_scale_f32 v17, s[4:5], v16, v16, 1.0
	v_rcp_f32_e32 v18, v17
	s_nop 0
	v_fma_f32 v19, -v17, v18, 1.0
	v_fmac_f32_e32 v18, v19, v18
	v_div_scale_f32 v19, vcc, 1.0, v16, 1.0
	v_mul_f32_e32 v20, v19, v18
	v_fma_f32 v21, -v17, v20, v19
	v_fmac_f32_e32 v20, v21, v18
	v_fma_f32 v17, -v17, v20, v19
	v_div_fmas_f32 v17, v17, v18, v20
	v_div_fixup_f32 v16, v17, v16, 1.0
	v_mul_f32_e32 v8, v16, v8
	v_div_scale_f32 v16, s[4:5], v15, v15, 1.0
	v_rcp_f32_e32 v17, v16
	s_lshl_b64 s[4:5], s[76:77], 12
	v_fma_f32 v18, -v16, v17, 1.0
	v_fmac_f32_e32 v17, v18, v17
	v_div_scale_f32 v18, vcc, 1.0, v15, 1.0
	v_mul_f32_e32 v19, v18, v17
	v_fma_f32 v20, -v16, v19, v18
	v_fmac_f32_e32 v19, v20, v17
	v_fma_f32 v16, -v16, v19, v18
	v_div_fmas_f32 v16, v16, v17, v19
	v_div_fixup_f32 v15, v16, v15, 1.0
	v_mul_f32_e32 v9, v15, v9
	v_cvt_pk_bf16_f32 v7, v8, v9
	v_lshl_add_u64 v[8:9], v[10:11], 0, s[4:5]
	s_mul_i32 s4, s86, 0x410
	v_add_u32_e32 v15, s4, v174
	global_store_dwordx2 v[8:9], v[6:7], off
	ds_read_b128 v[6:9], v15
	s_waitcnt lgkmcnt(0)
	v_mul_f32_e32 v16, v7, v7
	v_mul_f32_e32 v17, v9, v9
	v_fmac_f32_e32 v16, v6, v6
	v_fmac_f32_e32 v17, v8, v8
	v_add_f32_e32 v16, v16, v17
	s_waitcnt lgkmcnt(0)
	s_nop 1
	v_add_f32_dpp v16, v16, v16 quad_perm:[1,0,3,2] row_mask:0xf bank_mask:0xf
	s_waitcnt lgkmcnt(0)
	s_nop 1
	v_add_f32_dpp v16, v16, v16 quad_perm:[2,3,0,1] row_mask:0xf bank_mask:0xf
	s_waitcnt lgkmcnt(0)
	s_nop 1
	v_add_f32_dpp v16, v16, v16 row_half_mirror row_mask:0xf bank_mask:0xf
	s_waitcnt lgkmcnt(0)
	s_nop 1
	v_add_f32_dpp v16, v16, v16 row_mirror row_mask:0xf bank_mask:0xf
	s_waitcnt lgkmcnt(0)
	v_mov_b32_e32 v17, v16
	s_nop 1
	v_permlane16_swap_b32_e32 v16, v17
	v_add_f32_e32 v16, v16, v17
	s_waitcnt lgkmcnt(0)
; #define LAS __attribute__((address_space(3)))
; __device__ __forceinline__ float bf2f(unsigned h) { return __uint_as_float(h << 16); }
; __device__ __forceinline__ unsigned pk2(float lo, float hi) { return pg8::cvt_pk_bf16(lo, hi); }
; __device__ __forceinline__ float sigmoidf_(float v) { return 1.0f / (1.0f + __expf(-v)); }
; __device__ __forceinline__ void m3_phase(const Ctx& C, const float* mnorm_g, const float* conv_w, const float* conv_b) {
;     ...
;         for (int i = 0; i < 8; ++i) { const int t = 8 * wave + i;
;             const f32x4 v = *(const LAS f32x4*)(Hb + t * 260 + 4 * lane);
;             const float ss = wave_sum((v.x * v.x + v.y * v.y) + (v.z * v.z + v.w * v.w));
;             const float rs = 1.0f / sqrtf(ss * (1.0f / DV) + EPS);
;             const f32x4 g = gmn; const u32x2 mo = mov[i];
;             const float o0 = v.x * rs * g.x * sigmoidf_(bf2f(mo.x & 0xffffu)), o1 = v.y * rs * g.y * sigmoidf_(bf2f(mo.x >> 16));
;             const float o2 = v.z * rs * g.z * sigmoidf_(bf2f(mo.y & 0xffffu)), o3 = v.w * rs * g.w * sigmoidf_(bf2f(mo.y >> 16));
;             u32x2 w; w.x = pk2(o0, o1); w.y = pk2(o2, o3);
;             *(u32x2*)(CAT + (size_t)(row0 + t) * DM + h * DV + 4 * lane) = w; }
	v_mov_b32_e32 v17, v16
	s_nop 1
	v_permlane32_swap_b32_e32 v16, v17
	v_add_f32_e32 v16, v16, v17
	v_fmamk_f32 v16, v16, 0x3b800000, v212
	v_cmp_gt_f32_e32 vcc, s97, v16
	v_mul_f32_e32 v17, 0x4f800000, v16
	s_nop 0
	v_cndmask_b32_e32 v16, v16, v17, vcc
	v_sqrt_f32_e32 v17, v16
	s_nop 0
	v_add_u32_e32 v18, -1, v17
	v_fma_f32 v19, -v18, v17, v16
	v_cmp_ge_f32_e64 s[40:41], 0, v19
	v_add_u32_e32 v19, 1, v17
	s_nop 0
	v_cndmask_b32_e64 v18, v17, v18, s[40:41]
	v_fma_f32 v17, -v19, v17, v16
	v_cmp_lt_f32_e64 s[40:41], 0, v17
	s_nop 1
	v_cndmask_b32_e64 v17, v18, v19, s[40:41]
	v_mul_f32_e32 v18, 0x37800000, v17
	v_cndmask_b32_e32 v17, v17, v18, vcc
	v_cmp_class_f32_e32 vcc, v16, v213
	s_nop 1
	v_cndmask_b32_e32 v16, v17, v16, vcc
	v_div_scale_f32 v17, s[4:5], v16, v16, 1.0
	v_rcp_f32_e32 v18, v17
	s_nop 0
	v_fma_f32 v19, -v17, v18, 1.0
	v_fmac_f32_e32 v18, v19, v18
	v_div_scale_f32 v19, vcc, 1.0, v16, 1.0
	v_mul_f32_e32 v20, v19, v18
	v_fma_f32 v21, -v17, v20, v19
	v_fmac_f32_e32 v20, v21, v18
	v_fma_f32 v17, -v17, v20, v19
	v_div_fmas_f32 v17, v17, v18, v20
	v_div_fixup_f32 v16, v17, v16, 1.0
	v_lshlrev_b32_e32 v17, 16, v134
	v_mul_f32_e32 v17, 0xbfb8aa3b, v17
	v_exp_f32_e32 v17, v17
	v_mul_f32_e32 v6, v6, v16
	v_mul_f32_e32 v6, v2, v6
	v_mul_f32_e32 v7, v7, v16
	v_add_f32_e32 v17, 1.0, v17
	v_div_scale_f32 v18, s[4:5], v17, v17, 1.0
	v_rcp_f32_e32 v19, v18
	v_mul_f32_e32 v7, v3, v7
	v_mul_f32_e32 v8, v8, v16
	v_mul_f32_e32 v9, v9, v16
	v_fma_f32 v20, -v18, v19, 1.0
	v_fmac_f32_e32 v19, v20, v19
	v_div_scale_f32 v20, vcc, 1.0, v17, 1.0
	v_mul_f32_e32 v21, v20, v19
	v_fma_f32 v22, -v18, v21, v20
	v_fmac_f32_e32 v21, v22, v19
	v_fma_f32 v18, -v18, v21, v20
	v_div_fmas_f32 v18, v18, v19, v21
	v_div_fixup_f32 v17, v18, v17, 1.0
	v_mul_f32_e32 v6, v17, v6
	v_and_b32_e32 v17, 0xffff0000, v134
	v_mul_f32_e32 v17, 0xbfb8aa3b, v17
	v_exp_f32_e32 v17, v17
	v_and_b32_e32 v16, 0xffff0000, v135
	v_mul_f32_e32 v16, 0xbfb8aa3b, v16
	v_exp_f32_e32 v16, v16
	v_add_f32_e32 v17, 1.0, v17
	v_div_scale_f32 v18, s[4:5], v17, v17, 1.0
	v_rcp_f32_e32 v19, v18
	v_mul_f32_e32 v8, v4, v8
	v_add_f32_e32 v16, 1.0, v16
	v_mul_f32_e32 v9, v5, v9
	v_fma_f32 v20, -v18, v19, 1.0
	v_fmac_f32_e32 v19, v20, v19
	v_div_scale_f32 v20, vcc, 1.0, v17, 1.0
	v_mul_f32_e32 v21, v20, v19
	v_fma_f32 v22, -v18, v21, v20
	v_fmac_f32_e32 v21, v22, v19
	v_fma_f32 v18, -v18, v21, v20
	v_div_fmas_f32 v18, v18, v19, v21
	v_div_fixup_f32 v17, v18, v17, 1.0
	v_mul_f32_e32 v7, v17, v7
	v_lshlrev_b32_e32 v17, 16, v135
	v_mul_f32_e32 v17, 0xbfb8aa3b, v17
	v_exp_f32_e32 v17, v17
	v_cvt_pk_bf16_f32 v6, v6, v7
	s_nop 0
	v_add_f32_e32 v17, 1.0, v17
	v_div_scale_f32 v18, s[4:5], v17, v17, 1.0
	v_rcp_f32_e32 v19, v18
	s_nop 0
	v_fma_f32 v20, -v18, v19, 1.0
	v_fmac_f32_e32 v19, v20, v19
	v_div_scale_f32 v20, vcc, 1.0, v17, 1.0
	v_mul_f32_e32 v21, v20, v19
	v_fma_f32 v22, -v18, v21, v20
	v_fmac_f32_e32 v21, v22, v19
	v_fma_f32 v18, -v18, v21, v20
	v_div_fmas_f32 v18, v18, v19, v21
	v_div_fixup_f32 v17, v18, v17, 1.0
	v_mul_f32_e32 v8, v17, v8
	v_div_scale_f32 v17, s[4:5], v16, v16, 1.0
	v_rcp_f32_e32 v18, v17
	s_add_i32 s4, s52, s86
	s_ashr_i32 s5, s4, 31
	s_lshl_b64 s[4:5], s[4:5], 12
	v_fma_f32 v19, -v17, v18, 1.0
	v_fmac_f32_e32 v18, v19, v18
	v_div_scale_f32 v19, vcc, 1.0, v16, 1.0
	v_mul_f32_e32 v20, v19, v18
	v_fma_f32 v21, -v17, v20, v19
	v_fmac_f32_e32 v20, v21, v18
	v_fma_f32 v17, -v17, v20, v19
	v_div_fmas_f32 v17, v17, v18, v20
	v_div_fixup_f32 v16, v17, v16, 1.0
	v_mul_f32_e32 v9, v16, v9
	v_cvt_pk_bf16_f32 v7, v8, v9
	v_lshl_add_u64 v[8:9], v[10:11], 0, s[4:5]
	global_store_dwordx2 v[8:9], v[6:7], off
	ds_read_b128 v[6:9], v15 offset:1040
	s_waitcnt lgkmcnt(0)
	v_mul_f32_e32 v16, v7, v7
	v_mul_f32_e32 v17, v9, v9
	v_fmac_f32_e32 v16, v6, v6
	v_fmac_f32_e32 v17, v8, v8
	v_add_f32_e32 v16, v16, v17
	s_waitcnt lgkmcnt(0)
	s_nop 1
	v_add_f32_dpp v16, v16, v16 quad_perm:[1,0,3,2] row_mask:0xf bank_mask:0xf
	s_waitcnt lgkmcnt(0)
	s_nop 1
	v_add_f32_dpp v16, v16, v16 quad_perm:[2,3,0,1] row_mask:0xf bank_mask:0xf
	s_waitcnt lgkmcnt(0)
	s_nop 1
	v_add_f32_dpp v16, v16, v16 row_half_mirror row_mask:0xf bank_mask:0xf
	s_waitcnt lgkmcnt(0)
	s_nop 1
	v_add_f32_dpp v16, v16, v16 row_mirror row_mask:0xf bank_mask:0xf
	s_waitcnt lgkmcnt(0)
	v_mov_b32_e32 v17, v16
	s_nop 1
	v_permlane16_swap_b32_e32 v16, v17
	v_add_f32_e32 v16, v16, v17
	s_waitcnt lgkmcnt(0)
; #define LAS __attribute__((address_space(3)))
; __device__ __forceinline__ float bf2f(unsigned h) { return __uint_as_float(h << 16); }
; __device__ __forceinline__ unsigned pk2(float lo, float hi) { return pg8::cvt_pk_bf16(lo, hi); }
; __device__ __forceinline__ float sigmoidf_(float v) { return 1.0f / (1.0f + __expf(-v)); }
; __device__ __forceinline__ float wave_sum(float v) {
; #pragma unroll
;     for (int o = 1; o < 64; o <<= 1) v += __shfl_xor(v, o);
;     return v;
; }
; __device__ __forceinline__ void m3_phase(const Ctx& C, const float* mnorm_g, const float* conv_w, const float* conv_b) {
;     ...
;         for (int i = 0; i < 8; ++i) { const int t = 8 * wave + i;
;             const f32x4 v = *(const LAS f32x4*)(Hb + t * 260 + 4 * lane);
;             const float ss = wave_sum((v.x * v.x + v.y * v.y) + (v.z * v.z + v.w * v.w));
;             const float rs = 1.0f / sqrtf(ss * (1.0f / DV) + EPS);
;             const f32x4 g = gmn; const u32x2 mo = mov[i];
;             const float o0 = v.x * rs * g.x * sigmoidf_(bf2f(mo.x & 0xffffu)), o1 = v.y * rs * g.y * sigmoidf_(bf2f(mo.x >> 16));
;             const float o2 = v.z * rs * g.z * sigmoidf_(bf2f(mo.y & 0xffffu)), o3 = v.w * rs * g.w * sigmoidf_(bf2f(mo.y >> 16));
;             u32x2 w; w.x = pk2(o0, o1); w.y = pk2(o2, o3);
;             *(u32x2*)(CAT + (size_t)(row0 + t) * DM + h * DV + 4 * lane) = w; }
	v_mov_b32_e32 v17, v16
	s_nop 1
	v_permlane32_swap_b32_e32 v16, v17
	v_add_f32_e32 v16, v16, v17
	v_fmamk_f32 v16, v16, 0x3b800000, v212
	v_cmp_gt_f32_e32 vcc, s97, v16
	v_mul_f32_e32 v17, 0x4f800000, v16
	s_nop 0
	v_cndmask_b32_e32 v16, v16, v17, vcc
	v_sqrt_f32_e32 v17, v16
	s_nop 0
	v_add_u32_e32 v18, -1, v17
	v_fma_f32 v19, -v18, v17, v16
	v_cmp_ge_f32_e64 s[40:41], 0, v19
	v_add_u32_e32 v19, 1, v17
	s_nop 0
	v_cndmask_b32_e64 v18, v17, v18, s[40:41]
	v_fma_f32 v17, -v19, v17, v16
	v_cmp_lt_f32_e64 s[40:41], 0, v17
	s_nop 1
	v_cndmask_b32_e64 v17, v18, v19, s[40:41]
	v_mul_f32_e32 v18, 0x37800000, v17
	v_cndmask_b32_e32 v17, v17, v18, vcc
	v_cmp_class_f32_e32 vcc, v16, v213
	s_nop 1
	v_cndmask_b32_e32 v16, v17, v16, vcc
	v_div_scale_f32 v17, s[4:5], v16, v16, 1.0
	v_rcp_f32_e32 v18, v17
	s_nop 0
	v_fma_f32 v19, -v17, v18, 1.0
	v_fmac_f32_e32 v18, v19, v18
	v_div_scale_f32 v19, vcc, 1.0, v16, 1.0
	v_mul_f32_e32 v20, v19, v18
	v_fma_f32 v21, -v17, v20, v19
	v_fmac_f32_e32 v20, v21, v18
	v_fma_f32 v17, -v17, v20, v19
	v_div_fmas_f32 v17, v17, v18, v20
	v_div_fixup_f32 v16, v17, v16, 1.0
	v_lshlrev_b32_e32 v17, 16, v132
	v_mul_f32_e32 v17, 0xbfb8aa3b, v17
	v_exp_f32_e32 v17, v17
	v_mul_f32_e32 v6, v6, v16
	v_mul_f32_e32 v6, v2, v6
	v_mul_f32_e32 v7, v7, v16
	v_add_f32_e32 v17, 1.0, v17
	v_div_scale_f32 v18, s[4:5], v17, v17, 1.0
	v_rcp_f32_e32 v19, v18
	v_mul_f32_e32 v7, v3, v7
	v_mul_f32_e32 v8, v8, v16
	v_mul_f32_e32 v9, v9, v16
	v_fma_f32 v20, -v18, v19, 1.0
	v_fmac_f32_e32 v19, v20, v19
	v_div_scale_f32 v20, vcc, 1.0, v17, 1.0
	v_mul_f32_e32 v21, v20, v19
	v_fma_f32 v22, -v18, v21, v20
	v_fmac_f32_e32 v21, v22, v19
	v_fma_f32 v18, -v18, v21, v20
	v_div_fmas_f32 v18, v18, v19, v21
	v_div_fixup_f32 v17, v18, v17, 1.0
	v_mul_f32_e32 v6, v17, v6
	v_and_b32_e32 v17, 0xffff0000, v132
	v_mul_f32_e32 v17, 0xbfb8aa3b, v17
	v_exp_f32_e32 v17, v17
	v_and_b32_e32 v16, 0xffff0000, v133
	v_mul_f32_e32 v16, 0xbfb8aa3b, v16
	v_exp_f32_e32 v16, v16
	v_add_f32_e32 v17, 1.0, v17
	v_div_scale_f32 v18, s[4:5], v17, v17, 1.0
	v_rcp_f32_e32 v19, v18
	v_mul_f32_e32 v8, v4, v8
	v_add_f32_e32 v16, 1.0, v16
	v_mul_f32_e32 v9, v5, v9
	v_fma_f32 v20, -v18, v19, 1.0
	v_fmac_f32_e32 v19, v20, v19
	v_div_scale_f32 v20, vcc, 1.0, v17, 1.0
	v_mul_f32_e32 v21, v20, v19
	v_fma_f32 v22, -v18, v21, v20
	v_fmac_f32_e32 v21, v22, v19
	v_fma_f32 v18, -v18, v21, v20
	v_div_fmas_f32 v18, v18, v19, v21
	v_div_fixup_f32 v17, v18, v17, 1.0
	v_mul_f32_e32 v7, v17, v7
	v_lshlrev_b32_e32 v17, 16, v133
	v_mul_f32_e32 v17, 0xbfb8aa3b, v17
	v_exp_f32_e32 v17, v17
	v_cvt_pk_bf16_f32 v6, v6, v7
	s_nop 0
	v_add_f32_e32 v17, 1.0, v17
	v_div_scale_f32 v18, s[4:5], v17, v17, 1.0
	v_rcp_f32_e32 v19, v18
	s_nop 0
	v_fma_f32 v20, -v18, v19, 1.0
	v_fmac_f32_e32 v19, v20, v19
	v_div_scale_f32 v20, vcc, 1.0, v17, 1.0
	v_mul_f32_e32 v21, v20, v19
	v_fma_f32 v22, -v18, v21, v20
	v_fmac_f32_e32 v21, v22, v19
	v_fma_f32 v18, -v18, v21, v20
	v_div_fmas_f32 v18, v18, v19, v21
	v_div_fixup_f32 v17, v18, v17, 1.0
	v_mul_f32_e32 v8, v17, v8
	v_div_scale_f32 v17, s[4:5], v16, v16, 1.0
	v_rcp_f32_e32 v18, v17
	s_add_i32 s4, s52, s87
	s_ashr_i32 s5, s4, 31
	s_lshl_b64 s[4:5], s[4:5], 12
	v_fma_f32 v19, -v17, v18, 1.0
	v_fmac_f32_e32 v18, v19, v18
	v_div_scale_f32 v19, vcc, 1.0, v16, 1.0
	v_mul_f32_e32 v20, v19, v18
	v_fma_f32 v21, -v17, v20, v19
	v_fmac_f32_e32 v20, v21, v18
	v_fma_f32 v17, -v17, v20, v19
	v_div_fmas_f32 v17, v17, v18, v20
	v_div_fixup_f32 v16, v17, v16, 1.0
	v_mul_f32_e32 v9, v16, v9
	v_cvt_pk_bf16_f32 v7, v8, v9
	v_lshl_add_u64 v[8:9], v[10:11], 0, s[4:5]
	global_store_dwordx2 v[8:9], v[6:7], off
	ds_read_b128 v[6:9], v15 offset:2080
	s_waitcnt lgkmcnt(0)
	v_mul_f32_e32 v16, v7, v7
	v_mul_f32_e32 v17, v9, v9
	v_fmac_f32_e32 v16, v6, v6
	v_fmac_f32_e32 v17, v8, v8
	v_add_f32_e32 v16, v16, v17
	s_waitcnt lgkmcnt(0)
	s_nop 1
	v_add_f32_dpp v16, v16, v16 quad_perm:[1,0,3,2] row_mask:0xf bank_mask:0xf
	s_waitcnt lgkmcnt(0)
	s_nop 1
	v_add_f32_dpp v16, v16, v16 quad_perm:[2,3,0,1] row_mask:0xf bank_mask:0xf
	s_waitcnt lgkmcnt(0)
	s_nop 1
	v_add_f32_dpp v16, v16, v16 row_half_mirror row_mask:0xf bank_mask:0xf
	s_waitcnt lgkmcnt(0)
	s_nop 1
	v_add_f32_dpp v16, v16, v16 row_mirror row_mask:0xf bank_mask:0xf
	s_waitcnt lgkmcnt(0)
	v_mov_b32_e32 v17, v16
	s_nop 1
	v_permlane16_swap_b32_e32 v16, v17
	v_add_f32_e32 v16, v16, v17
	s_waitcnt lgkmcnt(0)
; #define LAS __attribute__((address_space(3)))
; __device__ __forceinline__ float bf2f(unsigned h) { return __uint_as_float(h << 16); }
; __device__ __forceinline__ unsigned pk2(float lo, float hi) { return pg8::cvt_pk_bf16(lo, hi); }
; __device__ __forceinline__ float sigmoidf_(float v) { return 1.0f / (1.0f + __expf(-v)); }
; __device__ __forceinline__ float wave_sum(float v) {
; #pragma unroll
;     for (int o = 1; o < 64; o <<= 1) v += __shfl_xor(v, o);
;     return v;
; }
; __device__ __forceinline__ void m3_phase(const Ctx& C, const float* mnorm_g, const float* conv_w, const float* conv_b) {
;     ...
;         for (int i = 0; i < 8; ++i) { const int t = 8 * wave + i;
;             const f32x4 v = *(const LAS f32x4*)(Hb + t * 260 + 4 * lane);
;             const float ss = wave_sum((v.x * v.x + v.y * v.y) + (v.z * v.z + v.w * v.w));
;             const float rs = 1.0f / sqrtf(ss * (1.0f / DV) + EPS);
;             const f32x4 g = gmn; const u32x2 mo = mov[i];
;             const float o0 = v.x * rs * g.x * sigmoidf_(bf2f(mo.x & 0xffffu)), o1 = v.y * rs * g.y * sigmoidf_(bf2f(mo.x >> 16));
;             const float o2 = v.z * rs * g.z * sigmoidf_(bf2f(mo.y & 0xffffu)), o3 = v.w * rs * g.w * sigmoidf_(bf2f(mo.y >> 16));
;             u32x2 w; w.x = pk2(o0, o1); w.y = pk2(o2, o3);
;             *(u32x2*)(CAT + (size_t)(row0 + t) * DM + h * DV + 4 * lane) = w; }
	v_mov_b32_e32 v17, v16
	s_nop 1
	v_permlane32_swap_b32_e32 v16, v17
	v_add_f32_e32 v16, v16, v17
	v_fmamk_f32 v16, v16, 0x3b800000, v212
	v_cmp_gt_f32_e32 vcc, s97, v16
	v_mul_f32_e32 v17, 0x4f800000, v16
	s_nop 0
	v_cndmask_b32_e32 v16, v16, v17, vcc
	v_sqrt_f32_e32 v17, v16
	s_nop 0
	v_add_u32_e32 v18, -1, v17
	v_fma_f32 v19, -v18, v17, v16
	v_cmp_ge_f32_e64 s[40:41], 0, v19
	v_add_u32_e32 v19, 1, v17
	s_nop 0
	v_cndmask_b32_e64 v18, v17, v18, s[40:41]
	v_fma_f32 v17, -v19, v17, v16
	v_cmp_lt_f32_e64 s[40:41], 0, v17
	s_nop 1
	v_cndmask_b32_e64 v17, v18, v19, s[40:41]
	v_mul_f32_e32 v18, 0x37800000, v17
	v_cndmask_b32_e32 v17, v17, v18, vcc
	v_cmp_class_f32_e32 vcc, v16, v213
	s_nop 1
	v_cndmask_b32_e32 v16, v17, v16, vcc
	v_div_scale_f32 v17, s[4:5], v16, v16, 1.0
	v_rcp_f32_e32 v18, v17
	s_nop 0
	v_fma_f32 v19, -v17, v18, 1.0
	v_fmac_f32_e32 v18, v19, v18
	v_div_scale_f32 v19, vcc, 1.0, v16, 1.0
	v_mul_f32_e32 v20, v19, v18
	v_fma_f32 v21, -v17, v20, v19
	v_fmac_f32_e32 v20, v21, v18
	v_fma_f32 v17, -v17, v20, v19
	v_div_fmas_f32 v17, v17, v18, v20
	v_div_fixup_f32 v16, v17, v16, 1.0
	v_lshlrev_b32_e32 v17, 16, v130
	v_mul_f32_e32 v17, 0xbfb8aa3b, v17
	v_exp_f32_e32 v17, v17
	v_mul_f32_e32 v6, v6, v16
	v_mul_f32_e32 v6, v2, v6
	v_mul_f32_e32 v7, v7, v16
	v_add_f32_e32 v17, 1.0, v17
	v_div_scale_f32 v18, s[4:5], v17, v17, 1.0
	v_rcp_f32_e32 v19, v18
	v_mul_f32_e32 v7, v3, v7
	v_mul_f32_e32 v8, v8, v16
	v_mul_f32_e32 v9, v9, v16
	v_fma_f32 v20, -v18, v19, 1.0
	v_fmac_f32_e32 v19, v20, v19
	v_div_scale_f32 v20, vcc, 1.0, v17, 1.0
	v_mul_f32_e32 v21, v20, v19
	v_fma_f32 v22, -v18, v21, v20
	v_fmac_f32_e32 v21, v22, v19
	v_fma_f32 v18, -v18, v21, v20
	v_div_fmas_f32 v18, v18, v19, v21
	v_div_fixup_f32 v17, v18, v17, 1.0
	v_mul_f32_e32 v6, v17, v6
	v_and_b32_e32 v17, 0xffff0000, v130
	v_mul_f32_e32 v17, 0xbfb8aa3b, v17
	v_exp_f32_e32 v17, v17
	v_and_b32_e32 v16, 0xffff0000, v131
	v_mul_f32_e32 v16, 0xbfb8aa3b, v16
	v_exp_f32_e32 v16, v16
	v_add_f32_e32 v17, 1.0, v17
	v_div_scale_f32 v18, s[4:5], v17, v17, 1.0
	v_rcp_f32_e32 v19, v18
	v_mul_f32_e32 v8, v4, v8
	v_add_f32_e32 v16, 1.0, v16
	v_mul_f32_e32 v9, v5, v9
	v_fma_f32 v20, -v18, v19, 1.0
	v_fmac_f32_e32 v19, v20, v19
	v_div_scale_f32 v20, vcc, 1.0, v17, 1.0
	v_mul_f32_e32 v21, v20, v19
	v_fma_f32 v22, -v18, v21, v20
	v_fmac_f32_e32 v21, v22, v19
	v_fma_f32 v18, -v18, v21, v20
	v_div_fmas_f32 v18, v18, v19, v21
	v_div_fixup_f32 v17, v18, v17, 1.0
	v_mul_f32_e32 v7, v17, v7
	v_lshlrev_b32_e32 v17, 16, v131
	v_mul_f32_e32 v17, 0xbfb8aa3b, v17
	v_exp_f32_e32 v17, v17
	v_cvt_pk_bf16_f32 v6, v6, v7
	s_nop 0
	v_add_f32_e32 v17, 1.0, v17
	v_div_scale_f32 v18, s[4:5], v17, v17, 1.0
	v_rcp_f32_e32 v19, v18
	s_nop 0
	v_fma_f32 v20, -v18, v19, 1.0
	v_fmac_f32_e32 v19, v20, v19
	v_div_scale_f32 v20, vcc, 1.0, v17, 1.0
	v_mul_f32_e32 v21, v20, v19
	v_fma_f32 v22, -v18, v21, v20
	v_fmac_f32_e32 v21, v22, v19
	v_fma_f32 v18, -v18, v21, v20
	v_div_fmas_f32 v18, v18, v19, v21
	v_div_fixup_f32 v17, v18, v17, 1.0
	v_mul_f32_e32 v8, v17, v8
	v_div_scale_f32 v17, s[4:5], v16, v16, 1.0
	v_rcp_f32_e32 v18, v17
	s_add_i32 s4, s52, s88
	s_ashr_i32 s5, s4, 31
	s_lshl_b64 s[4:5], s[4:5], 12
	v_fma_f32 v19, -v17, v18, 1.0
	v_fmac_f32_e32 v18, v19, v18
	v_div_scale_f32 v19, vcc, 1.0, v16, 1.0
	v_mul_f32_e32 v20, v19, v18
	v_fma_f32 v21, -v17, v20, v19
	v_fmac_f32_e32 v20, v21, v18
	v_fma_f32 v17, -v17, v20, v19
	v_div_fmas_f32 v17, v17, v18, v20
	v_div_fixup_f32 v16, v17, v16, 1.0
	v_mul_f32_e32 v9, v16, v9
	v_cvt_pk_bf16_f32 v7, v8, v9
	v_lshl_add_u64 v[8:9], v[10:11], 0, s[4:5]
	global_store_dwordx2 v[8:9], v[6:7], off
	ds_read_b128 v[6:9], v15 offset:3120
	s_waitcnt lgkmcnt(0)
	v_mul_f32_e32 v16, v7, v7
	v_mul_f32_e32 v17, v9, v9
	v_fmac_f32_e32 v16, v6, v6
	v_fmac_f32_e32 v17, v8, v8
	v_add_f32_e32 v16, v16, v17
	s_waitcnt lgkmcnt(0)
	s_nop 1
	v_add_f32_dpp v16, v16, v16 quad_perm:[1,0,3,2] row_mask:0xf bank_mask:0xf
	s_waitcnt lgkmcnt(0)
	s_nop 1
	v_add_f32_dpp v16, v16, v16 quad_perm:[2,3,0,1] row_mask:0xf bank_mask:0xf
	s_waitcnt lgkmcnt(0)
	s_nop 1
	v_add_f32_dpp v16, v16, v16 row_half_mirror row_mask:0xf bank_mask:0xf
	s_waitcnt lgkmcnt(0)
	s_nop 1
	v_add_f32_dpp v16, v16, v16 row_mirror row_mask:0xf bank_mask:0xf
	s_waitcnt lgkmcnt(0)
	v_mov_b32_e32 v17, v16
	s_nop 1
	v_permlane16_swap_b32_e32 v16, v17
	v_add_f32_e32 v16, v16, v17
	s_waitcnt lgkmcnt(0)
; #define LAS __attribute__((address_space(3)))
; __device__ __forceinline__ float bf2f(unsigned h) { return __uint_as_float(h << 16); }
; __device__ __forceinline__ unsigned pk2(float lo, float hi) { return pg8::cvt_pk_bf16(lo, hi); }
; __device__ __forceinline__ float sigmoidf_(float v) { return 1.0f / (1.0f + __expf(-v)); }
; __device__ __forceinline__ float wave_sum(float v) {
; #pragma unroll
;     for (int o = 1; o < 64; o <<= 1) v += __shfl_xor(v, o);
;     return v;
; }
; __device__ __forceinline__ void m3_phase(const Ctx& C, const float* mnorm_g, const float* conv_w, const float* conv_b) {
;     ...
;         for (int i = 0; i < 8; ++i) { const int t = 8 * wave + i;
;             const f32x4 v = *(const LAS f32x4*)(Hb + t * 260 + 4 * lane);
;             const float ss = wave_sum((v.x * v.x + v.y * v.y) + (v.z * v.z + v.w * v.w));
;             const float rs = 1.0f / sqrtf(ss * (1.0f / DV) + EPS);
;             const f32x4 g = gmn; const u32x2 mo = mov[i];
;             const float o0 = v.x * rs * g.x * sigmoidf_(bf2f(mo.x & 0xffffu)), o1 = v.y * rs * g.y * sigmoidf_(bf2f(mo.x >> 16));
;             const float o2 = v.z * rs * g.z * sigmoidf_(bf2f(mo.y & 0xffffu)), o3 = v.w * rs * g.w * sigmoidf_(bf2f(mo.y >> 16));
;             u32x2 w; w.x = pk2(o0, o1); w.y = pk2(o2, o3);
;             *(u32x2*)(CAT + (size_t)(row0 + t) * DM + h * DV + 4 * lane) = w; }
	v_mov_b32_e32 v17, v16
	s_nop 1
	v_permlane32_swap_b32_e32 v16, v17
	v_add_f32_e32 v16, v16, v17
	v_fmamk_f32 v16, v16, 0x3b800000, v212
	v_cmp_gt_f32_e32 vcc, s97, v16
	v_mul_f32_e32 v17, 0x4f800000, v16
	s_nop 0
	v_cndmask_b32_e32 v16, v16, v17, vcc
	v_sqrt_f32_e32 v17, v16
	s_nop 0
	v_add_u32_e32 v18, -1, v17
	v_fma_f32 v19, -v18, v17, v16
	v_cmp_ge_f32_e64 s[40:41], 0, v19
	v_add_u32_e32 v19, 1, v17
	s_nop 0
	v_cndmask_b32_e64 v18, v17, v18, s[40:41]
	v_fma_f32 v17, -v19, v17, v16
	v_cmp_lt_f32_e64 s[40:41], 0, v17
	s_nop 1
	v_cndmask_b32_e64 v17, v18, v19, s[40:41]
	v_mul_f32_e32 v18, 0x37800000, v17
	v_cndmask_b32_e32 v17, v17, v18, vcc
	v_cmp_class_f32_e32 vcc, v16, v213
	s_nop 1
	v_cndmask_b32_e32 v16, v17, v16, vcc
	v_div_scale_f32 v17, s[4:5], v16, v16, 1.0
	v_rcp_f32_e32 v18, v17
	s_nop 0
	v_fma_f32 v19, -v17, v18, 1.0
	v_fmac_f32_e32 v18, v19, v18
	v_div_scale_f32 v19, vcc, 1.0, v16, 1.0
	v_mul_f32_e32 v20, v19, v18
	v_fma_f32 v21, -v17, v20, v19
	v_fmac_f32_e32 v20, v21, v18
	v_fma_f32 v17, -v17, v20, v19
	v_div_fmas_f32 v17, v17, v18, v20
	v_div_fixup_f32 v16, v17, v16, 1.0
	v_lshlrev_b32_e32 v17, 16, v128
	v_mul_f32_e32 v17, 0xbfb8aa3b, v17
	v_exp_f32_e32 v17, v17
	v_mul_f32_e32 v6, v6, v16
	v_mul_f32_e32 v6, v2, v6
	v_mul_f32_e32 v7, v7, v16
	v_add_f32_e32 v17, 1.0, v17
	v_div_scale_f32 v18, s[4:5], v17, v17, 1.0
	v_rcp_f32_e32 v19, v18
	v_mul_f32_e32 v7, v3, v7
	v_mul_f32_e32 v8, v8, v16
	v_mul_f32_e32 v9, v9, v16
	v_fma_f32 v20, -v18, v19, 1.0
	v_fmac_f32_e32 v19, v20, v19
	v_div_scale_f32 v20, vcc, 1.0, v17, 1.0
	v_mul_f32_e32 v21, v20, v19
	v_fma_f32 v22, -v18, v21, v20
	v_fmac_f32_e32 v21, v22, v19
	v_fma_f32 v18, -v18, v21, v20
	v_div_fmas_f32 v18, v18, v19, v21
	v_div_fixup_f32 v17, v18, v17, 1.0
	v_mul_f32_e32 v6, v17, v6
	v_and_b32_e32 v17, 0xffff0000, v128
	v_mul_f32_e32 v17, 0xbfb8aa3b, v17
	v_exp_f32_e32 v17, v17
	v_and_b32_e32 v16, 0xffff0000, v129
	v_mul_f32_e32 v16, 0xbfb8aa3b, v16
	v_exp_f32_e32 v16, v16
	v_add_f32_e32 v17, 1.0, v17
	v_div_scale_f32 v18, s[4:5], v17, v17, 1.0
	v_rcp_f32_e32 v19, v18
	v_mul_f32_e32 v8, v4, v8
	v_add_f32_e32 v16, 1.0, v16
	v_mul_f32_e32 v9, v5, v9
	v_fma_f32 v20, -v18, v19, 1.0
	v_fmac_f32_e32 v19, v20, v19
	v_div_scale_f32 v20, vcc, 1.0, v17, 1.0
	v_mul_f32_e32 v21, v20, v19
	v_fma_f32 v22, -v18, v21, v20
	v_fmac_f32_e32 v21, v22, v19
	v_fma_f32 v18, -v18, v21, v20
	v_div_fmas_f32 v18, v18, v19, v21
	v_div_fixup_f32 v17, v18, v17, 1.0
	v_mul_f32_e32 v7, v17, v7
	v_lshlrev_b32_e32 v17, 16, v129
	v_mul_f32_e32 v17, 0xbfb8aa3b, v17
	v_exp_f32_e32 v17, v17
	v_cvt_pk_bf16_f32 v6, v6, v7
	s_nop 0
	v_add_f32_e32 v17, 1.0, v17
	v_div_scale_f32 v18, s[4:5], v17, v17, 1.0
	v_rcp_f32_e32 v19, v18
	s_nop 0
	v_fma_f32 v20, -v18, v19, 1.0
	v_fmac_f32_e32 v19, v20, v19
	v_div_scale_f32 v20, vcc, 1.0, v17, 1.0
	v_mul_f32_e32 v21, v20, v19
	v_fma_f32 v22, -v18, v21, v20
	v_fmac_f32_e32 v21, v22, v19
	v_fma_f32 v18, -v18, v21, v20
	v_div_fmas_f32 v18, v18, v19, v21
	v_div_fixup_f32 v17, v18, v17, 1.0
	v_mul_f32_e32 v8, v17, v8
	v_div_scale_f32 v17, s[4:5], v16, v16, 1.0
	v_rcp_f32_e32 v18, v17
	s_add_i32 s4, s52, s89
	s_ashr_i32 s5, s4, 31
	s_lshl_b64 s[4:5], s[4:5], 12
	v_fma_f32 v19, -v17, v18, 1.0
	v_fmac_f32_e32 v18, v19, v18
	v_div_scale_f32 v19, vcc, 1.0, v16, 1.0
	v_mul_f32_e32 v20, v19, v18
	v_fma_f32 v21, -v17, v20, v19
	v_fmac_f32_e32 v20, v21, v18
	v_fma_f32 v17, -v17, v20, v19
	v_div_fmas_f32 v17, v17, v18, v20
	v_div_fixup_f32 v16, v17, v16, 1.0
	v_mul_f32_e32 v9, v16, v9
	v_cvt_pk_bf16_f32 v7, v8, v9
	v_lshl_add_u64 v[8:9], v[10:11], 0, s[4:5]
	global_store_dwordx2 v[8:9], v[6:7], off
	ds_read_b128 v[6:9], v15 offset:4160
	s_waitcnt lgkmcnt(0)
	v_mul_f32_e32 v16, v7, v7
	v_mul_f32_e32 v17, v9, v9
	v_fmac_f32_e32 v16, v6, v6
	v_fmac_f32_e32 v17, v8, v8
	v_add_f32_e32 v16, v16, v17
	s_waitcnt lgkmcnt(0)
	s_nop 1
	v_add_f32_dpp v16, v16, v16 quad_perm:[1,0,3,2] row_mask:0xf bank_mask:0xf
	s_waitcnt lgkmcnt(0)
	s_nop 1
	v_add_f32_dpp v16, v16, v16 quad_perm:[2,3,0,1] row_mask:0xf bank_mask:0xf
	s_waitcnt lgkmcnt(0)
	s_nop 1
	v_add_f32_dpp v16, v16, v16 row_half_mirror row_mask:0xf bank_mask:0xf
	s_waitcnt lgkmcnt(0)
	s_nop 1
	v_add_f32_dpp v16, v16, v16 row_mirror row_mask:0xf bank_mask:0xf
	s_waitcnt lgkmcnt(0)
	v_mov_b32_e32 v17, v16
	s_nop 1
	v_permlane16_swap_b32_e32 v16, v17
	v_add_f32_e32 v16, v16, v17
	s_waitcnt lgkmcnt(0)
; #define LAS __attribute__((address_space(3)))
; __device__ __forceinline__ float bf2f(unsigned h) { return __uint_as_float(h << 16); }
; __device__ __forceinline__ unsigned pk2(float lo, float hi) { return pg8::cvt_pk_bf16(lo, hi); }
; __device__ __forceinline__ float sigmoidf_(float v) { return 1.0f / (1.0f + __expf(-v)); }
; __device__ __forceinline__ float wave_sum(float v) {
; #pragma unroll
;     for (int o = 1; o < 64; o <<= 1) v += __shfl_xor(v, o);
;     return v;
; }
; __device__ __forceinline__ void m3_phase(const Ctx& C, const float* mnorm_g, const float* conv_w, const float* conv_b) {
;     ...
;         for (int i = 0; i < 8; ++i) { const int t = 8 * wave + i;
;             const f32x4 v = *(const LAS f32x4*)(Hb + t * 260 + 4 * lane);
;             const float ss = wave_sum((v.x * v.x + v.y * v.y) + (v.z * v.z + v.w * v.w));
;             const float rs = 1.0f / sqrtf(ss * (1.0f / DV) + EPS);
;             const f32x4 g = gmn; const u32x2 mo = mov[i];
;             const float o0 = v.x * rs * g.x * sigmoidf_(bf2f(mo.x & 0xffffu)), o1 = v.y * rs * g.y * sigmoidf_(bf2f(mo.x >> 16));
;             const float o2 = v.z * rs * g.z * sigmoidf_(bf2f(mo.y & 0xffffu)), o3 = v.w * rs * g.w * sigmoidf_(bf2f(mo.y >> 16));
;             u32x2 w; w.x = pk2(o0, o1); w.y = pk2(o2, o3);
;             *(u32x2*)(CAT + (size_t)(row0 + t) * DM + h * DV + 4 * lane) = w; }
	v_mov_b32_e32 v17, v16
	s_nop 1
	v_permlane32_swap_b32_e32 v16, v17
	v_add_f32_e32 v16, v16, v17
	v_fmamk_f32 v16, v16, 0x3b800000, v212
	v_cmp_gt_f32_e32 vcc, s97, v16
	v_mul_f32_e32 v17, 0x4f800000, v16
	s_nop 0
	v_cndmask_b32_e32 v16, v16, v17, vcc
	v_sqrt_f32_e32 v17, v16
	s_nop 0
	v_add_u32_e32 v18, -1, v17
	v_fma_f32 v19, -v18, v17, v16
	v_cmp_ge_f32_e64 s[40:41], 0, v19
	v_add_u32_e32 v19, 1, v17
	s_nop 0
	v_cndmask_b32_e64 v18, v17, v18, s[40:41]
	v_fma_f32 v17, -v19, v17, v16
	v_cmp_lt_f32_e64 s[40:41], 0, v17
	s_nop 1
	v_cndmask_b32_e64 v17, v18, v19, s[40:41]
	v_mul_f32_e32 v18, 0x37800000, v17
	v_cndmask_b32_e32 v17, v17, v18, vcc
	v_cmp_class_f32_e32 vcc, v16, v213
	s_nop 1
	v_cndmask_b32_e32 v16, v17, v16, vcc
	v_div_scale_f32 v17, s[4:5], v16, v16, 1.0
	v_rcp_f32_e32 v18, v17
	s_nop 0
	v_fma_f32 v19, -v17, v18, 1.0
	v_fmac_f32_e32 v18, v19, v18
	v_div_scale_f32 v19, vcc, 1.0, v16, 1.0
	v_mul_f32_e32 v20, v19, v18
	v_fma_f32 v21, -v17, v20, v19
	v_fmac_f32_e32 v20, v21, v18
	v_fma_f32 v17, -v17, v20, v19
	v_div_fmas_f32 v17, v17, v18, v20
	v_div_fixup_f32 v16, v17, v16, 1.0
	v_lshlrev_b32_e32 v17, 16, v126
	v_mul_f32_e32 v17, 0xbfb8aa3b, v17
	v_exp_f32_e32 v17, v17
	v_mul_f32_e32 v6, v6, v16
	v_mul_f32_e32 v6, v2, v6
	v_mul_f32_e32 v7, v7, v16
	v_add_f32_e32 v17, 1.0, v17
	v_div_scale_f32 v18, s[4:5], v17, v17, 1.0
	v_rcp_f32_e32 v19, v18
	v_mul_f32_e32 v7, v3, v7
	v_mul_f32_e32 v8, v8, v16
	v_mul_f32_e32 v9, v9, v16
	v_fma_f32 v20, -v18, v19, 1.0
	v_fmac_f32_e32 v19, v20, v19
	v_div_scale_f32 v20, vcc, 1.0, v17, 1.0
	v_mul_f32_e32 v21, v20, v19
	v_fma_f32 v22, -v18, v21, v20
	v_fmac_f32_e32 v21, v22, v19
	v_fma_f32 v18, -v18, v21, v20
	v_div_fmas_f32 v18, v18, v19, v21
	v_div_fixup_f32 v17, v18, v17, 1.0
	v_mul_f32_e32 v6, v17, v6
	v_and_b32_e32 v17, 0xffff0000, v126
	v_mul_f32_e32 v17, 0xbfb8aa3b, v17
	v_exp_f32_e32 v17, v17
	v_and_b32_e32 v16, 0xffff0000, v127
	v_mul_f32_e32 v16, 0xbfb8aa3b, v16
	v_exp_f32_e32 v16, v16
	v_add_f32_e32 v17, 1.0, v17
	v_div_scale_f32 v18, s[4:5], v17, v17, 1.0
	v_rcp_f32_e32 v19, v18
	v_mul_f32_e32 v8, v4, v8
	v_add_f32_e32 v16, 1.0, v16
	v_mul_f32_e32 v9, v5, v9
	v_fma_f32 v20, -v18, v19, 1.0
	v_fmac_f32_e32 v19, v20, v19
	v_div_scale_f32 v20, vcc, 1.0, v17, 1.0
	v_mul_f32_e32 v21, v20, v19
	v_fma_f32 v22, -v18, v21, v20
	v_fmac_f32_e32 v21, v22, v19
	v_fma_f32 v18, -v18, v21, v20
	v_div_fmas_f32 v18, v18, v19, v21
	v_div_fixup_f32 v17, v18, v17, 1.0
	v_mul_f32_e32 v7, v17, v7
	v_lshlrev_b32_e32 v17, 16, v127
	v_mul_f32_e32 v17, 0xbfb8aa3b, v17
	v_exp_f32_e32 v17, v17
	v_cvt_pk_bf16_f32 v6, v6, v7
	s_nop 0
	v_add_f32_e32 v17, 1.0, v17
	v_div_scale_f32 v18, s[4:5], v17, v17, 1.0
	v_rcp_f32_e32 v19, v18
	s_nop 0
	v_fma_f32 v20, -v18, v19, 1.0
	v_fmac_f32_e32 v19, v20, v19
	v_div_scale_f32 v20, vcc, 1.0, v17, 1.0
	v_mul_f32_e32 v21, v20, v19
	v_fma_f32 v22, -v18, v21, v20
	v_fmac_f32_e32 v21, v22, v19
	v_fma_f32 v18, -v18, v21, v20
	v_div_fmas_f32 v18, v18, v19, v21
	v_div_fixup_f32 v17, v18, v17, 1.0
	v_mul_f32_e32 v8, v17, v8
	v_div_scale_f32 v17, s[4:5], v16, v16, 1.0
	v_rcp_f32_e32 v18, v17
	s_add_i32 s4, s52, s90
	s_ashr_i32 s5, s4, 31
	s_lshl_b64 s[4:5], s[4:5], 12
	v_fma_f32 v19, -v17, v18, 1.0
	v_fmac_f32_e32 v18, v19, v18
	v_div_scale_f32 v19, vcc, 1.0, v16, 1.0
	v_mul_f32_e32 v20, v19, v18
	v_fma_f32 v21, -v17, v20, v19
	v_fmac_f32_e32 v20, v21, v18
	v_fma_f32 v17, -v17, v20, v19
	v_div_fmas_f32 v17, v17, v18, v20
	v_div_fixup_f32 v16, v17, v16, 1.0
	v_mul_f32_e32 v9, v16, v9
	v_cvt_pk_bf16_f32 v7, v8, v9
	v_lshl_add_u64 v[8:9], v[10:11], 0, s[4:5]
	global_store_dwordx2 v[8:9], v[6:7], off
	ds_read_b128 v[6:9], v15 offset:5200
	s_waitcnt lgkmcnt(0)
	v_mul_f32_e32 v16, v7, v7
	v_mul_f32_e32 v17, v9, v9
	v_fmac_f32_e32 v16, v6, v6
	v_fmac_f32_e32 v17, v8, v8
	v_add_f32_e32 v16, v16, v17
	s_waitcnt lgkmcnt(0)
	s_nop 1
	v_add_f32_dpp v16, v16, v16 quad_perm:[1,0,3,2] row_mask:0xf bank_mask:0xf
	s_waitcnt lgkmcnt(0)
	s_nop 1
	v_add_f32_dpp v16, v16, v16 quad_perm:[2,3,0,1] row_mask:0xf bank_mask:0xf
	s_waitcnt lgkmcnt(0)
	s_nop 1
	v_add_f32_dpp v16, v16, v16 row_half_mirror row_mask:0xf bank_mask:0xf
	s_waitcnt lgkmcnt(0)
	s_nop 1
	v_add_f32_dpp v16, v16, v16 row_mirror row_mask:0xf bank_mask:0xf
	s_waitcnt lgkmcnt(0)
	v_mov_b32_e32 v17, v16
	s_nop 1
	v_permlane16_swap_b32_e32 v16, v17
	v_add_f32_e32 v16, v16, v17
	s_waitcnt lgkmcnt(0)
; #define LAS __attribute__((address_space(3)))
; __device__ __forceinline__ float bf2f(unsigned h) { return __uint_as_float(h << 16); }
; __device__ __forceinline__ unsigned pk2(float lo, float hi) { return pg8::cvt_pk_bf16(lo, hi); }
; __device__ __forceinline__ float sigmoidf_(float v) { return 1.0f / (1.0f + __expf(-v)); }
; __device__ __forceinline__ float wave_sum(float v) {
; #pragma unroll
;     for (int o = 1; o < 64; o <<= 1) v += __shfl_xor(v, o);
;     return v;
; }
; __device__ __forceinline__ void m3_phase(const Ctx& C, const float* mnorm_g, const float* conv_w, const float* conv_b) {
;     ...
;         for (int i = 0; i < 8; ++i) { const int t = 8 * wave + i;
;             const f32x4 v = *(const LAS f32x4*)(Hb + t * 260 + 4 * lane);
;             const float ss = wave_sum((v.x * v.x + v.y * v.y) + (v.z * v.z + v.w * v.w));
;             const float rs = 1.0f / sqrtf(ss * (1.0f / DV) + EPS);
;             const f32x4 g = gmn; const u32x2 mo = mov[i];
;             const float o0 = v.x * rs * g.x * sigmoidf_(bf2f(mo.x & 0xffffu)), o1 = v.y * rs * g.y * sigmoidf_(bf2f(mo.x >> 16));
;             const float o2 = v.z * rs * g.z * sigmoidf_(bf2f(mo.y & 0xffffu)), o3 = v.w * rs * g.w * sigmoidf_(bf2f(mo.y >> 16));
;             u32x2 w; w.x = pk2(o0, o1); w.y = pk2(o2, o3);
;             *(u32x2*)(CAT + (size_t)(row0 + t) * DM + h * DV + 4 * lane) = w; }
	v_mov_b32_e32 v17, v16
	s_nop 1
	v_permlane32_swap_b32_e32 v16, v17
	v_add_f32_e32 v16, v16, v17
	v_fmamk_f32 v16, v16, 0x3b800000, v212
	v_cmp_gt_f32_e32 vcc, s97, v16
	v_mul_f32_e32 v17, 0x4f800000, v16
	s_nop 0
	v_cndmask_b32_e32 v16, v16, v17, vcc
	v_sqrt_f32_e32 v17, v16
	s_nop 0
	v_add_u32_e32 v18, -1, v17
	v_fma_f32 v19, -v18, v17, v16
	v_cmp_ge_f32_e64 s[40:41], 0, v19
	v_add_u32_e32 v19, 1, v17
	s_nop 0
	v_cndmask_b32_e64 v18, v17, v18, s[40:41]
	v_fma_f32 v17, -v19, v17, v16
	v_cmp_lt_f32_e64 s[40:41], 0, v17
	s_nop 1
	v_cndmask_b32_e64 v17, v18, v19, s[40:41]
	v_mul_f32_e32 v18, 0x37800000, v17
	v_cndmask_b32_e32 v17, v17, v18, vcc
	v_cmp_class_f32_e32 vcc, v16, v213
	s_nop 1
	v_cndmask_b32_e32 v16, v17, v16, vcc
	v_div_scale_f32 v17, s[4:5], v16, v16, 1.0
	v_rcp_f32_e32 v18, v17
	s_nop 0
	v_fma_f32 v19, -v17, v18, 1.0
	v_fmac_f32_e32 v18, v19, v18
	v_div_scale_f32 v19, vcc, 1.0, v16, 1.0
	v_mul_f32_e32 v20, v19, v18
	v_fma_f32 v21, -v17, v20, v19
	v_fmac_f32_e32 v20, v21, v18
	v_fma_f32 v17, -v17, v20, v19
	v_div_fmas_f32 v17, v17, v18, v20
	v_div_fixup_f32 v16, v17, v16, 1.0
	v_lshlrev_b32_e32 v17, 16, v124
	v_mul_f32_e32 v17, 0xbfb8aa3b, v17
	v_exp_f32_e32 v17, v17
	v_mul_f32_e32 v6, v6, v16
	v_mul_f32_e32 v6, v2, v6
	v_mul_f32_e32 v7, v7, v16
	v_add_f32_e32 v17, 1.0, v17
	v_div_scale_f32 v18, s[4:5], v17, v17, 1.0
	v_rcp_f32_e32 v19, v18
	v_mul_f32_e32 v7, v3, v7
	v_mul_f32_e32 v8, v8, v16
	v_mul_f32_e32 v9, v9, v16
	v_fma_f32 v20, -v18, v19, 1.0
	v_fmac_f32_e32 v19, v20, v19
	v_div_scale_f32 v20, vcc, 1.0, v17, 1.0
	v_mul_f32_e32 v21, v20, v19
	v_fma_f32 v22, -v18, v21, v20
	v_fmac_f32_e32 v21, v22, v19
	v_fma_f32 v18, -v18, v21, v20
	v_div_fmas_f32 v18, v18, v19, v21
	v_div_fixup_f32 v17, v18, v17, 1.0
	v_mul_f32_e32 v6, v17, v6
	v_and_b32_e32 v17, 0xffff0000, v124
	v_mul_f32_e32 v17, 0xbfb8aa3b, v17
	v_exp_f32_e32 v17, v17
	v_and_b32_e32 v16, 0xffff0000, v125
	v_mul_f32_e32 v16, 0xbfb8aa3b, v16
	v_exp_f32_e32 v16, v16
	v_add_f32_e32 v17, 1.0, v17
	v_div_scale_f32 v18, s[4:5], v17, v17, 1.0
	v_rcp_f32_e32 v19, v18
	v_mul_f32_e32 v8, v4, v8
	v_add_f32_e32 v16, 1.0, v16
	v_mul_f32_e32 v9, v5, v9
	v_fma_f32 v20, -v18, v19, 1.0
	v_fmac_f32_e32 v19, v20, v19
	v_div_scale_f32 v20, vcc, 1.0, v17, 1.0
	v_mul_f32_e32 v21, v20, v19
	v_fma_f32 v22, -v18, v21, v20
	v_fmac_f32_e32 v21, v22, v19
	v_fma_f32 v18, -v18, v21, v20
	v_div_fmas_f32 v18, v18, v19, v21
	v_div_fixup_f32 v17, v18, v17, 1.0
	v_mul_f32_e32 v7, v17, v7
	v_lshlrev_b32_e32 v17, 16, v125
	v_mul_f32_e32 v17, 0xbfb8aa3b, v17
	v_exp_f32_e32 v17, v17
	v_cvt_pk_bf16_f32 v6, v6, v7
	s_nop 0
	v_add_f32_e32 v17, 1.0, v17
	v_div_scale_f32 v18, s[4:5], v17, v17, 1.0
	v_rcp_f32_e32 v19, v18
	s_nop 0
	v_fma_f32 v20, -v18, v19, 1.0
	v_fmac_f32_e32 v19, v20, v19
	v_div_scale_f32 v20, vcc, 1.0, v17, 1.0
	v_mul_f32_e32 v21, v20, v19
	v_fma_f32 v22, -v18, v21, v20
	v_fmac_f32_e32 v21, v22, v19
	v_fma_f32 v18, -v18, v21, v20
	v_div_fmas_f32 v18, v18, v19, v21
	v_div_fixup_f32 v17, v18, v17, 1.0
	v_mul_f32_e32 v8, v17, v8
	v_div_scale_f32 v17, s[4:5], v16, v16, 1.0
	v_rcp_f32_e32 v18, v17
	s_add_i32 s4, s52, s91
	s_ashr_i32 s5, s4, 31
	s_lshl_b64 s[4:5], s[4:5], 12
	v_fma_f32 v19, -v17, v18, 1.0
	v_fmac_f32_e32 v18, v19, v18
	v_div_scale_f32 v19, vcc, 1.0, v16, 1.0
	v_mul_f32_e32 v20, v19, v18
	v_fma_f32 v21, -v17, v20, v19
	v_fmac_f32_e32 v20, v21, v18
	v_fma_f32 v17, -v17, v20, v19
	v_div_fmas_f32 v17, v17, v18, v20
	v_div_fixup_f32 v16, v17, v16, 1.0
	v_mul_f32_e32 v9, v16, v9
	v_cvt_pk_bf16_f32 v7, v8, v9
	v_lshl_add_u64 v[8:9], v[10:11], 0, s[4:5]
	global_store_dwordx2 v[8:9], v[6:7], off
	ds_read_b128 v[6:9], v15 offset:6240
	s_waitcnt lgkmcnt(0)
	v_mul_f32_e32 v15, v7, v7
	v_mul_f32_e32 v16, v9, v9
	v_fmac_f32_e32 v15, v6, v6
	v_fmac_f32_e32 v16, v8, v8
	v_add_f32_e32 v15, v15, v16
	s_waitcnt lgkmcnt(0)
	s_nop 1
	v_add_f32_dpp v15, v15, v15 quad_perm:[1,0,3,2] row_mask:0xf bank_mask:0xf
	s_waitcnt lgkmcnt(0)
; #define LAS __attribute__((address_space(3)))
; __device__ __forceinline__ float bf2f(unsigned h) { return __uint_as_float(h << 16); }
; __device__ __forceinline__ unsigned pk2(float lo, float hi) { return pg8::cvt_pk_bf16(lo, hi); }
; __device__ __forceinline__ float sigmoidf_(float v) { return 1.0f / (1.0f + __expf(-v)); }
; __device__ __forceinline__ void m3_phase(const Ctx& C, const float* mnorm_g, const float* conv_w, const float* conv_b) {
;     ...
;         for (int i = 0; i < 8; ++i) { const int t = 8 * wave + i;
;             const f32x4 v = *(const LAS f32x4*)(Hb + t * 260 + 4 * lane);
;             const float ss = wave_sum((v.x * v.x + v.y * v.y) + (v.z * v.z + v.w * v.w));
;             const float rs = 1.0f / sqrtf(ss * (1.0f / DV) + EPS);
;             const f32x4 g = gmn; const u32x2 mo = mov[i];
;             const float o0 = v.x * rs * g.x * sigmoidf_(bf2f(mo.x & 0xffffu)), o1 = v.y * rs * g.y * sigmoidf_(bf2f(mo.x >> 16));
;             const float o2 = v.z * rs * g.z * sigmoidf_(bf2f(mo.y & 0xffffu)), o3 = v.w * rs * g.w * sigmoidf_(bf2f(mo.y >> 16));
;             u32x2 w; w.x = pk2(o0, o1); w.y = pk2(o2, o3);
;             *(u32x2*)(CAT + (size_t)(row0 + t) * DM + h * DV + 4 * lane) = w; }
;         __syncthreads();
	s_nop 1
	v_add_f32_dpp v15, v15, v15 quad_perm:[2,3,0,1] row_mask:0xf bank_mask:0xf
	s_waitcnt lgkmcnt(0)
	s_nop 1
	v_add_f32_dpp v15, v15, v15 row_half_mirror row_mask:0xf bank_mask:0xf
	ds_bpermute_b32 v12, v12, v15
	s_waitcnt lgkmcnt(0)
	v_add_f32_e32 v12, v15, v12
	s_waitcnt lgkmcnt(0)
	v_mov_b32_e32 v13, v12
	s_nop 1
	v_permlane16_swap_b32_e32 v12, v13
	v_add_f32_e32 v12, v12, v13
	s_waitcnt lgkmcnt(0)
	v_mov_b32_e32 v13, v12
	s_nop 1
	v_permlane32_swap_b32_e32 v12, v13
	v_add_f32_e32 v12, v12, v13
	v_fmamk_f32 v12, v12, 0x3b800000, v212
	v_cmp_gt_f32_e32 vcc, s97, v12
	v_mul_f32_e32 v13, 0x4f800000, v12
	s_nop 0
	v_cndmask_b32_e32 v12, v12, v13, vcc
	v_sqrt_f32_e32 v13, v12
	s_nop 0
	v_add_u32_e32 v14, -1, v13
	v_fma_f32 v15, -v14, v13, v12
	v_cmp_ge_f32_e64 s[40:41], 0, v15
	v_add_u32_e32 v15, 1, v13
	s_nop 0
	v_cndmask_b32_e64 v14, v13, v14, s[40:41]
	v_fma_f32 v13, -v15, v13, v12
	v_cmp_lt_f32_e64 s[40:41], 0, v13
	s_nop 1
	v_cndmask_b32_e64 v13, v14, v15, s[40:41]
	v_mul_f32_e32 v14, 0x37800000, v13
	v_cndmask_b32_e32 v13, v13, v14, vcc
	v_cmp_class_f32_e32 vcc, v12, v213
	s_nop 1
	v_cndmask_b32_e32 v12, v13, v12, vcc
	v_div_scale_f32 v13, s[4:5], v12, v12, 1.0
	v_rcp_f32_e32 v14, v13
	s_nop 0
	v_fma_f32 v15, -v13, v14, 1.0
	v_fmac_f32_e32 v14, v15, v14
	v_div_scale_f32 v15, vcc, 1.0, v12, 1.0
	v_mul_f32_e32 v16, v15, v14
	v_fma_f32 v17, -v13, v16, v15
	v_fmac_f32_e32 v16, v17, v14
	v_fma_f32 v13, -v13, v16, v15
	v_div_fmas_f32 v13, v13, v14, v16
	v_div_fixup_f32 v12, v13, v12, 1.0
	v_mul_f32_e32 v6, v6, v12
	v_mul_f32_e32 v2, v2, v6
	v_lshlrev_b32_e32 v6, 16, v122
	v_mul_f32_e32 v6, 0xbfb8aa3b, v6
	v_exp_f32_e32 v6, v6
	s_nop 0
	v_add_f32_e32 v6, 1.0, v6
	v_div_scale_f32 v13, s[4:5], v6, v6, 1.0
	v_rcp_f32_e32 v14, v13
	s_nop 0
	v_fma_f32 v15, -v13, v14, 1.0
	v_fmac_f32_e32 v14, v15, v14
	v_div_scale_f32 v15, vcc, 1.0, v6, 1.0
	v_mul_f32_e32 v16, v15, v14
	v_fma_f32 v17, -v13, v16, v15
	v_fmac_f32_e32 v16, v17, v14
	v_fma_f32 v13, -v13, v16, v15
	v_div_fmas_f32 v13, v13, v14, v16
	v_div_fixup_f32 v6, v13, v6, 1.0
	v_mul_f32_e32 v2, v6, v2
	v_mul_f32_e32 v6, v7, v12
	v_mul_f32_e32 v3, v3, v6
	v_and_b32_e32 v6, 0xffff0000, v122
	v_mul_f32_e32 v6, 0xbfb8aa3b, v6
	v_exp_f32_e32 v6, v6
	s_nop 0
	v_add_f32_e32 v6, 1.0, v6
	v_div_scale_f32 v7, s[4:5], v6, v6, 1.0
	v_rcp_f32_e32 v13, v7
	s_nop 0
	v_fma_f32 v14, -v7, v13, 1.0
	v_fmac_f32_e32 v13, v14, v13
	v_div_scale_f32 v14, vcc, 1.0, v6, 1.0
	v_mul_f32_e32 v15, v14, v13
	v_fma_f32 v16, -v7, v15, v14
	v_fmac_f32_e32 v15, v16, v13
	v_fma_f32 v7, -v7, v15, v14
	v_div_fmas_f32 v7, v7, v13, v15
	v_div_fixup_f32 v6, v7, v6, 1.0
	v_mul_f32_e32 v3, v6, v3
	v_mul_f32_e32 v6, v8, v12
	v_mul_f32_e32 v4, v4, v6
	v_lshlrev_b32_e32 v6, 16, v123
	v_mul_f32_e32 v6, 0xbfb8aa3b, v6
	v_exp_f32_e32 v6, v6
	v_cvt_pk_bf16_f32 v2, v2, v3
	s_nop 0
	v_add_f32_e32 v6, 1.0, v6
	v_div_scale_f32 v7, s[4:5], v6, v6, 1.0
	v_rcp_f32_e32 v8, v7
	s_nop 0
	v_fma_f32 v13, -v7, v8, 1.0
	v_fmac_f32_e32 v8, v13, v8
	v_div_scale_f32 v13, vcc, 1.0, v6, 1.0
	v_mul_f32_e32 v14, v13, v8
	v_fma_f32 v15, -v7, v14, v13
	v_fmac_f32_e32 v14, v15, v8
	v_fma_f32 v7, -v7, v14, v13
	v_div_fmas_f32 v7, v7, v8, v14
	v_div_fixup_f32 v6, v7, v6, 1.0
	v_mul_f32_e32 v4, v6, v4
	v_mul_f32_e32 v6, v9, v12
	v_mul_f32_e32 v5, v5, v6
	v_and_b32_e32 v6, 0xffff0000, v123
	v_mul_f32_e32 v6, 0xbfb8aa3b, v6
	v_exp_f32_e32 v6, v6
	s_nop 0
	v_add_f32_e32 v6, 1.0, v6
	v_div_scale_f32 v7, s[4:5], v6, v6, 1.0
	v_rcp_f32_e32 v8, v7
	s_add_i32 s4, s52, s92
	s_ashr_i32 s5, s4, 31
	s_lshl_b64 s[4:5], s[4:5], 12
	v_fma_f32 v9, -v7, v8, 1.0
	v_fmac_f32_e32 v8, v9, v8
	v_div_scale_f32 v9, vcc, 1.0, v6, 1.0
	v_mul_f32_e32 v12, v9, v8
	v_fma_f32 v13, -v7, v12, v9
	v_fmac_f32_e32 v12, v13, v8
	v_fma_f32 v7, -v7, v12, v9
	v_div_fmas_f32 v7, v7, v8, v12
	v_div_fixup_f32 v6, v7, v6, 1.0
	v_mul_f32_e32 v5, v6, v5
	v_cvt_pk_bf16_f32 v3, v4, v5
	v_lshl_add_u64 v[4:5], v[10:11], 0, s[4:5]
	s_cmpk_lt_i32 s80, 0x400
	global_store_dwordx2 v[4:5], v[2:3], off
	s_barrier
	s_cbranch_scc0 .LBB0_683

; __device__ __forceinline__ unsigned pk2(float lo, float hi) { return pg8::cvt_pk_bf16(lo, hi); }
; __device__ __forceinline__ void m3_phase(const Ctx& C, const float* mnorm_g, const float* conv_w, const float* conv_b) {
;     ...
;                 const float bs = bv[s], is = igv[s];
; #pragma unroll
;                 for (int j = 0; j < 4; ++j) { const int t = tr * 16 + 4 * fq + j; float p = (s <= t) ? acc[j] * __expf(bv[t] - bs + is) : 0.f;
;                     P[t * VTS + s] = (bf16)(pk2(p, 0.f) & 0xffffu);
;                     p += __shfl_xor(p, 1); p += __shfl_xor(p, 2); p += __shfl_xor(p, 4); p += __shfl_xor(p, 8);
;                     if (fr == 0) unsafeAtomicAdd((float*)&den[t], p); }
.LBB0_666:
	s_or_b64 exec, exec, s[78:79]
	v_cvt_pk_bf16_f32 v38, v42, v107
	v_and_b32_e32 v43, 64, v215
	s_nop 3
	ds_write_b16 v190, v38
	v_xor_b32_e32 v38, 1, v215
	v_add_u32_e32 v77, 64, v43
	v_cmp_lt_i32_e32 vcc, v38, v77
	s_nop 1
	v_cndmask_b32_e32 v43, v215, v38, vcc
	v_lshlrev_b32_e32 v46, 2, v43
	ds_bpermute_b32 v43, v46, v42
	s_waitcnt lgkmcnt(0)
	v_add_f32_e32 v43, v42, v43
	v_xor_b32_e32 v42, 2, v215
	v_cmp_lt_i32_e32 vcc, v42, v77
	s_nop 1
	v_cndmask_b32_e32 v47, v215, v42, vcc
	v_lshlrev_b32_e32 v47, 2, v47
	s_waitcnt lgkmcnt(0)
	s_nop 1
	v_add_f32_dpp v49, v43, v43 quad_perm:[2,3,0,1] row_mask:0xf bank_mask:0xf
	v_xor_b32_e32 v43, 4, v215
	v_cmp_lt_i32_e32 vcc, v43, v77
	s_nop 1
	v_cndmask_b32_e32 v48, v215, v43, vcc
	v_lshlrev_b32_e32 v48, 2, v48
	ds_bpermute_b32 v50, v48, v49
	s_waitcnt lgkmcnt(0)
	v_add_f32_e32 v50, v49, v50
	v_xor_b32_e32 v49, 8, v215
	v_cmp_lt_i32_e32 vcc, v49, v77
	s_nop 1
	v_cndmask_b32_e32 v49, v215, v49, vcc
	v_lshlrev_b32_e32 v49, 2, v49
	ds_bpermute_b32 v51, v49, v50
	s_and_saveexec_b64 s[78:79], s[18:19]
	s_cbranch_execz .LBB0_668
	s_waitcnt lgkmcnt(0)
	v_add_f32_e32 v50, v50, v51
	ds_add_f32 v180, v50

; __device__ __forceinline__ float bf2f(unsigned h) { return __uint_as_float(h << 16); }
; __device__ __forceinline__ unsigned pk2(float lo, float hi) { return pg8::cvt_pk_bf16(lo, hi); }
; __device__ __forceinline__ void attn_combine(const Ctx& C, const Args& A) {
;     ...
;         for (int rr = 0; rr < 2; ++rr) { const int t = t0 + rr * NGW; if (t < M) {
;             float d[16]; float ss = 0.f;
; #pragma unroll
;             for (int q = 0; q < 2; ++q)
; #pragma unroll
;                 for (int k = 0; k < 4; ++k) { const unsigned wa = a[rr][q][k], wb = b[rr][q][k];
;                     const float d0 = bf2f(wa & 0xffffu) - lam * bf2f(wb & 0xffffu), d1 = bf2f(wa >> 16) - lam * bf2f(wb >> 16);
;                     d[8 * q + 2 * k] = d0; d[8 * q + 2 * k + 1] = d1; ss += d0 * d0 + d1 * d1; }
;             ss += __shfl_xor(ss, 1); ss += __shfl_xor(ss, 2); ss += __shfl_xor(ss, 4);
;             const float rs = 1.0f / sqrtf(ss * (1.0f / 128.0f) + EPS);
;             u32x4 o0, o1;
; #pragma unroll
;             for (int k = 0; k < 4; ++k) { o0[k] = pk2(d[2 * k] * rs * g[2 * k], d[2 * k + 1] * rs * g[2 * k + 1]); o1[k] = pk2(d[8 + 2 * k] * rs * g[8 + 2 * k], d[9 + 2 * k] * rs * g[9 + 2 * k]); }
;             bf16* q = CAT + (size_t)t * DM + 1024 + h * 128 + 16 * part; *(u32x4*)q = o0; *(u32x4*)(q + 8) = o1; } }
.LBB0_689:
	s_waitcnt vmcnt(2)
	v_lshlrev_b32_e32 v37, 16, v26
	s_waitcnt vmcnt(0)
	v_lshlrev_b32_e32 v62, 16, v30
	v_fma_f32 v37, -v40, v62, v37
	v_and_b32_e32 v26, 0xffff0000, v26
	v_and_b32_e32 v30, 0xffff0000, v30
	v_lshlrev_b32_e32 v62, 16, v27
	v_lshlrev_b32_e32 v63, 16, v31
	v_and_b32_e32 v27, 0xffff0000, v27
	v_and_b32_e32 v31, 0xffff0000, v31
	v_fma_f32 v30, -v40, v30, v26
	v_fma_f32 v31, -v40, v31, v27
	v_mul_f32_e32 v26, v30, v30
	v_fma_f32 v62, -v40, v63, v62
	v_mul_f32_e32 v27, v31, v31
	v_fmac_f32_e32 v26, v37, v37
	v_fmac_f32_e32 v27, v62, v62
	v_add_f32_e32 v26, v26, v27
	v_lshlrev_b32_e32 v27, 16, v28
	v_lshlrev_b32_e32 v63, 16, v32
	v_fma_f32 v63, -v40, v63, v27
	v_and_b32_e32 v27, 0xffff0000, v28
	v_and_b32_e32 v28, 0xffff0000, v32
	v_fma_f32 v28, -v40, v28, v27
	v_mul_f32_e32 v27, v28, v28
	v_fmac_f32_e32 v27, v63, v63
	v_add_f32_e32 v26, v27, v26
	v_lshlrev_b32_e32 v27, 16, v29
	v_lshlrev_b32_e32 v32, 16, v33
	v_fma_f32 v32, -v40, v32, v27
	v_and_b32_e32 v27, 0xffff0000, v29
	v_and_b32_e32 v29, 0xffff0000, v33
	v_fma_f32 v29, -v40, v29, v27
	v_mul_f32_e32 v27, v29, v29
	v_fmac_f32_e32 v27, v32, v32
	v_add_f32_e32 v26, v27, v26
	v_lshlrev_b32_e32 v27, 16, v22
	v_lshlrev_b32_e32 v33, 16, v18
	v_and_b32_e32 v22, 0xffff0000, v22
	v_and_b32_e32 v18, 0xffff0000, v18
	v_fma_f32 v64, -v40, v18, v22
	v_fma_f32 v33, -v40, v33, v27
	v_mul_f32_e32 v18, v64, v64
	v_fmac_f32_e32 v18, v33, v33
	v_add_f32_e32 v18, v18, v26
	v_lshlrev_b32_e32 v22, 16, v23
	v_lshlrev_b32_e32 v26, 16, v19
	v_fma_f32 v65, -v40, v26, v22
	v_and_b32_e32 v22, 0xffff0000, v23
	v_and_b32_e32 v19, 0xffff0000, v19
	v_fma_f32 v66, -v40, v19, v22
	v_mul_f32_e32 v19, v66, v66
	v_fmac_f32_e32 v19, v65, v65
	v_add_f32_e32 v67, v19, v18
	v_lshlrev_b32_e32 v19, 16, v25
	v_lshlrev_b32_e32 v18, 16, v24
	v_lshlrev_b32_e32 v23, 16, v21
	v_lshlrev_b32_e32 v22, 16, v20
	v_pk_fma_f32 v[26:27], v[40:41], v[22:23], v[18:19] neg_lo:[1,0,0] neg_hi:[1,0,0]
	v_and_b32_e32 v19, 0xffff0000, v25
	v_and_b32_e32 v18, 0xffff0000, v24
	v_and_b32_e32 v21, 0xffff0000, v21
	v_and_b32_e32 v20, 0xffff0000, v20
	v_pk_fma_f32 v[24:25], v[40:41], v[20:21], v[18:19] neg_lo:[1,0,0] neg_hi:[1,0,0]
	s_nop 0
	v_pk_mul_f32 v[18:19], v[24:25], v[24:25]
	s_nop 0
	v_pk_fma_f32 v[18:19], v[26:27], v[26:27], v[18:19]
	s_nop 0
	v_add_f32_e32 v18, v18, v67
	v_add_f32_e32 v18, v19, v18
	s_waitcnt lgkmcnt(0)
	s_nop 1
	v_add_f32_dpp v18, v18, v18 quad_perm:[1,0,3,2] row_mask:0xf bank_mask:0xf
	s_waitcnt lgkmcnt(0)
	s_nop 1
	v_add_f32_dpp v18, v18, v18 quad_perm:[2,3,0,1] row_mask:0xf bank_mask:0xf
	s_waitcnt lgkmcnt(0)
	s_nop 1
	v_add_f32_dpp v18, v18, v18 row_half_mirror row_mask:0xf bank_mask:0xf
	v_fmamk_f32 v18, v18, 0x3c000000, v44
	v_mul_f32_e32 v19, 0x4f800000, v18
	v_cmp_gt_f32_e32 vcc, s16, v18
	s_nop 1
	v_cndmask_b32_e32 v18, v18, v19, vcc
	v_sqrt_f32_e32 v19, v18
	s_nop 0
	v_add_u32_e32 v20, -1, v19
	v_fma_f32 v21, -v20, v19, v18
	v_cmp_ge_f32_e64 s[6:7], 0, v21
	v_add_u32_e32 v21, 1, v19
	s_nop 0
	v_cndmask_b32_e64 v20, v19, v20, s[6:7]
	v_fma_f32 v19, -v21, v19, v18
	v_cmp_lt_f32_e64 s[6:7], 0, v19
	s_nop 1
	v_cndmask_b32_e64 v19, v20, v21, s[6:7]
	v_mul_f32_e32 v20, 0x37800000, v19
	v_cndmask_b32_e32 v19, v19, v20, vcc
	v_cmp_class_f32_e32 vcc, v18, v45
	s_nop 1
	v_cndmask_b32_e32 v18, v19, v18, vcc
	v_div_scale_f32 v19, s[4:5], v18, v18, 1.0
	v_rcp_f32_e32 v20, v19
	s_add_u32 s4, s42, s14
	s_addc_u32 s5, s43, s15
	v_fma_f32 v21, -v19, v20, 1.0
	v_fmac_f32_e32 v20, v21, v20
	v_div_scale_f32 v21, vcc, 1.0, v18, 1.0
	v_mul_f32_e32 v22, v21, v20
	v_fma_f32 v23, -v19, v22, v21
	v_fmac_f32_e32 v22, v23, v20
	v_fma_f32 v19, -v19, v22, v21
	v_div_fmas_f32 v19, v19, v20, v22
	v_div_fixup_f32 v67, v19, v18, 1.0
	v_mul_f32_e32 v18, v37, v67
	v_mul_f32_e32 v19, v30, v67
	v_mul_f32_e32 v18, v46, v18
	v_mul_f32_e32 v19, v47, v19
	v_cvt_pk_bf16_f32 v18, v18, v19
	v_mul_f32_e32 v19, v33, v67
	v_mul_f32_e32 v20, v64, v67
	v_mul_f32_e32 v19, v54, v19
	v_mul_f32_e32 v20, v55, v20
	v_cvt_pk_bf16_f32 v22, v19, v20
	v_mul_f32_e32 v19, v62, v67
	v_mul_f32_e32 v20, v31, v67
	v_mul_f32_e32 v19, v48, v19
	v_mul_f32_e32 v20, v49, v20
	v_cvt_pk_bf16_f32 v19, v19, v20
	v_mul_f32_e32 v20, v65, v67
	v_mul_f32_e32 v21, v66, v67
	v_mul_f32_e32 v20, v56, v20
	v_mul_f32_e32 v21, v57, v21
	v_cvt_pk_bf16_f32 v23, v20, v21
	v_mul_f32_e32 v20, v63, v67
	v_mul_f32_e32 v21, v28, v67
	v_mul_f32_e32 v20, v50, v20
	v_mul_f32_e32 v21, v51, v21
	v_cvt_pk_bf16_f32 v20, v20, v21
	v_mul_f32_e32 v21, v26, v67
	v_mul_f32_e32 v24, v24, v67
	v_mul_f32_e32 v21, v58, v21
	v_mul_f32_e32 v24, v59, v24
	v_cvt_pk_bf16_f32 v24, v21, v24
	v_mul_f32_e32 v21, v32, v67
	v_mul_f32_e32 v26, v29, v67
	v_mul_f32_e32 v21, v52, v21
	v_mul_f32_e32 v26, v53, v26
	v_cvt_pk_bf16_f32 v21, v21, v26
	v_mul_f32_e32 v26, v27, v67
	v_mul_f32_e32 v25, v25, v67
	v_mul_f32_e32 v26, v60, v26
	v_mul_f32_e32 v25, v61, v25
	v_cvt_pk_bf16_f32 v25, v26, v25
	v_lshl_add_u64 v[26:27], s[4:5], 0, v[34:35]
	v_mov_b32_e32 v37, v35
	v_lshl_add_u64 v[26:27], v[26:27], 0, v[36:37]
	v_lshl_add_u64 v[28:29], v[26:27], 0, s[8:9]
	v_add_co_u32_e32 v26, vcc, 0x1ae00000, v26
	global_store_dwordx4 v[28:29], v[22:25], off offset:16
	s_nop 0
	v_addc_co_u32_e32 v27, vcc, 0, v27, vcc
	s_andn2_b64 vcc, exec, s[12:13]
	global_store_dwordx4 v[26:27], v[18:21], off offset:2048
	s_cbranch_vccnz .LBB0_686
; __device__ __forceinline__ float bf2f(unsigned h) { return __uint_as_float(h << 16); }
; __device__ __forceinline__ unsigned pk2(float lo, float hi) { return pg8::cvt_pk_bf16(lo, hi); }
; __device__ __forceinline__ void attn_combine(const Ctx& C, const Args& A) {
;     ...
;         for (int rr = 0; rr < 2; ++rr) { const int t = t0 + rr * NGW; if (t < M) {
;             float d[16]; float ss = 0.f;
; #pragma unroll
;             for (int q = 0; q < 2; ++q)
; #pragma unroll
;                 for (int k = 0; k < 4; ++k) { const unsigned wa = a[rr][q][k], wb = b[rr][q][k];
;                     const float d0 = bf2f(wa & 0xffffu) - lam * bf2f(wb & 0xffffu), d1 = bf2f(wa >> 16) - lam * bf2f(wb >> 16);
;                     d[8 * q + 2 * k] = d0; d[8 * q + 2 * k + 1] = d1; ss += d0 * d0 + d1 * d1; }
;             ss += __shfl_xor(ss, 1); ss += __shfl_xor(ss, 2); ss += __shfl_xor(ss, 4);
;             const float rs = 1.0f / sqrtf(ss * (1.0f / 128.0f) + EPS);
;             u32x4 o0, o1;
; #pragma unroll
;             for (int k = 0; k < 4; ++k) { o0[k] = pk2(d[2 * k] * rs * g[2 * k], d[2 * k + 1] * rs * g[2 * k + 1]); o1[k] = pk2(d[8 + 2 * k] * rs * g[8 + 2 * k], d[9 + 2 * k] * rs * g[9 + 2 * k]); }
;             bf16* q = CAT + (size_t)t * DM + 1024 + h * 128 + 16 * part; *(u32x4*)q = o0; *(u32x4*)(q + 8) = o1; } }
	s_nop 0
	v_lshlrev_b32_e32 v18, 16, v6
	v_lshlrev_b32_e32 v19, 16, v14
	v_fma_f32 v22, -v40, v19, v18
	v_and_b32_e32 v18, 0xffff0000, v6
	v_and_b32_e32 v19, 0xffff0000, v14
	v_fma_f32 v23, -v40, v19, v18
	v_lshlrev_b32_e32 v19, 16, v7
	v_lshlrev_b32_e32 v20, 16, v15
	v_fma_f32 v28, -v40, v20, v19
	v_and_b32_e32 v19, 0xffff0000, v7
	v_and_b32_e32 v20, 0xffff0000, v15
	v_fma_f32 v29, -v40, v20, v19
	v_mul_f32_e32 v18, v23, v23
	v_mul_f32_e32 v19, v29, v29
	v_fmac_f32_e32 v18, v22, v22
	v_fmac_f32_e32 v19, v28, v28
	v_add_f32_e32 v18, v18, v19
	v_lshlrev_b32_e32 v19, 16, v8
	v_lshlrev_b32_e32 v20, 16, v16
	v_fma_f32 v30, -v40, v20, v19
	v_and_b32_e32 v19, 0xffff0000, v8
	v_and_b32_e32 v20, 0xffff0000, v16
	v_fma_f32 v31, -v40, v20, v19
	v_mul_f32_e32 v19, v31, v31
	v_fmac_f32_e32 v19, v30, v30
	v_add_f32_e32 v18, v19, v18
	v_lshlrev_b32_e32 v19, 16, v9
	v_lshlrev_b32_e32 v20, 16, v17
	v_fma_f32 v32, -v40, v20, v19
	v_and_b32_e32 v19, 0xffff0000, v9
	v_and_b32_e32 v20, 0xffff0000, v17
	v_fma_f32 v33, -v40, v20, v19
	v_mul_f32_e32 v19, v33, v33
	v_fmac_f32_e32 v19, v32, v32
	v_add_f32_e32 v18, v19, v18
	v_lshlrev_b32_e32 v19, 16, v2
	v_lshlrev_b32_e32 v20, 16, v10
	v_fma_f32 v62, -v40, v20, v19
	v_and_b32_e32 v19, 0xffff0000, v2
	v_and_b32_e32 v20, 0xffff0000, v10
	v_fma_f32 v63, -v40, v20, v19
	v_mul_f32_e32 v19, v63, v63
	v_fmac_f32_e32 v19, v62, v62
	v_add_f32_e32 v18, v19, v18
	v_lshlrev_b32_e32 v19, 16, v3
	v_lshlrev_b32_e32 v20, 16, v11
	v_fma_f32 v64, -v40, v20, v19
	v_and_b32_e32 v19, 0xffff0000, v3
	v_and_b32_e32 v20, 0xffff0000, v11
	v_fma_f32 v65, -v40, v20, v19
	v_mul_f32_e32 v19, v65, v65
	v_fmac_f32_e32 v19, v64, v64
	v_add_f32_e32 v66, v19, v18
	v_lshlrev_b32_e32 v19, 16, v5
	v_lshlrev_b32_e32 v18, 16, v4
	v_lshlrev_b32_e32 v21, 16, v13
	v_lshlrev_b32_e32 v20, 16, v12
	v_pk_fma_f32 v[24:25], v[40:41], v[20:21], v[18:19] neg_lo:[1,0,0] neg_hi:[1,0,0]
	v_and_b32_e32 v19, 0xffff0000, v5
	v_and_b32_e32 v18, 0xffff0000, v4
	v_and_b32_e32 v21, 0xffff0000, v13
	v_and_b32_e32 v20, 0xffff0000, v12
	v_pk_fma_f32 v[26:27], v[40:41], v[20:21], v[18:19] neg_lo:[1,0,0] neg_hi:[1,0,0]
	s_ashr_i32 s11, s10, 31
	v_pk_mul_f32 v[18:19], v[26:27], v[26:27]
	s_nop 0
	v_pk_fma_f32 v[18:19], v[24:25], v[24:25], v[18:19]
	s_nop 0
	v_add_f32_e32 v18, v18, v66
	v_add_f32_e32 v18, v19, v18
	s_waitcnt lgkmcnt(0)
	s_nop 1
	v_add_f32_dpp v18, v18, v18 quad_perm:[1,0,3,2] row_mask:0xf bank_mask:0xf
	s_waitcnt lgkmcnt(0)
	s_nop 1
	v_add_f32_dpp v18, v18, v18 quad_perm:[2,3,0,1] row_mask:0xf bank_mask:0xf
	s_waitcnt lgkmcnt(0)
	s_nop 1
	v_add_f32_dpp v18, v18, v18 row_half_mirror row_mask:0xf bank_mask:0xf
	v_fmamk_f32 v18, v18, 0x3c000000, v44
	v_mul_f32_e32 v19, 0x4f800000, v18
	v_cmp_gt_f32_e32 vcc, s16, v18
	s_nop 1
	v_cndmask_b32_e32 v18, v18, v19, vcc
	v_sqrt_f32_e32 v19, v18
	s_nop 0
	v_add_u32_e32 v20, -1, v19
	v_fma_f32 v21, -v20, v19, v18
	v_cmp_ge_f32_e64 s[6:7], 0, v21
	v_add_u32_e32 v21, 1, v19
	s_nop 0
	v_cndmask_b32_e64 v20, v19, v20, s[6:7]
	v_fma_f32 v19, -v21, v19, v18
	v_cmp_lt_f32_e64 s[6:7], 0, v19
	s_nop 1
	v_cndmask_b32_e64 v19, v20, v21, s[6:7]
	v_mul_f32_e32 v20, 0x37800000, v19
	v_cndmask_b32_e32 v19, v19, v20, vcc
	v_cmp_class_f32_e32 vcc, v18, v45
	s_nop 1
	v_cndmask_b32_e32 v18, v19, v18, vcc
	v_div_scale_f32 v19, s[4:5], v18, v18, 1.0
	v_rcp_f32_e32 v20, v19
	s_lshl_b64 s[4:5], s[10:11], 12
	s_add_u32 s4, s42, s4
	s_addc_u32 s5, s43, s5
	v_fma_f32 v21, -v19, v20, 1.0
	v_fmac_f32_e32 v20, v21, v20
	v_div_scale_f32 v21, vcc, 1.0, v18, 1.0
	v_mul_f32_e32 v66, v21, v20
	v_fma_f32 v67, -v19, v66, v21
	v_fmac_f32_e32 v66, v67, v20
	v_fma_f32 v19, -v19, v66, v21
	v_div_fmas_f32 v19, v19, v20, v66
	v_div_fixup_f32 v66, v19, v18, 1.0
	v_mul_f32_e32 v18, v22, v66
	v_mul_f32_e32 v19, v23, v66
	v_mul_f32_e32 v18, v46, v18
	v_mul_f32_e32 v19, v47, v19
	v_cvt_pk_bf16_f32 v18, v18, v19
	v_mul_f32_e32 v19, v62, v66
	v_mul_f32_e32 v20, v63, v66
	v_mul_f32_e32 v19, v54, v19
	v_mul_f32_e32 v20, v55, v20
	v_cvt_pk_bf16_f32 v22, v19, v20
	v_mul_f32_e32 v19, v28, v66
	v_mul_f32_e32 v20, v29, v66
	v_mul_f32_e32 v19, v48, v19
	v_mul_f32_e32 v20, v49, v20
	v_cvt_pk_bf16_f32 v19, v19, v20
	v_mul_f32_e32 v20, v64, v66
	v_mul_f32_e32 v21, v65, v66
	v_mul_f32_e32 v20, v56, v20
	v_mul_f32_e32 v21, v57, v21
	v_cvt_pk_bf16_f32 v23, v20, v21
	v_mul_f32_e32 v20, v30, v66
	v_mul_f32_e32 v21, v31, v66
	v_mul_f32_e32 v20, v50, v20
	v_mul_f32_e32 v21, v51, v21
	v_cvt_pk_bf16_f32 v20, v20, v21
	v_mul_f32_e32 v21, v24, v66
	v_mul_f32_e32 v24, v26, v66
	v_mul_f32_e32 v21, v58, v21
	v_mul_f32_e32 v24, v59, v24
	v_cvt_pk_bf16_f32 v24, v21, v24
	v_mul_f32_e32 v21, v32, v66
	v_mul_f32_e32 v26, v33, v66
	v_mul_f32_e32 v21, v52, v21
	v_mul_f32_e32 v26, v53, v26
	v_cvt_pk_bf16_f32 v21, v21, v26
	v_mul_f32_e32 v25, v25, v66
	v_mul_f32_e32 v26, v27, v66
	v_mul_f32_e32 v25, v60, v25
	v_mul_f32_e32 v26, v61, v26
	v_cvt_pk_bf16_f32 v25, v25, v26
	v_lshl_add_u64 v[26:27], s[4:5], 0, v[34:35]
	v_lshl_add_u64 v[26:27], v[26:27], 0, v[36:37]
	v_lshl_add_u64 v[28:29], v[26:27], 0, s[8:9]
	v_add_co_u32_e32 v26, vcc, 0x1ae00000, v26
	s_nop 1
	v_addc_co_u32_e32 v27, vcc, 0, v27, vcc
	global_store_dwordx4 v[26:27], v[18:21], off offset:2048
	global_store_dwordx4 v[28:29], v[22:25], off offset:16
	s_branch .LBB0_686

; __device__ __forceinline__ float bf2f(unsigned h) { return __uint_as_float(h << 16); }
; template <int MODE> __device__ __forceinline__ void rows_pass(const Ctx& C, const float* src, const float* g, bf16* dst_bf, float* dst_f, const LAS float* wg, const float* b_ig = nullptr, const float* b_fg = nullptr, const bf16* add_bf = nullptr, const bf16* add2_bf = nullptr) {
;     ...
;     for (int m = gw; m < M; m += NGW) {
;         const f32x4* xr = (const f32x4*)(src + (size_t)m * DM) + lane;
;         f32x4 v[8]; float ss = 0.f;
; #pragma unroll
;         for (int j = 0; j < 8; ++j) v[j] = xr[64 * j];
;         if (MODE != 0) { const u32x2* ar = (const u32x2*)(add_bf + (size_t)m * DM) + lane;
; #pragma unroll
;             for (int j = 0; j < 8; ++j) { const u32x2 a = ar[64 * j]; v[j].x += bf2f(a.x & 0xffffu); v[j].y += bf2f(a.x >> 16); v[j].z += bf2f(a.y & 0xffffu); v[j].w += bf2f(a.y >> 16); }
;             if (MODE == 2) { const u32x2* ar2 = (const u32x2*)(add2_bf + (size_t)m * DM) + lane;
; #pragma unroll
;                 for (int j = 0; j < 8; ++j) { const u32x2 a = ar2[64 * j]; v[j].x += bf2f(a.x & 0xffffu); v[j].y += bf2f(a.x >> 16); v[j].z += bf2f(a.y & 0xffffu); v[j].w += bf2f(a.y >> 16); } } }
; #pragma unroll
;         for (int j = 0; j < 8; ++j) ss += (v[j].x * v[j].x + v[j].y * v[j].y) + (v[j].z * v[j].z + v[j].w * v[j].w);
;         const float rs = 1.0f / sqrtf(wave_sum(ss) * (1.0f / DM) + EPS);
; #pragma unroll
;         for (int j = 0; j < 8; ++j) { const f32x4 gg = ((const f32x4*)g)[64 * j + lane]; v[j] = v[j] * rs * gg; }
.LBB0_827:
	v_lshl_add_u64 v[72:73], s[20:21], 0, v[70:71]
	global_load_dwordx4 v[30:33], v[68:69], off offset:-4096
	global_load_dwordx4 v[26:29], v[68:69], off offset:-3072
	global_load_dwordx4 v[22:25], v[68:69], off offset:-2048
	global_load_dwordx4 v[18:21], v[68:69], off offset:-1024
	global_load_dwordx4 v[14:17], v[68:69], off
	global_load_dwordx4 v[10:13], v[68:69], off offset:1024
	global_load_dwordx4 v[6:9], v[68:69], off offset:2048
	global_load_dwordx4 v[2:5], v[68:69], off offset:3072
	global_load_dwordx4 v[34:37], v[58:59], off
	global_load_dwordx4 v[38:41], v[58:59], off offset:1024
	global_load_dwordx4 v[42:45], v[58:59], off offset:2048
	global_load_dwordx4 v[46:49], v[58:59], off offset:3072
	global_load_dwordx4 v[50:53], v[60:61], off
	global_load_dwordx4 v[54:57], v[62:63], off
	global_load_dwordx4 v[84:87], v[64:65], off
	global_load_dwordx4 v[88:91], v[66:67], off
	global_load_dwordx2 v[92:93], v[72:73], off offset:-2048
	global_load_dwordx2 v[94:95], v[72:73], off offset:-1536
	global_load_dwordx2 v[96:97], v[72:73], off offset:-1024
	global_load_dwordx2 v[98:99], v[72:73], off offset:-512
	global_load_dwordx2 v[100:101], v[72:73], off
	global_load_dwordx2 v[102:103], v[72:73], off offset:512
	global_load_dwordx2 v[104:105], v[72:73], off offset:1024
	global_load_dwordx2 v[106:107], v[72:73], off offset:1536
	s_add_i32 s3, s3, s12
	v_lshl_add_u64 v[74:75], s[16:17], 0, v[70:71]
	v_lshl_add_u64 v[68:69], v[68:69], 0, s[14:15]
	v_lshl_add_u64 v[70:71], v[70:71], 0, s[18:19]
	s_cmpk_lt_i32 s3, 0x4000
	s_waitcnt vmcnt(0)
	v_lshlrev_b32_e32 v72, 16, v92
	v_and_b32_e32 v73, 0xffff0000, v92
	v_lshlrev_b32_e32 v92, 16, v93
	v_and_b32_e32 v93, 0xffff0000, v93
	v_lshlrev_b32_e32 v108, 16, v94
	v_and_b32_e32 v109, 0xffff0000, v94
	v_lshlrev_b32_e32 v94, 16, v95
	v_and_b32_e32 v95, 0xffff0000, v95
	v_lshlrev_b32_e32 v110, 16, v96
	v_and_b32_e32 v111, 0xffff0000, v96
	v_lshlrev_b32_e32 v96, 16, v97
	v_and_b32_e32 v97, 0xffff0000, v97
	v_pk_add_f32 v[30:31], v[30:31], v[72:73]
	v_pk_add_f32 v[32:33], v[32:33], v[92:93]
	v_pk_add_f32 v[26:27], v[26:27], v[108:109]
	v_pk_add_f32 v[28:29], v[28:29], v[94:95]
	v_lshlrev_b32_e32 v114, 16, v100
	v_and_b32_e32 v115, 0xffff0000, v100
	v_lshlrev_b32_e32 v100, 16, v101
	v_and_b32_e32 v101, 0xffff0000, v101
	v_pk_add_f32 v[22:23], v[22:23], v[110:111]
	v_pk_add_f32 v[24:25], v[24:25], v[96:97]
	v_mov_b32_e32 v92, v31
	v_mov_b32_e32 v93, v27
	v_mov_b32_e32 v96, v33
	v_mov_b32_e32 v97, v29
	v_lshlrev_b32_e32 v112, 16, v98
	v_and_b32_e32 v113, 0xffff0000, v98
	v_lshlrev_b32_e32 v98, 16, v99
	v_and_b32_e32 v99, 0xffff0000, v99
	v_pk_add_f32 v[16:17], v[16:17], v[100:101]
	v_mov_b32_e32 v72, v30
	v_mov_b32_e32 v73, v26
	v_mov_b32_e32 v94, v32
	v_mov_b32_e32 v95, v28
	v_mov_b32_e32 v100, v23
	v_mov_b32_e32 v101, v25
	v_pk_mul_f32 v[92:93], v[92:93], v[92:93]
	v_pk_mul_f32 v[96:97], v[96:97], v[96:97]
	v_lshlrev_b32_e32 v116, 16, v102
	v_and_b32_e32 v117, 0xffff0000, v102
	v_lshlrev_b32_e32 v102, 16, v103
	v_and_b32_e32 v103, 0xffff0000, v103
	v_lshlrev_b32_e32 v118, 16, v104
	v_and_b32_e32 v119, 0xffff0000, v104
	v_lshlrev_b32_e32 v104, 16, v105
	v_and_b32_e32 v105, 0xffff0000, v105
	v_pk_add_f32 v[18:19], v[18:19], v[112:113]
	v_pk_add_f32 v[20:21], v[20:21], v[98:99]
	v_mov_b32_e32 v98, v22
	v_mov_b32_e32 v99, v24
	v_pk_mul_f32 v[100:101], v[100:101], v[100:101]
	v_pk_fma_f32 v[72:73], v[72:73], v[72:73], v[92:93]
	v_pk_fma_f32 v[92:93], v[94:95], v[94:95], v[96:97]
	v_lshlrev_b32_e32 v120, 16, v106
	v_and_b32_e32 v121, 0xffff0000, v106
	v_lshlrev_b32_e32 v106, 16, v107
	v_and_b32_e32 v107, 0xffff0000, v107
	v_pk_add_f32 v[14:15], v[14:15], v[114:115]
	v_pk_add_f32 v[12:13], v[12:13], v[102:103]
	v_pk_add_f32 v[8:9], v[8:9], v[104:105]
	v_mul_f32_e32 v102, v19, v19
	v_mul_f32_e32 v104, v21, v21
	v_pk_fma_f32 v[94:95], v[98:99], v[98:99], v[100:101]
	v_pk_add_f32 v[72:73], v[72:73], v[92:93]
	v_pk_add_f32 v[10:11], v[10:11], v[116:117]
	v_pk_add_f32 v[4:5], v[4:5], v[106:107]
	v_pk_mul_f32 v[106:107], v[14:15], v[14:15]
	v_pk_mul_f32 v[108:109], v[16:17], v[16:17]
	v_pk_fma_f32 v[102:103], v[18:19], v[18:19], v[102:103] op_sel_hi:[1,1,0]
	v_pk_fma_f32 v[104:105], v[20:21], v[20:21], v[104:105] op_sel_hi:[1,1,0]
	v_pk_add_f32 v[92:93], v[94:95], v[94:95] op_sel:[0,1] op_sel_hi:[1,0]
	v_pk_add_f32 v[72:73], v[72:73], v[72:73] op_sel:[0,1] op_sel_hi:[1,0]
	v_mov_b32_e32 v112, v11
	v_mov_b32_e32 v113, v13
	v_mov_b32_e32 v103, v108
	v_mov_b32_e32 v105, v109
	v_mov_b32_e32 v93, v107
	v_mov_b32_e32 v73, v106
	v_pk_add_f32 v[6:7], v[6:7], v[118:119]
	v_mov_b32_e32 v110, v10
	v_mov_b32_e32 v111, v12
	v_pk_mul_f32 v[112:113], v[112:113], v[112:113]
	v_pk_add_f32 v[94:95], v[102:103], v[104:105]
	v_pk_add_f32 v[72:73], v[72:73], v[92:93]
	v_pk_add_f32 v[2:3], v[2:3], v[120:121]
	v_mul_f32_e32 v114, v7, v7
	v_mul_f32_e32 v116, v9, v9
	v_pk_fma_f32 v[96:97], v[110:111], v[110:111], v[112:113]
	v_pk_add_f32 v[72:73], v[72:73], v[94:95]
	v_pk_mul_f32 v[118:119], v[2:3], v[2:3]
	v_pk_mul_f32 v[120:121], v[4:5], v[4:5]
	v_pk_fma_f32 v[114:115], v[6:7], v[6:7], v[114:115] op_sel_hi:[1,1,0]
	v_pk_fma_f32 v[116:117], v[8:9], v[8:9], v[116:117] op_sel_hi:[1,1,0]
	v_pk_add_f32 v[96:97], v[96:97], v[96:97] op_sel:[0,1] op_sel_hi:[1,0]
	v_pk_add_f32 v[72:73], v[72:73], v[72:73] op_sel:[0,1] op_sel_hi:[1,0]
	v_mov_b32_e32 v115, v120
	v_mov_b32_e32 v117, v121
	v_mov_b32_e32 v97, v119
	v_mov_b32_e32 v73, v118
	v_pk_add_f32 v[98:99], v[114:115], v[116:117]
	v_pk_add_f32 v[72:73], v[72:73], v[96:97]
	s_nop 0
	v_pk_add_f32 v[72:73], v[72:73], v[98:99]
	s_nop 0
	v_add_f32_e32 v72, v72, v73
	s_waitcnt lgkmcnt(0)
; __device__ __forceinline__ unsigned pk2(float lo, float hi) { return pg8::cvt_pk_bf16(lo, hi); }
; template <int MODE> __device__ __forceinline__ void rows_pass(const Ctx& C, const float* src, const float* g, bf16* dst_bf, float* dst_f, const LAS float* wg, const float* b_ig = nullptr, const float* b_fg = nullptr, const bf16* add_bf = nullptr, const bf16* add2_bf = nullptr) {
;     ...
;         const float rs = 1.0f / sqrtf(wave_sum(ss) * (1.0f / DM) + EPS);
; #pragma unroll
;         for (int j = 0; j < 8; ++j) { const f32x4 gg = ((const f32x4*)g)[64 * j + lane]; v[j] = v[j] * rs * gg; }
;         if (MODE == 2) {
;             f32x4* o = (f32x4*)(dst_f + (size_t)m * DM) + lane;
; #pragma unroll
;             for (int j = 0; j < 8; ++j) o[64 * j] = v[j];
;         } else {
;             u32x2* o = (u32x2*)(dst_bf + (size_t)m * DM) + lane;
; #pragma unroll
;             for (int j = 0; j < 8; ++j) { u32x2 w; w.x = pk2(v[j].x, v[j].y); w.y = pk2(v[j].z, v[j].w); o[64 * j] = w; }
	s_nop 1
	v_add_f32_dpp v72, v72, v72 quad_perm:[1,0,3,2] row_mask:0xf bank_mask:0xf
	s_waitcnt lgkmcnt(0)
	s_nop 1
	v_add_f32_dpp v72, v72, v72 quad_perm:[2,3,0,1] row_mask:0xf bank_mask:0xf
	s_waitcnt lgkmcnt(0)
	s_nop 1
	v_add_f32_dpp v72, v72, v72 row_half_mirror row_mask:0xf bank_mask:0xf
	s_waitcnt lgkmcnt(0)
	s_nop 1
	v_add_f32_dpp v72, v72, v72 row_mirror row_mask:0xf bank_mask:0xf
	s_waitcnt lgkmcnt(0)
	v_mov_b32_e32 v73, v72
	s_nop 1
	v_permlane16_swap_b32_e32 v72, v73
	v_add_f32_e32 v72, v72, v73
	s_waitcnt lgkmcnt(0)
	v_mov_b32_e32 v73, v72
	s_nop 1
	v_permlane32_swap_b32_e32 v72, v73
	v_add_f32_e32 v72, v72, v73
	v_fmamk_f32 v72, v72, 0x3a000000, v81
	v_mul_f32_e32 v73, 0x4f800000, v72
	v_cmp_gt_f32_e32 vcc, s13, v72
	s_nop 1
	v_cndmask_b32_e32 v72, v72, v73, vcc
	v_sqrt_f32_e32 v73, v72
	s_nop 0
	v_add_u32_e32 v83, -1, v73
	v_add_u32_e32 v92, 1, v73
	v_fma_f32 v93, -v83, v73, v72
	v_fma_f32 v94, -v92, v73, v72
	v_cmp_ge_f32_e64 s[6:7], 0, v93
	s_nop 1
	v_cndmask_b32_e64 v73, v73, v83, s[6:7]
	v_cmp_lt_f32_e64 s[6:7], 0, v94
	s_nop 1
	v_cndmask_b32_e64 v73, v73, v92, s[6:7]
	v_mul_f32_e32 v83, 0x37800000, v73
	v_cndmask_b32_e32 v73, v73, v83, vcc
	v_cmp_class_f32_e32 vcc, v72, v82
	s_nop 1
	v_cndmask_b32_e32 v72, v73, v72, vcc
	v_div_scale_f32 v73, s[4:5], v72, v72, 1.0
	v_rcp_f32_e32 v92, v73
	v_div_scale_f32 v83, vcc, 1.0, v72, 1.0
	v_fma_f32 v93, -v73, v92, 1.0
	v_fmac_f32_e32 v92, v93, v92
	v_mul_f32_e32 v93, v83, v92
	v_fma_f32 v94, -v73, v93, v83
	v_fmac_f32_e32 v93, v94, v92
	v_fma_f32 v73, -v73, v93, v83
	v_div_fmas_f32 v73, v73, v92, v93
	v_div_fixup_f32 v72, v73, v72, 1.0
	v_pk_mul_f32 v[30:31], v[30:31], v[72:73] op_sel_hi:[1,0]
	v_pk_mul_f32 v[26:27], v[26:27], v[72:73] op_sel_hi:[1,0]
	v_pk_mul_f32 v[22:23], v[22:23], v[72:73] op_sel_hi:[1,0]
	v_pk_mul_f32 v[18:19], v[18:19], v[72:73] op_sel_hi:[1,0]
	v_pk_mul_f32 v[14:15], v[14:15], v[72:73] op_sel_hi:[1,0]
	v_pk_mul_f32 v[10:11], v[10:11], v[72:73] op_sel_hi:[1,0]
	v_pk_mul_f32 v[6:7], v[6:7], v[72:73] op_sel_hi:[1,0]
	v_pk_mul_f32 v[2:3], v[2:3], v[72:73] op_sel_hi:[1,0]
	v_pk_mul_f32 v[32:33], v[32:33], v[72:73] op_sel_hi:[1,0]
	v_pk_mul_f32 v[28:29], v[28:29], v[72:73] op_sel_hi:[1,0]
	v_pk_mul_f32 v[24:25], v[24:25], v[72:73] op_sel_hi:[1,0]
	v_pk_mul_f32 v[20:21], v[20:21], v[72:73] op_sel_hi:[1,0]
	v_pk_mul_f32 v[16:17], v[16:17], v[72:73] op_sel_hi:[1,0]
	v_pk_mul_f32 v[12:13], v[12:13], v[72:73] op_sel_hi:[1,0]
	v_pk_mul_f32 v[8:9], v[8:9], v[72:73] op_sel_hi:[1,0]
	v_pk_mul_f32 v[4:5], v[4:5], v[72:73] op_sel_hi:[1,0]
	v_pk_mul_f32 v[30:31], v[34:35], v[30:31]
	v_pk_mul_f32 v[26:27], v[38:39], v[26:27]
	v_pk_mul_f32 v[22:23], v[42:43], v[22:23]
	v_pk_mul_f32 v[18:19], v[46:47], v[18:19]
	v_pk_mul_f32 v[14:15], v[50:51], v[14:15]
	v_pk_mul_f32 v[10:11], v[54:55], v[10:11]
	v_pk_mul_f32 v[6:7], v[84:85], v[6:7]
	v_pk_mul_f32 v[2:3], v[88:89], v[2:3]
	v_pk_mul_f32 v[32:33], v[36:37], v[32:33]
	v_pk_mul_f32 v[28:29], v[40:41], v[28:29]
	v_pk_mul_f32 v[24:25], v[44:45], v[24:25]
	v_pk_mul_f32 v[20:21], v[48:49], v[20:21]
	v_pk_mul_f32 v[16:17], v[52:53], v[16:17]
	v_pk_mul_f32 v[12:13], v[56:57], v[12:13]
	v_pk_mul_f32 v[8:9], v[86:87], v[8:9]
	v_pk_mul_f32 v[4:5], v[90:91], v[4:5]
	v_cvt_pk_bf16_f32 v30, v30, v31
	v_cvt_pk_bf16_f32 v31, v32, v33
	global_store_dwordx2 v[74:75], v[30:31], off offset:-2048
	v_cvt_pk_bf16_f32 v26, v26, v27
	v_cvt_pk_bf16_f32 v27, v28, v29
	global_store_dwordx2 v[74:75], v[26:27], off offset:-1536
	v_cvt_pk_bf16_f32 v22, v22, v23
	v_cvt_pk_bf16_f32 v23, v24, v25
	global_store_dwordx2 v[74:75], v[22:23], off offset:-1024
	v_cvt_pk_bf16_f32 v18, v18, v19
	v_cvt_pk_bf16_f32 v19, v20, v21
	global_store_dwordx2 v[74:75], v[18:19], off offset:-512
	v_cvt_pk_bf16_f32 v14, v14, v15
	v_cvt_pk_bf16_f32 v15, v16, v17
	global_store_dwordx2 v[74:75], v[14:15], off
	v_cvt_pk_bf16_f32 v10, v10, v11
	v_cvt_pk_bf16_f32 v11, v12, v13
	global_store_dwordx2 v[74:75], v[10:11], off offset:512
	v_cvt_pk_bf16_f32 v6, v6, v7
	v_cvt_pk_bf16_f32 v7, v8, v9
	global_store_dwordx2 v[74:75], v[6:7], off offset:1024
	v_cvt_pk_bf16_f32 v2, v2, v3
	v_cvt_pk_bf16_f32 v3, v4, v5
	global_store_dwordx2 v[74:75], v[2:3], off offset:1536
	s_cbranch_scc1 .LBB0_827

; __device__ __forceinline__ float bf2f(unsigned h) { return __uint_as_float(h << 16); }
; template <int MODE> __device__ __forceinline__ void rows_pass(const Ctx& C, const float* src, const float* g, bf16* dst_bf, float* dst_f, const LAS float* wg, const float* b_ig = nullptr, const float* b_fg = nullptr, const bf16* add_bf = nullptr, const bf16* add2_bf = nullptr) {
;     ...
;     for (int m = gw; m < M; m += NGW) {
;         const f32x4* xr = (const f32x4*)(src + (size_t)m * DM) + lane;
;         f32x4 v[8]; float ss = 0.f;
; #pragma unroll
;         for (int j = 0; j < 8; ++j) v[j] = xr[64 * j];
;         if (MODE != 0) { const u32x2* ar = (const u32x2*)(add_bf + (size_t)m * DM) + lane;
; #pragma unroll
;             for (int j = 0; j < 8; ++j) { const u32x2 a = ar[64 * j]; v[j].x += bf2f(a.x & 0xffffu); v[j].y += bf2f(a.x >> 16); v[j].z += bf2f(a.y & 0xffffu); v[j].w += bf2f(a.y >> 16); }
;             if (MODE == 2) { const u32x2* ar2 = (const u32x2*)(add2_bf + (size_t)m * DM) + lane;
; #pragma unroll
;                 for (int j = 0; j < 8; ++j) { const u32x2 a = ar2[64 * j]; v[j].x += bf2f(a.x & 0xffffu); v[j].y += bf2f(a.x >> 16); v[j].z += bf2f(a.y & 0xffffu); v[j].w += bf2f(a.y >> 16); } } }
; #pragma unroll
;         for (int j = 0; j < 8; ++j) ss += (v[j].x * v[j].x + v[j].y * v[j].y) + (v[j].z * v[j].z + v[j].w * v[j].w);
.LBB0_1081:
	v_lshl_add_u64 v[46:47], s[4:5], 0, v[32:33]
	v_lshl_add_u64 v[48:49], s[14:15], 0, v[44:45]
	v_lshl_add_u64 v[50:51], s[10:11], 0, v[44:45]
	global_load_dwordx4 v[0:3], v[34:35], off
	global_load_dwordx4 v[4:7], v[34:35], off offset:1024
	global_load_dwordx4 v[8:11], v[34:35], off offset:2048
	global_load_dwordx4 v[12:15], v[34:35], off offset:3072
	global_load_dwordx4 v[16:19], v[36:37], off
	global_load_dwordx4 v[20:23], v[38:39], off
	global_load_dwordx4 v[24:27], v[40:41], off
	global_load_dwordx4 v[28:31], v[42:43], off
	global_load_dwordx2 v[90:91], v[48:49], off offset:-2048
	global_load_dwordx2 v[92:93], v[50:51], off offset:-2048
	global_load_dwordx2 v[94:95], v[48:49], off offset:-1536
	global_load_dwordx2 v[96:97], v[50:51], off offset:-1536
	global_load_dwordx2 v[98:99], v[48:49], off offset:-1024
	global_load_dwordx2 v[100:101], v[50:51], off offset:-1024
	global_load_dwordx2 v[102:103], v[48:49], off offset:-512
	global_load_dwordx2 v[104:105], v[50:51], off offset:-512
	global_load_dwordx2 v[106:107], v[48:49], off
	global_load_dwordx2 v[108:109], v[50:51], off
	global_load_dwordx2 v[110:111], v[48:49], off offset:512
	global_load_dwordx2 v[112:113], v[50:51], off offset:512
	global_load_dwordx2 v[114:115], v[48:49], off offset:1024
	global_load_dwordx2 v[116:117], v[50:51], off offset:1024
	global_load_dwordx2 v[118:119], v[48:49], off offset:1536
	global_load_dwordx2 v[120:121], v[50:51], off offset:1536
	global_load_dwordx4 v[62:65], v[46:47], off
	global_load_dwordx4 v[66:69], v[46:47], off offset:1024
	global_load_dwordx4 v[70:73], v[46:47], off offset:2048
	global_load_dwordx4 v[74:77], v[46:47], off offset:3072
	v_add_co_u32_e32 v50, vcc, 0x1000, v46
	v_lshl_add_u64 v[52:53], s[6:7], 0, v[32:33]
	s_nop 0
	v_addc_co_u32_e32 v51, vcc, 0, v47, vcc
	global_load_dwordx4 v[46:49], v[50:51], off
	global_load_dwordx4 v[78:81], v[50:51], off offset:1024
	global_load_dwordx4 v[82:85], v[50:51], off offset:2048
	global_load_dwordx4 v[86:89], v[50:51], off offset:3072
	v_add_co_u32_e64 v122, s[0:1], s3, v52
	s_add_i32 s16, s16, s2
	s_nop 0
	v_addc_co_u32_e64 v123, s[0:1], 0, v53, s[0:1]
	s_add_u32 s4, s4, s8
	s_addc_u32 s5, s5, s9
	s_add_u32 s6, s6, s8
	s_addc_u32 s7, s7, s9
	v_lshl_add_u64 v[44:45], v[44:45], 0, s[12:13]
	s_cmpk_lt_i32 s16, 0x4000
	s_waitcnt vmcnt(0)
	v_lshlrev_b32_e32 v50, 16, v90
	v_and_b32_e32 v51, 0xffff0000, v90
	v_lshlrev_b32_e32 v90, 16, v91
	v_and_b32_e32 v91, 0xffff0000, v91
	v_lshlrev_b32_e32 v126, 16, v94
	v_and_b32_e32 v127, 0xffff0000, v94
	v_lshlrev_b32_e32 v94, 16, v95
	v_and_b32_e32 v95, 0xffff0000, v95
	v_lshlrev_b32_e32 v124, 16, v92
	v_and_b32_e32 v125, 0xffff0000, v92
	v_lshlrev_b32_e32 v92, 16, v93
	v_and_b32_e32 v93, 0xffff0000, v93
	v_lshlrev_b32_e32 v128, 16, v96
	v_and_b32_e32 v129, 0xffff0000, v96
	v_lshlrev_b32_e32 v96, 16, v97
	v_and_b32_e32 v97, 0xffff0000, v97
	v_lshlrev_b32_e32 v130, 16, v98
	v_and_b32_e32 v131, 0xffff0000, v98
	v_lshlrev_b32_e32 v98, 16, v99
	v_and_b32_e32 v99, 0xffff0000, v99
	v_pk_add_f32 v[50:51], v[62:63], v[50:51]
	v_pk_add_f32 v[62:63], v[64:65], v[90:91]
	v_pk_add_f32 v[64:65], v[66:67], v[126:127]
	v_pk_add_f32 v[66:67], v[68:69], v[94:95]
	v_lshlrev_b32_e32 v132, 16, v100
	v_and_b32_e32 v133, 0xffff0000, v100
	v_lshlrev_b32_e32 v100, 16, v101
	v_and_b32_e32 v101, 0xffff0000, v101
	v_pk_add_f32 v[68:69], v[70:71], v[130:131]
	v_pk_add_f32 v[70:71], v[72:73], v[98:99]
	v_pk_add_f32 v[50:51], v[50:51], v[124:125]
	v_pk_add_f32 v[62:63], v[62:63], v[92:93]
	v_pk_add_f32 v[64:65], v[64:65], v[128:129]
	v_pk_add_f32 v[66:67], v[66:67], v[96:97]
	v_lshlrev_b32_e32 v134, 16, v102
	v_and_b32_e32 v135, 0xffff0000, v102
	v_lshlrev_b32_e32 v102, 16, v103
	v_and_b32_e32 v103, 0xffff0000, v103
	v_lshlrev_b32_e32 v142, 16, v110
	v_and_b32_e32 v143, 0xffff0000, v110
	v_lshlrev_b32_e32 v110, 16, v111
	v_and_b32_e32 v111, 0xffff0000, v111
	v_lshlrev_b32_e32 v146, 16, v114
	v_and_b32_e32 v147, 0xffff0000, v114
	v_lshlrev_b32_e32 v114, 16, v115
	v_and_b32_e32 v115, 0xffff0000, v115
	v_lshlrev_b32_e32 v150, 16, v118
	v_and_b32_e32 v151, 0xffff0000, v118
	v_lshlrev_b32_e32 v118, 16, v119
	v_and_b32_e32 v119, 0xffff0000, v119
	v_pk_add_f32 v[68:69], v[68:69], v[132:133]
	v_pk_add_f32 v[70:71], v[70:71], v[100:101]
	v_mov_b32_e32 v90, v51
	v_mov_b32_e32 v91, v65
	v_mov_b32_e32 v94, v63
	v_mov_b32_e32 v95, v67
	v_lshlrev_b32_e32 v136, 16, v104
	v_and_b32_e32 v137, 0xffff0000, v104
	v_lshlrev_b32_e32 v104, 16, v105
	v_and_b32_e32 v105, 0xffff0000, v105
	v_lshlrev_b32_e32 v138, 16, v106
	v_and_b32_e32 v139, 0xffff0000, v106
	v_lshlrev_b32_e32 v106, 16, v107
	v_and_b32_e32 v107, 0xffff0000, v107
	v_pk_add_f32 v[72:73], v[74:75], v[134:135]
	v_pk_add_f32 v[74:75], v[76:77], v[102:103]
	v_pk_add_f32 v[76:77], v[78:79], v[142:143]
	v_pk_add_f32 v[78:79], v[80:81], v[110:111]
	v_pk_add_f32 v[80:81], v[82:83], v[146:147]
	v_pk_add_f32 v[82:83], v[84:85], v[114:115]
	v_pk_add_f32 v[84:85], v[86:87], v[150:151]
	v_pk_add_f32 v[86:87], v[88:89], v[118:119]
	v_mov_b32_e32 v88, v50
	v_mov_b32_e32 v89, v64
	v_mov_b32_e32 v92, v62
	v_mov_b32_e32 v93, v66
	v_mov_b32_e32 v98, v69
	v_mov_b32_e32 v99, v71
	v_pk_mul_f32 v[90:91], v[90:91], v[90:91]
	v_pk_mul_f32 v[94:95], v[94:95], v[94:95]
	v_lshlrev_b32_e32 v140, 16, v108
	v_and_b32_e32 v141, 0xffff0000, v108
	v_lshlrev_b32_e32 v108, 16, v109
	v_and_b32_e32 v109, 0xffff0000, v109
	v_pk_add_f32 v[72:73], v[72:73], v[136:137]
	v_pk_add_f32 v[74:75], v[74:75], v[104:105]
	v_pk_add_f32 v[46:47], v[46:47], v[138:139]
	v_pk_add_f32 v[48:49], v[48:49], v[106:107]
	v_mov_b32_e32 v96, v68
	v_mov_b32_e32 v97, v70
	v_pk_mul_f32 v[98:99], v[98:99], v[98:99]
; __device__ __forceinline__ unsigned pk2(float lo, float hi) { return pg8::cvt_pk_bf16(lo, hi); }
; template <int MODE> __device__ __forceinline__ void rows_pass(const Ctx& C, const float* src, const float* g, bf16* dst_bf, float* dst_f, const LAS float* wg, const float* b_ig = nullptr, const float* b_fg = nullptr, const bf16* add_bf = nullptr, const bf16* add2_bf = nullptr) {
;     ...
;         for (int j = 0; j < 8; ++j) ss += (v[j].x * v[j].x + v[j].y * v[j].y) + (v[j].z * v[j].z + v[j].w * v[j].w);
;         const float rs = 1.0f / sqrtf(wave_sum(ss) * (1.0f / DM) + EPS);
; #pragma unroll
;         for (int j = 0; j < 8; ++j) { const f32x4 gg = ((const f32x4*)g)[64 * j + lane]; v[j] = v[j] * rs * gg; }
;         if (MODE == 2) {
;             f32x4* o = (f32x4*)(dst_f + (size_t)m * DM) + lane;
; #pragma unroll
;             for (int j = 0; j < 8; ++j) o[64 * j] = v[j];
;         } else {
;             u32x2* o = (u32x2*)(dst_bf + (size_t)m * DM) + lane;
; #pragma unroll
;             for (int j = 0; j < 8; ++j) { u32x2 w; w.x = pk2(v[j].x, v[j].y); w.y = pk2(v[j].z, v[j].w); o[64 * j] = w; }
	v_pk_fma_f32 v[88:89], v[88:89], v[88:89], v[90:91]
	v_pk_fma_f32 v[90:91], v[92:93], v[92:93], v[94:95]
	v_lshlrev_b32_e32 v144, 16, v112
	v_and_b32_e32 v145, 0xffff0000, v112
	v_lshlrev_b32_e32 v112, 16, v113
	v_and_b32_e32 v113, 0xffff0000, v113
	v_pk_add_f32 v[46:47], v[46:47], v[140:141]
	v_pk_add_f32 v[48:49], v[48:49], v[108:109]
	v_mul_f32_e32 v100, v73, v73
	v_mul_f32_e32 v102, v75, v75
	v_pk_fma_f32 v[92:93], v[96:97], v[96:97], v[98:99]
	v_pk_add_f32 v[88:89], v[88:89], v[90:91]
	v_pk_add_f32 v[76:77], v[76:77], v[144:145]
	v_pk_add_f32 v[78:79], v[78:79], v[112:113]
	v_pk_fma_f32 v[100:101], v[72:73], v[72:73], v[100:101] op_sel_hi:[1,1,0]
	v_pk_fma_f32 v[102:103], v[74:75], v[74:75], v[102:103] op_sel_hi:[1,1,0]
	v_pk_mul_f32 v[104:105], v[46:47], v[46:47]
	v_pk_mul_f32 v[106:107], v[48:49], v[48:49]
	v_pk_add_f32 v[90:91], v[92:93], v[92:93] op_sel:[0,1] op_sel_hi:[1,0]
	v_pk_add_f32 v[88:89], v[88:89], v[88:89] op_sel:[0,1] op_sel_hi:[1,0]
	v_lshlrev_b32_e32 v148, 16, v116
	v_and_b32_e32 v149, 0xffff0000, v116
	v_lshlrev_b32_e32 v116, 16, v117
	v_and_b32_e32 v117, 0xffff0000, v117
	v_mov_b32_e32 v110, v77
	v_mov_b32_e32 v111, v79
	v_mov_b32_e32 v101, v106
	v_mov_b32_e32 v103, v107
	v_mov_b32_e32 v91, v105
	v_mov_b32_e32 v89, v104
	v_lshlrev_b32_e32 v152, 16, v120
	v_and_b32_e32 v153, 0xffff0000, v120
	v_lshlrev_b32_e32 v120, 16, v121
	v_and_b32_e32 v121, 0xffff0000, v121
	v_pk_add_f32 v[80:81], v[80:81], v[148:149]
	v_pk_add_f32 v[82:83], v[82:83], v[116:117]
	v_mov_b32_e32 v108, v76
	v_mov_b32_e32 v109, v78
	v_pk_mul_f32 v[94:95], v[110:111], v[110:111]
	v_pk_add_f32 v[92:93], v[100:101], v[102:103]
	v_pk_add_f32 v[88:89], v[88:89], v[90:91]
	v_pk_add_f32 v[84:85], v[84:85], v[152:153]
	v_pk_add_f32 v[86:87], v[86:87], v[120:121]
	v_mul_f32_e32 v112, v81, v81
	v_mul_f32_e32 v114, v83, v83
	v_pk_fma_f32 v[94:95], v[108:109], v[108:109], v[94:95]
	v_pk_add_f32 v[88:89], v[88:89], v[92:93]
	v_pk_mul_f32 v[116:117], v[84:85], v[84:85]
	v_pk_mul_f32 v[118:119], v[86:87], v[86:87]
	v_pk_fma_f32 v[96:97], v[80:81], v[80:81], v[112:113] op_sel_hi:[1,1,0]
	v_pk_fma_f32 v[98:99], v[82:83], v[82:83], v[114:115] op_sel_hi:[1,1,0]
	v_pk_add_f32 v[94:95], v[94:95], v[94:95] op_sel:[0,1] op_sel_hi:[1,0]
	v_pk_add_f32 v[88:89], v[88:89], v[88:89] op_sel:[0,1] op_sel_hi:[1,0]
	v_mov_b32_e32 v97, v118
	v_mov_b32_e32 v99, v119
	v_mov_b32_e32 v95, v117
	v_mov_b32_e32 v89, v116
	v_pk_add_f32 v[96:97], v[96:97], v[98:99]
	v_pk_add_f32 v[88:89], v[88:89], v[94:95]
	s_nop 0
	v_pk_add_f32 v[88:89], v[88:89], v[96:97]
	s_nop 0
	v_add_f32_e32 v88, v88, v89
	s_waitcnt lgkmcnt(0)
	s_nop 1
	v_add_f32_dpp v88, v88, v88 quad_perm:[1,0,3,2] row_mask:0xf bank_mask:0xf
	s_waitcnt lgkmcnt(0)
	s_nop 1
	v_add_f32_dpp v88, v88, v88 quad_perm:[2,3,0,1] row_mask:0xf bank_mask:0xf
	s_waitcnt lgkmcnt(0)
	s_nop 1
	v_add_f32_dpp v88, v88, v88 row_half_mirror row_mask:0xf bank_mask:0xf
	s_waitcnt lgkmcnt(0)
	s_nop 1
	v_add_f32_dpp v88, v88, v88 row_mirror row_mask:0xf bank_mask:0xf
	s_waitcnt lgkmcnt(0)
	v_mov_b32_e32 v89, v88
	s_nop 1
	v_permlane16_swap_b32_e32 v88, v89
	v_add_f32_e32 v88, v88, v89
	s_waitcnt lgkmcnt(0)
	v_mov_b32_e32 v89, v88
	s_nop 1
	v_permlane32_swap_b32_e32 v88, v89
	v_add_f32_e32 v88, v88, v89
	v_fmamk_f32 v88, v88, 0x3a000000, v60
	v_mul_f32_e32 v89, 0x4f800000, v88
	v_cmp_gt_f32_e32 vcc, s17, v88
	s_nop 1
	v_cndmask_b32_e32 v88, v88, v89, vcc
	v_sqrt_f32_e32 v89, v88
	s_nop 0
	v_add_u32_e32 v90, -1, v89
	v_add_u32_e32 v91, 1, v89
	v_fma_f32 v92, -v90, v89, v88
	v_fma_f32 v93, -v91, v89, v88
	v_cmp_ge_f32_e64 s[0:1], 0, v92
	s_nop 1
	v_cndmask_b32_e64 v89, v89, v90, s[0:1]
	v_cmp_lt_f32_e64 s[0:1], 0, v93
	s_nop 1
	v_cndmask_b32_e64 v89, v89, v91, s[0:1]
	v_mul_f32_e32 v90, 0x37800000, v89
	v_cndmask_b32_e32 v89, v89, v90, vcc
	v_cmp_class_f32_e32 vcc, v88, v61
	s_nop 1
	v_cndmask_b32_e32 v88, v89, v88, vcc
	v_div_scale_f32 v89, s[0:1], v88, v88, 1.0
	v_rcp_f32_e32 v91, v89
	v_div_scale_f32 v90, vcc, 1.0, v88, 1.0
	v_fma_f32 v92, -v89, v91, 1.0
	v_fmac_f32_e32 v91, v92, v91
	v_mul_f32_e32 v92, v90, v91
	v_fma_f32 v93, -v89, v92, v90
	v_fmac_f32_e32 v92, v93, v91
	v_fma_f32 v89, -v89, v92, v90
	v_div_fmas_f32 v89, v89, v91, v92
	v_div_fixup_f32 v88, v89, v88, 1.0
	v_pk_mul_f32 v[50:51], v[50:51], v[88:89] op_sel_hi:[1,0]
	v_pk_mul_f32 v[62:63], v[62:63], v[88:89] op_sel_hi:[1,0]
	v_pk_mul_f32 v[64:65], v[64:65], v[88:89] op_sel_hi:[1,0]
	v_pk_mul_f32 v[66:67], v[66:67], v[88:89] op_sel_hi:[1,0]
	v_pk_mul_f32 v[68:69], v[68:69], v[88:89] op_sel_hi:[1,0]
	v_pk_mul_f32 v[70:71], v[70:71], v[88:89] op_sel_hi:[1,0]
	v_pk_mul_f32 v[72:73], v[72:73], v[88:89] op_sel_hi:[1,0]
	v_pk_mul_f32 v[74:75], v[74:75], v[88:89] op_sel_hi:[1,0]
	v_pk_mul_f32 v[46:47], v[46:47], v[88:89] op_sel_hi:[1,0]
	v_pk_mul_f32 v[48:49], v[48:49], v[88:89] op_sel_hi:[1,0]
	v_pk_mul_f32 v[76:77], v[76:77], v[88:89] op_sel_hi:[1,0]
	v_pk_mul_f32 v[78:79], v[78:79], v[88:89] op_sel_hi:[1,0]
	v_pk_mul_f32 v[80:81], v[80:81], v[88:89] op_sel_hi:[1,0]
	v_pk_mul_f32 v[82:83], v[82:83], v[88:89] op_sel_hi:[1,0]
	v_pk_mul_f32 v[84:85], v[84:85], v[88:89] op_sel_hi:[1,0]
	v_pk_mul_f32 v[86:87], v[86:87], v[88:89] op_sel_hi:[1,0]
	v_pk_mul_f32 v[2:3], v[2:3], v[62:63]
	v_pk_mul_f32 v[0:1], v[0:1], v[50:51]
	v_pk_mul_f32 v[6:7], v[6:7], v[66:67]
	v_pk_mul_f32 v[4:5], v[4:5], v[64:65]
	v_pk_mul_f32 v[10:11], v[10:11], v[70:71]
	v_pk_mul_f32 v[8:9], v[8:9], v[68:69]
	v_pk_mul_f32 v[14:15], v[14:15], v[74:75]
	v_pk_mul_f32 v[12:13], v[12:13], v[72:73]
	v_pk_mul_f32 v[18:19], v[18:19], v[48:49]
	v_pk_mul_f32 v[16:17], v[16:17], v[46:47]
	v_pk_mul_f32 v[22:23], v[22:23], v[78:79]
	v_pk_mul_f32 v[20:21], v[20:21], v[76:77]
	v_pk_mul_f32 v[26:27], v[26:27], v[82:83]
	v_pk_mul_f32 v[24:25], v[24:25], v[80:81]
	v_pk_mul_f32 v[30:31], v[30:31], v[86:87]
	v_pk_mul_f32 v[28:29], v[28:29], v[84:85]
	global_store_dwordx4 v[52:53], v[0:3], off
	global_store_dwordx4 v[52:53], v[4:7], off offset:1024
	global_store_dwordx4 v[52:53], v[8:11], off offset:2048
	global_store_dwordx4 v[52:53], v[12:15], off offset:3072
	global_store_dwordx4 v[122:123], v[16:19], off
	global_store_dwordx4 v[122:123], v[20:23], off offset:1024
	global_store_dwordx4 v[122:123], v[24:27], off offset:2048
	global_store_dwordx4 v[122:123], v[28:31], off offset:3072
	s_cbranch_scc1 .LBB0_1081
